# O/F2 residual epilogue: 4 rows per trip loaded together with one wait, interleaved row-sum shuffles, global instead of flat stores
# speedup vs baseline: 1.0411x; 1.0026x over previous
; DI f32x16 mfma(bf16x8 a, bf16x8 b, f32x16 c) { return __builtin_amdgcn_mfma_f32_32x32x16_bf16(a, b, c, 0, 0, 0); }
;     ...
;   __syncthreads();
;   DMA_ISSUE(0, 0)
;   asm volatile("s_waitcnt vmcnt(0)" ::: "memory");
;   __builtin_amdgcn_s_barrier();
;   for (int kt = 0; kt < nk; ++kt) {
;     const char* cur = lds + (kt & 1) * DBUF;
;     if (kt + 1 < nk) DMA_ISSUE((kt + 1) & 1, kt + 1)
; #pragma unroll(NTB == 1 ? 2 : 4)
;     for (int s = 0; s < 4; ++s) {
;       const int ro = ((2 * s + hh) ^ xr) * 16;
;       bf16x8 bfr[NTB];
; #pragma unroll
;       for (int tb = 0; tb < NTB; ++tb) bfr[tb] = *(const bf16x8*)(cur + bbase + tb * 32 * DROW + ro);
; #pragma unroll
;       for (int fb = 0; fb < NFB; ++fb) {
;         const bf16x8 afr = *(const bf16x8*)(cur + abase + fb * 32 * DROW + ro);
; #pragma unroll
;         for (int tb = 0; tb < NTB; ++tb) acc[tb * NFB + fb] = mfma(afr, bfr[tb], acc[tb * NFB + fb]);
;       }
;     }
;     asm volatile("s_waitcnt vmcnt(0) lgkmcnt(0)" ::: "memory");
;     __builtin_amdgcn_s_barrier();
;   }
; __global__ void __launch_bounds__(512) mega(Params p) {
;     ...
;         for (int n = 0; n < 3; ++n) {
;           f32x16 acc[4]; zero4(acc);
;           const size_t ooff = (n == 0) ? R_OA : (n == 1 ? R_OB : R_OC);
;           gemm_main<4, 1>((const u16*)(ws + OFF_WBR) + ((size_t)n * 1024 + ft * 256) * 512, 512, (const u16*)(ws + ooff) + (size_t)tt * 128 * 512, 512, 8, acc, lds);
.LBB0_25:
	s_cmp_eq_u32 s8, 1
	s_mov_b32 s0, 0x19db1000
	s_cselect_b32 s33, s0, 0x1bdb1000
	s_cmp_eq_u32 s8, 0
	s_cselect_b64 s[0:1], -1, 0
	s_and_b64 s[34:35], s[0:1], exec
	s_cselect_b32 s33, 0x6db1000, s33
	s_lshl_b32 s34, s8, 10
	s_add_u32 s34, s34, s54
	s_addc_u32 s35, 0, s55
	s_lshl_b64 s[66:67], s[34:35], 10
	v_mov_b32_e32 v8, v145
	s_add_u32 s66, s36, s66
	s_addc_u32 s67, s37, s67
	v_ashrrev_i32_e32 v2, 3, v8
	v_lshrrev_b32_e32 v0, 4, v8
	v_xor_b32_e32 v0, v0, v8
	v_ashrrev_i32_e32 v3, 31, v2
	s_add_u32 s68, s9, s33
	v_lshlrev_b64 v[4:5], 10, v[2:3]
	v_lshlrev_b32_e32 v0, 4, v0
	v_lshl_add_u32 v15, v8, 4, 0
	s_addc_u32 s69, s59, 0
	v_lshl_add_u64 v[2:3], s[66:67], 0, v[4:5]
	v_and_b32_e32 v0, 0x70, v0
	v_readfirstlane_b32 s33, v15
	v_add_u32_e32 v16, 0x2000, v15
	v_lshl_add_u64 v[2:3], v[2:3], 0, v[0:1]
	v_lshl_add_u64 v[4:5], s[68:69], 0, v[4:5]
	s_waitcnt vmcnt(0) lgkmcnt(0)
	s_barrier
	v_lshl_add_u64 v[4:5], v[4:5], 0, v[0:1]
	s_mov_b64 s[68:69], 0x10000
	v_lshl_add_u64 v[6:7], v[2:3], 0, s[68:69]
	v_lshl_add_u64 v[12:13], v[4:5], 0, s[68:69]
	v_lshl_add_u64 v[8:9], v[6:7], 0, s[68:69]
	v_lshl_add_u64 v[10:11], v[8:9], 0, s[68:69]
	s_add_u32 m0, s33, 0x0
	s_nop 0
	global_load_lds_dwordx4 v[2:3], off
	s_add_u32 m0, s33, 0x2000
	s_nop 0
	global_load_lds_dwordx4 v[6:7], off
	s_add_u32 m0, s33, 0x4000
	s_nop 0
	global_load_lds_dwordx4 v[8:9], off
	s_add_u32 m0, s33, 0x6000
	s_nop 0
	global_load_lds_dwordx4 v[10:11], off
	s_add_u32 m0, s33, 0x8000
	s_nop 0
	global_load_lds_dwordx4 v[4:5], off
	s_add_u32 m0, s33, 0xa000
	s_nop 0
	global_load_lds_dwordx4 v[12:13], off
	s_add_u32 m0, s33, 0xc000
	v_lshl_add_u64 v[2:3], v[2:3], 0, s[84:85]
	global_load_lds_dwordx4 v[2:3], off
	s_add_u32 m0, s33, 0xe000
	v_lshl_add_u64 v[6:7], v[6:7], 0, s[84:85]
	global_load_lds_dwordx4 v[6:7], off
	s_add_u32 m0, s33, 0x10000
	v_lshl_add_u64 v[8:9], v[8:9], 0, s[84:85]
	global_load_lds_dwordx4 v[8:9], off
	s_add_u32 m0, s33, 0x12000
	v_lshl_add_u64 v[10:11], v[10:11], 0, s[84:85]
	global_load_lds_dwordx4 v[10:11], off
	s_add_u32 m0, s33, 0x14000
	v_lshl_add_u64 v[4:5], v[4:5], 0, s[84:85]
	global_load_lds_dwordx4 v[4:5], off
	s_add_u32 m0, s33, 0x16000
	v_lshl_add_u64 v[12:13], v[12:13], 0, s[84:85]
	global_load_lds_dwordx4 v[12:13], off
	v_and_b32_e32 v238, 31, v145
	v_lshrrev_b32_e32 v239, 8, v145
	v_bfe_u32 v240, v145, 6, 2
	v_lshl_add_u32 v239, v239, 7, v238
	v_lshl_add_u32 v240, v240, 5, v238
	v_lshlrev_b32_e32 v239, 7, v239
	v_lshlrev_b32_e32 v240, 7, v240
	v_bfe_u32 v241, v145, 5, 1
	v_bfe_u32 v242, v145, 1, 3
	v_or_b32_e32 v243, 0, v241
	v_xor_b32_e32 v243, v243, v242
	v_lshlrev_b32_e32 v243, 4, v243
	v_add_u32_e32 v14, v239, v243
	v_add_u32_e32 v186, v240, v243
	v_or_b32_e32 v243, 2, v241
	v_xor_b32_e32 v243, v243, v242
	v_lshlrev_b32_e32 v243, 4, v243
	v_add_u32_e32 v15, v239, v243
	v_add_u32_e32 v189, v240, v243
	v_or_b32_e32 v243, 4, v241
	v_xor_b32_e32 v243, v243, v242
	v_lshlrev_b32_e32 v243, 4, v243
	v_add_u32_e32 v0, v239, v243
	v_add_u32_e32 v233, v240, v243
	v_or_b32_e32 v243, 6, v241
	v_xor_b32_e32 v243, v243, v242
	v_lshlrev_b32_e32 v243, 4, v243
	v_add_u32_e32 v184, v239, v243
	v_add_u32_e32 v234, v240, v243
	s_waitcnt vmcnt(6)
	s_barrier
	ds_read_b128 v[180:183], v186 offset:32768
	ds_read_b128 v[238:241], v14
	ds_read_b128 v[242:245], v14 offset:4096
	ds_read_b128 v[246:249], v14 offset:8192
	ds_read_b128 v[250:253], v14 offset:12288
	ds_read_b128 v[190:193], v189 offset:32768
	s_waitcnt lgkmcnt(4)
	v_mfma_f32_32x32x16_bf16 v[112:127], v[238:241], v[180:183], 0
	ds_read_b128 v[238:241], v15
	s_add_u32 m0, s33, 0x18000
	v_lshl_add_u64 v[2:3], v[2:3], 0, s[84:85]
	global_load_lds_dwordx4 v[2:3], off
	s_waitcnt lgkmcnt(4)
	v_mfma_f32_32x32x16_bf16 v[96:111], v[242:245], v[180:183], 0
	ds_read_b128 v[242:245], v15 offset:4096
	s_add_u32 m0, s33, 0x1a000
	v_lshl_add_u64 v[6:7], v[6:7], 0, s[84:85]
	global_load_lds_dwordx4 v[6:7], off
	s_waitcnt lgkmcnt(4)
	v_mfma_f32_32x32x16_bf16 v[80:95], v[246:249], v[180:183], 0
	ds_read_b128 v[246:249], v15 offset:8192
	s_waitcnt lgkmcnt(4)
	v_mfma_f32_32x32x16_bf16 v[64:79], v[250:253], v[180:183], 0
	ds_read_b128 v[250:253], v15 offset:12288
	s_add_u32 m0, s33, 0x1c000
	v_lshl_add_u64 v[8:9], v[8:9], 0, s[84:85]
	global_load_lds_dwordx4 v[8:9], off
	ds_read_b128 v[180:183], v233 offset:32768
	s_waitcnt lgkmcnt(4)
	v_mfma_f32_32x32x16_bf16 v[112:127], v[238:241], v[190:193], v[112:127]
	ds_read_b128 v[238:241], v0
	s_waitcnt lgkmcnt(4)
	v_mfma_f32_32x32x16_bf16 v[96:111], v[242:245], v[190:193], v[96:111]
	ds_read_b128 v[242:245], v0 offset:4096
	s_add_u32 m0, s33, 0x1e000
	v_lshl_add_u64 v[10:11], v[10:11], 0, s[84:85]
	global_load_lds_dwordx4 v[10:11], off
	s_waitcnt lgkmcnt(4)
	v_mfma_f32_32x32x16_bf16 v[80:95], v[246:249], v[190:193], v[80:95]
	ds_read_b128 v[246:249], v0 offset:8192
	s_waitcnt lgkmcnt(4)
	v_mfma_f32_32x32x16_bf16 v[64:79], v[250:253], v[190:193], v[64:79]
	ds_read_b128 v[250:253], v0 offset:12288
	s_add_u32 m0, s33, 0x20000
	v_lshl_add_u64 v[4:5], v[4:5], 0, s[84:85]
	global_load_lds_dwordx4 v[4:5], off
	ds_read_b128 v[190:193], v234 offset:32768
	s_waitcnt lgkmcnt(4)
	v_mfma_f32_32x32x16_bf16 v[112:127], v[238:241], v[180:183], v[112:127]
	ds_read_b128 v[238:241], v184
	s_waitcnt lgkmcnt(4)
	v_mfma_f32_32x32x16_bf16 v[96:111], v[242:245], v[180:183], v[96:111]
	ds_read_b128 v[242:245], v184 offset:4096
	s_add_u32 m0, s33, 0x22000
	v_lshl_add_u64 v[12:13], v[12:13], 0, s[84:85]
	global_load_lds_dwordx4 v[12:13], off
	s_waitcnt lgkmcnt(4)
	v_mfma_f32_32x32x16_bf16 v[80:95], v[246:249], v[180:183], v[80:95]
	ds_read_b128 v[246:249], v184 offset:8192
	s_waitcnt lgkmcnt(4)
	v_mfma_f32_32x32x16_bf16 v[64:79], v[250:253], v[180:183], v[64:79]
	ds_read_b128 v[250:253], v184 offset:12288
	s_waitcnt lgkmcnt(3)
	v_mfma_f32_32x32x16_bf16 v[112:127], v[238:241], v[190:193], v[112:127]
	s_waitcnt lgkmcnt(2)
	v_mfma_f32_32x32x16_bf16 v[96:111], v[242:245], v[190:193], v[96:111]
	s_waitcnt lgkmcnt(1)
	v_mfma_f32_32x32x16_bf16 v[80:95], v[246:249], v[190:193], v[80:95]
	s_waitcnt lgkmcnt(0)
	v_mfma_f32_32x32x16_bf16 v[64:79], v[250:253], v[190:193], v[64:79]
	s_waitcnt vmcnt(6)
	s_barrier
; DI f32x16 mfma(bf16x8 a, bf16x8 b, f32x16 c) { return __builtin_amdgcn_mfma_f32_32x32x16_bf16(a, b, c, 0, 0, 0); }
;     ...
;   for (int kt = 0; kt < nk; ++kt) {
;     const char* cur = lds + (kt & 1) * DBUF;
;     if (kt + 1 < nk) DMA_ISSUE((kt + 1) & 1, kt + 1)
; #pragma unroll(NTB == 1 ? 2 : 4)
;     for (int s = 0; s < 4; ++s) {
;       const int ro = ((2 * s + hh) ^ xr) * 16;
;       bf16x8 bfr[NTB];
; #pragma unroll
;       for (int tb = 0; tb < NTB; ++tb) bfr[tb] = *(const bf16x8*)(cur + bbase + tb * 32 * DROW + ro);
; #pragma unroll
;       for (int fb = 0; fb < NFB; ++fb) {
;         const bf16x8 afr = *(const bf16x8*)(cur + abase + fb * 32 * DROW + ro);
; #pragma unroll
;         for (int tb = 0; tb < NTB; ++tb) acc[tb * NFB + fb] = mfma(afr, bfr[tb], acc[tb * NFB + fb]);
;       }
;     }
;     asm volatile("s_waitcnt vmcnt(0) lgkmcnt(0)" ::: "memory");
;     __builtin_amdgcn_s_barrier();
;   }
	v_add_u32_e32 v195, 0xc000, v186
	ds_read_b128 v[180:183], v195 offset:32768
	v_add_u32_e32 v194, 0xc000, v14
	ds_read_b128 v[238:241], v194
	ds_read_b128 v[242:245], v194 offset:4096
	ds_read_b128 v[246:249], v194 offset:8192
	ds_read_b128 v[250:253], v194 offset:12288
	v_add_u32_e32 v195, 0xc000, v189
	ds_read_b128 v[190:193], v195 offset:32768
	v_add_u32_e32 v194, 0xc000, v15
	s_waitcnt lgkmcnt(4)
	v_mfma_f32_32x32x16_bf16 v[112:127], v[238:241], v[180:183], v[112:127]
	ds_read_b128 v[238:241], v194
	s_add_u32 m0, s33, 0x0
	v_lshl_add_u64 v[2:3], v[2:3], 0, s[84:85]
	global_load_lds_dwordx4 v[2:3], off
	s_waitcnt lgkmcnt(4)
	v_mfma_f32_32x32x16_bf16 v[96:111], v[242:245], v[180:183], v[96:111]
	ds_read_b128 v[242:245], v194 offset:4096
	s_add_u32 m0, s33, 0x2000
	v_lshl_add_u64 v[6:7], v[6:7], 0, s[84:85]
	global_load_lds_dwordx4 v[6:7], off
	s_waitcnt lgkmcnt(4)
	v_mfma_f32_32x32x16_bf16 v[80:95], v[246:249], v[180:183], v[80:95]
	ds_read_b128 v[246:249], v194 offset:8192
	s_waitcnt lgkmcnt(4)
	v_mfma_f32_32x32x16_bf16 v[64:79], v[250:253], v[180:183], v[64:79]
	ds_read_b128 v[250:253], v194 offset:12288
	s_add_u32 m0, s33, 0x4000
	v_lshl_add_u64 v[8:9], v[8:9], 0, s[84:85]
	global_load_lds_dwordx4 v[8:9], off
	v_add_u32_e32 v195, 0xc000, v233
	ds_read_b128 v[180:183], v195 offset:32768
	v_add_u32_e32 v194, 0xc000, v0
	s_waitcnt lgkmcnt(4)
	v_mfma_f32_32x32x16_bf16 v[112:127], v[238:241], v[190:193], v[112:127]
	ds_read_b128 v[238:241], v194
	s_waitcnt lgkmcnt(4)
	v_mfma_f32_32x32x16_bf16 v[96:111], v[242:245], v[190:193], v[96:111]
	ds_read_b128 v[242:245], v194 offset:4096
	s_add_u32 m0, s33, 0x6000
	v_lshl_add_u64 v[10:11], v[10:11], 0, s[84:85]
	global_load_lds_dwordx4 v[10:11], off
	s_waitcnt lgkmcnt(4)
	v_mfma_f32_32x32x16_bf16 v[80:95], v[246:249], v[190:193], v[80:95]
	ds_read_b128 v[246:249], v194 offset:8192
	s_waitcnt lgkmcnt(4)
	v_mfma_f32_32x32x16_bf16 v[64:79], v[250:253], v[190:193], v[64:79]
	ds_read_b128 v[250:253], v194 offset:12288
	s_add_u32 m0, s33, 0x8000
	v_lshl_add_u64 v[4:5], v[4:5], 0, s[84:85]
	global_load_lds_dwordx4 v[4:5], off
	v_add_u32_e32 v195, 0xc000, v234
	ds_read_b128 v[190:193], v195 offset:32768
	v_add_u32_e32 v194, 0xc000, v184
	s_waitcnt lgkmcnt(4)
	v_mfma_f32_32x32x16_bf16 v[112:127], v[238:241], v[180:183], v[112:127]
	ds_read_b128 v[238:241], v194
	s_waitcnt lgkmcnt(4)
	v_mfma_f32_32x32x16_bf16 v[96:111], v[242:245], v[180:183], v[96:111]
	ds_read_b128 v[242:245], v194 offset:4096
	s_add_u32 m0, s33, 0xa000
	v_lshl_add_u64 v[12:13], v[12:13], 0, s[84:85]
	global_load_lds_dwordx4 v[12:13], off
	s_waitcnt lgkmcnt(4)
	v_mfma_f32_32x32x16_bf16 v[80:95], v[246:249], v[180:183], v[80:95]
	ds_read_b128 v[246:249], v194 offset:8192
	s_waitcnt lgkmcnt(4)
	v_mfma_f32_32x32x16_bf16 v[64:79], v[250:253], v[180:183], v[64:79]
	ds_read_b128 v[250:253], v194 offset:12288
	s_waitcnt lgkmcnt(3)
	v_mfma_f32_32x32x16_bf16 v[112:127], v[238:241], v[190:193], v[112:127]
	s_waitcnt lgkmcnt(2)
	v_mfma_f32_32x32x16_bf16 v[96:111], v[242:245], v[190:193], v[96:111]
	s_waitcnt lgkmcnt(1)
	v_mfma_f32_32x32x16_bf16 v[80:95], v[246:249], v[190:193], v[80:95]
	s_waitcnt lgkmcnt(0)
	v_mfma_f32_32x32x16_bf16 v[64:79], v[250:253], v[190:193], v[64:79]
	s_waitcnt vmcnt(6)
	s_barrier
	v_add_u32_e32 v195, 0x18000, v186
	ds_read_b128 v[180:183], v195 offset:32768
	v_add_u32_e32 v194, 0x18000, v14
	ds_read_b128 v[238:241], v194
	ds_read_b128 v[242:245], v194 offset:4096
	ds_read_b128 v[246:249], v194 offset:8192
	ds_read_b128 v[250:253], v194 offset:12288
	v_add_u32_e32 v195, 0x18000, v189
	ds_read_b128 v[190:193], v195 offset:32768
	v_add_u32_e32 v194, 0x18000, v15
	s_waitcnt lgkmcnt(4)
	v_mfma_f32_32x32x16_bf16 v[112:127], v[238:241], v[180:183], v[112:127]
	ds_read_b128 v[238:241], v194
	s_add_u32 m0, s33, 0xc000
	v_lshl_add_u64 v[2:3], v[2:3], 0, s[84:85]
	global_load_lds_dwordx4 v[2:3], off
	s_waitcnt lgkmcnt(4)
	v_mfma_f32_32x32x16_bf16 v[96:111], v[242:245], v[180:183], v[96:111]
	ds_read_b128 v[242:245], v194 offset:4096
	s_add_u32 m0, s33, 0xe000
	v_lshl_add_u64 v[6:7], v[6:7], 0, s[84:85]
	global_load_lds_dwordx4 v[6:7], off
	s_waitcnt lgkmcnt(4)
	v_mfma_f32_32x32x16_bf16 v[80:95], v[246:249], v[180:183], v[80:95]
	ds_read_b128 v[246:249], v194 offset:8192
	s_waitcnt lgkmcnt(4)
	v_mfma_f32_32x32x16_bf16 v[64:79], v[250:253], v[180:183], v[64:79]
	ds_read_b128 v[250:253], v194 offset:12288
	s_add_u32 m0, s33, 0x10000
	v_lshl_add_u64 v[8:9], v[8:9], 0, s[84:85]
	global_load_lds_dwordx4 v[8:9], off
	v_add_u32_e32 v195, 0x18000, v233
	ds_read_b128 v[180:183], v195 offset:32768
	v_add_u32_e32 v194, 0x18000, v0
	s_waitcnt lgkmcnt(4)
	v_mfma_f32_32x32x16_bf16 v[112:127], v[238:241], v[190:193], v[112:127]
	ds_read_b128 v[238:241], v194
	s_waitcnt lgkmcnt(4)
	v_mfma_f32_32x32x16_bf16 v[96:111], v[242:245], v[190:193], v[96:111]
	ds_read_b128 v[242:245], v194 offset:4096
	s_add_u32 m0, s33, 0x12000
	v_lshl_add_u64 v[10:11], v[10:11], 0, s[84:85]
	global_load_lds_dwordx4 v[10:11], off
	s_waitcnt lgkmcnt(4)
	v_mfma_f32_32x32x16_bf16 v[80:95], v[246:249], v[190:193], v[80:95]
	ds_read_b128 v[246:249], v194 offset:8192
	s_waitcnt lgkmcnt(4)
	v_mfma_f32_32x32x16_bf16 v[64:79], v[250:253], v[190:193], v[64:79]
	ds_read_b128 v[250:253], v194 offset:12288
	s_add_u32 m0, s33, 0x14000
	v_lshl_add_u64 v[4:5], v[4:5], 0, s[84:85]
	global_load_lds_dwordx4 v[4:5], off
	v_add_u32_e32 v195, 0x18000, v234
	ds_read_b128 v[190:193], v195 offset:32768
	v_add_u32_e32 v194, 0x18000, v184
	s_waitcnt lgkmcnt(4)
	v_mfma_f32_32x32x16_bf16 v[112:127], v[238:241], v[180:183], v[112:127]
	ds_read_b128 v[238:241], v194
	s_waitcnt lgkmcnt(4)
	v_mfma_f32_32x32x16_bf16 v[96:111], v[242:245], v[180:183], v[96:111]
	ds_read_b128 v[242:245], v194 offset:4096
	s_add_u32 m0, s33, 0x16000
	v_lshl_add_u64 v[12:13], v[12:13], 0, s[84:85]
	global_load_lds_dwordx4 v[12:13], off
	s_waitcnt lgkmcnt(4)
	v_mfma_f32_32x32x16_bf16 v[80:95], v[246:249], v[180:183], v[80:95]
	ds_read_b128 v[246:249], v194 offset:8192
	s_waitcnt lgkmcnt(4)
	v_mfma_f32_32x32x16_bf16 v[64:79], v[250:253], v[180:183], v[64:79]
	ds_read_b128 v[250:253], v194 offset:12288
	s_waitcnt lgkmcnt(3)
	v_mfma_f32_32x32x16_bf16 v[112:127], v[238:241], v[190:193], v[112:127]
	s_waitcnt lgkmcnt(2)
	v_mfma_f32_32x32x16_bf16 v[96:111], v[242:245], v[190:193], v[96:111]
	s_waitcnt lgkmcnt(1)
	v_mfma_f32_32x32x16_bf16 v[80:95], v[246:249], v[190:193], v[80:95]
	s_waitcnt lgkmcnt(0)
	v_mfma_f32_32x32x16_bf16 v[64:79], v[250:253], v[190:193], v[64:79]
	s_waitcnt vmcnt(6)
	s_barrier
; DI f32x16 mfma(bf16x8 a, bf16x8 b, f32x16 c) { return __builtin_amdgcn_mfma_f32_32x32x16_bf16(a, b, c, 0, 0, 0); }
;     ...
;   for (int kt = 0; kt < nk; ++kt) {
;     const char* cur = lds + (kt & 1) * DBUF;
;     if (kt + 1 < nk) DMA_ISSUE((kt + 1) & 1, kt + 1)
; #pragma unroll(NTB == 1 ? 2 : 4)
;     for (int s = 0; s < 4; ++s) {
;       const int ro = ((2 * s + hh) ^ xr) * 16;
;       bf16x8 bfr[NTB];
; #pragma unroll
;       for (int tb = 0; tb < NTB; ++tb) bfr[tb] = *(const bf16x8*)(cur + bbase + tb * 32 * DROW + ro);
; #pragma unroll
;       for (int fb = 0; fb < NFB; ++fb) {
;         const bf16x8 afr = *(const bf16x8*)(cur + abase + fb * 32 * DROW + ro);
; #pragma unroll
;         for (int tb = 0; tb < NTB; ++tb) acc[tb * NFB + fb] = mfma(afr, bfr[tb], acc[tb * NFB + fb]);
;       }
;     }
;     asm volatile("s_waitcnt vmcnt(0) lgkmcnt(0)" ::: "memory");
;     __builtin_amdgcn_s_barrier();
;   }
	ds_read_b128 v[180:183], v186 offset:32768
	ds_read_b128 v[238:241], v14
	ds_read_b128 v[242:245], v14 offset:4096
	ds_read_b128 v[246:249], v14 offset:8192
	ds_read_b128 v[250:253], v14 offset:12288
	ds_read_b128 v[190:193], v189 offset:32768
	s_waitcnt lgkmcnt(4)
	v_mfma_f32_32x32x16_bf16 v[112:127], v[238:241], v[180:183], v[112:127]
	ds_read_b128 v[238:241], v15
	s_add_u32 m0, s33, 0x18000
	v_lshl_add_u64 v[2:3], v[2:3], 0, s[84:85]
	global_load_lds_dwordx4 v[2:3], off
	s_waitcnt lgkmcnt(4)
	v_mfma_f32_32x32x16_bf16 v[96:111], v[242:245], v[180:183], v[96:111]
	ds_read_b128 v[242:245], v15 offset:4096
	s_add_u32 m0, s33, 0x1a000
	v_lshl_add_u64 v[6:7], v[6:7], 0, s[84:85]
	global_load_lds_dwordx4 v[6:7], off
	s_waitcnt lgkmcnt(4)
	v_mfma_f32_32x32x16_bf16 v[80:95], v[246:249], v[180:183], v[80:95]
	ds_read_b128 v[246:249], v15 offset:8192
	s_waitcnt lgkmcnt(4)
	v_mfma_f32_32x32x16_bf16 v[64:79], v[250:253], v[180:183], v[64:79]
	ds_read_b128 v[250:253], v15 offset:12288
	s_add_u32 m0, s33, 0x1c000
	v_lshl_add_u64 v[8:9], v[8:9], 0, s[84:85]
	global_load_lds_dwordx4 v[8:9], off
	ds_read_b128 v[180:183], v233 offset:32768
	s_waitcnt lgkmcnt(4)
	v_mfma_f32_32x32x16_bf16 v[112:127], v[238:241], v[190:193], v[112:127]
	ds_read_b128 v[238:241], v0
	s_waitcnt lgkmcnt(4)
	v_mfma_f32_32x32x16_bf16 v[96:111], v[242:245], v[190:193], v[96:111]
	ds_read_b128 v[242:245], v0 offset:4096
	s_add_u32 m0, s33, 0x1e000
	v_lshl_add_u64 v[10:11], v[10:11], 0, s[84:85]
	global_load_lds_dwordx4 v[10:11], off
	s_waitcnt lgkmcnt(4)
	v_mfma_f32_32x32x16_bf16 v[80:95], v[246:249], v[190:193], v[80:95]
	ds_read_b128 v[246:249], v0 offset:8192
	s_waitcnt lgkmcnt(4)
	v_mfma_f32_32x32x16_bf16 v[64:79], v[250:253], v[190:193], v[64:79]
	ds_read_b128 v[250:253], v0 offset:12288
	s_add_u32 m0, s33, 0x20000
	v_lshl_add_u64 v[4:5], v[4:5], 0, s[84:85]
	global_load_lds_dwordx4 v[4:5], off
	ds_read_b128 v[190:193], v234 offset:32768
	s_waitcnt lgkmcnt(4)
	v_mfma_f32_32x32x16_bf16 v[112:127], v[238:241], v[180:183], v[112:127]
	ds_read_b128 v[238:241], v184
	s_waitcnt lgkmcnt(4)
	v_mfma_f32_32x32x16_bf16 v[96:111], v[242:245], v[180:183], v[96:111]
	ds_read_b128 v[242:245], v184 offset:4096
	s_add_u32 m0, s33, 0x22000
	v_lshl_add_u64 v[12:13], v[12:13], 0, s[84:85]
	global_load_lds_dwordx4 v[12:13], off
	s_waitcnt lgkmcnt(4)
	v_mfma_f32_32x32x16_bf16 v[80:95], v[246:249], v[180:183], v[80:95]
	ds_read_b128 v[246:249], v184 offset:8192
	s_waitcnt lgkmcnt(4)
	v_mfma_f32_32x32x16_bf16 v[64:79], v[250:253], v[180:183], v[64:79]
	ds_read_b128 v[250:253], v184 offset:12288
	s_waitcnt lgkmcnt(3)
	v_mfma_f32_32x32x16_bf16 v[112:127], v[238:241], v[190:193], v[112:127]
	s_waitcnt lgkmcnt(2)
	v_mfma_f32_32x32x16_bf16 v[96:111], v[242:245], v[190:193], v[96:111]
	s_waitcnt lgkmcnt(1)
	v_mfma_f32_32x32x16_bf16 v[80:95], v[246:249], v[190:193], v[80:95]
	s_waitcnt lgkmcnt(0)
	v_mfma_f32_32x32x16_bf16 v[64:79], v[250:253], v[190:193], v[64:79]
	s_waitcnt vmcnt(6)
	s_barrier
	v_add_u32_e32 v195, 0xc000, v186
	ds_read_b128 v[180:183], v195 offset:32768
	v_add_u32_e32 v194, 0xc000, v14
	ds_read_b128 v[238:241], v194
	ds_read_b128 v[242:245], v194 offset:4096
	ds_read_b128 v[246:249], v194 offset:8192
	ds_read_b128 v[250:253], v194 offset:12288
	v_add_u32_e32 v195, 0xc000, v189
	ds_read_b128 v[190:193], v195 offset:32768
	v_add_u32_e32 v194, 0xc000, v15
	s_waitcnt lgkmcnt(4)
	v_mfma_f32_32x32x16_bf16 v[112:127], v[238:241], v[180:183], v[112:127]
	ds_read_b128 v[238:241], v194
	s_add_u32 m0, s33, 0x0
	v_lshl_add_u64 v[2:3], v[2:3], 0, s[84:85]
	global_load_lds_dwordx4 v[2:3], off
	s_waitcnt lgkmcnt(4)
	v_mfma_f32_32x32x16_bf16 v[96:111], v[242:245], v[180:183], v[96:111]
	ds_read_b128 v[242:245], v194 offset:4096
	s_add_u32 m0, s33, 0x2000
	v_lshl_add_u64 v[6:7], v[6:7], 0, s[84:85]
	global_load_lds_dwordx4 v[6:7], off
	s_waitcnt lgkmcnt(4)
	v_mfma_f32_32x32x16_bf16 v[80:95], v[246:249], v[180:183], v[80:95]
	ds_read_b128 v[246:249], v194 offset:8192
	s_waitcnt lgkmcnt(4)
	v_mfma_f32_32x32x16_bf16 v[64:79], v[250:253], v[180:183], v[64:79]
	ds_read_b128 v[250:253], v194 offset:12288
	s_add_u32 m0, s33, 0x4000
	v_lshl_add_u64 v[8:9], v[8:9], 0, s[84:85]
	global_load_lds_dwordx4 v[8:9], off
	v_add_u32_e32 v195, 0xc000, v233
	ds_read_b128 v[180:183], v195 offset:32768
	v_add_u32_e32 v194, 0xc000, v0
	s_waitcnt lgkmcnt(4)
	v_mfma_f32_32x32x16_bf16 v[112:127], v[238:241], v[190:193], v[112:127]
	ds_read_b128 v[238:241], v194
	s_waitcnt lgkmcnt(4)
	v_mfma_f32_32x32x16_bf16 v[96:111], v[242:245], v[190:193], v[96:111]
	ds_read_b128 v[242:245], v194 offset:4096
	s_add_u32 m0, s33, 0x6000
	v_lshl_add_u64 v[10:11], v[10:11], 0, s[84:85]
	global_load_lds_dwordx4 v[10:11], off
	s_waitcnt lgkmcnt(4)
	v_mfma_f32_32x32x16_bf16 v[80:95], v[246:249], v[190:193], v[80:95]
	ds_read_b128 v[246:249], v194 offset:8192
	s_waitcnt lgkmcnt(4)
	v_mfma_f32_32x32x16_bf16 v[64:79], v[250:253], v[190:193], v[64:79]
	ds_read_b128 v[250:253], v194 offset:12288
	s_add_u32 m0, s33, 0x8000
	v_lshl_add_u64 v[4:5], v[4:5], 0, s[84:85]
	global_load_lds_dwordx4 v[4:5], off
	v_add_u32_e32 v195, 0xc000, v234
	ds_read_b128 v[190:193], v195 offset:32768
	v_add_u32_e32 v194, 0xc000, v184
	s_waitcnt lgkmcnt(4)
	v_mfma_f32_32x32x16_bf16 v[112:127], v[238:241], v[180:183], v[112:127]
	ds_read_b128 v[238:241], v194
	s_waitcnt lgkmcnt(4)
	v_mfma_f32_32x32x16_bf16 v[96:111], v[242:245], v[180:183], v[96:111]
	ds_read_b128 v[242:245], v194 offset:4096
	s_add_u32 m0, s33, 0xa000
	v_lshl_add_u64 v[12:13], v[12:13], 0, s[84:85]
	global_load_lds_dwordx4 v[12:13], off
	s_waitcnt lgkmcnt(4)
	v_mfma_f32_32x32x16_bf16 v[80:95], v[246:249], v[180:183], v[80:95]
	ds_read_b128 v[246:249], v194 offset:8192
	s_waitcnt lgkmcnt(4)
	v_mfma_f32_32x32x16_bf16 v[64:79], v[250:253], v[180:183], v[64:79]
	ds_read_b128 v[250:253], v194 offset:12288
	s_waitcnt lgkmcnt(3)
	v_mfma_f32_32x32x16_bf16 v[112:127], v[238:241], v[190:193], v[112:127]
	s_waitcnt lgkmcnt(2)
	v_mfma_f32_32x32x16_bf16 v[96:111], v[242:245], v[190:193], v[96:111]
	s_waitcnt lgkmcnt(1)
	v_mfma_f32_32x32x16_bf16 v[80:95], v[246:249], v[190:193], v[80:95]
	s_waitcnt lgkmcnt(0)
	v_mfma_f32_32x32x16_bf16 v[64:79], v[250:253], v[190:193], v[64:79]
	s_waitcnt vmcnt(6)
	s_barrier
; DI f32x16 mfma(bf16x8 a, bf16x8 b, f32x16 c) { return __builtin_amdgcn_mfma_f32_32x32x16_bf16(a, b, c, 0, 0, 0); }
;     ...
;   for (int kt = 0; kt < nk; ++kt) {
;     const char* cur = lds + (kt & 1) * DBUF;
;     if (kt + 1 < nk) DMA_ISSUE((kt + 1) & 1, kt + 1)
; #pragma unroll(NTB == 1 ? 2 : 4)
;     for (int s = 0; s < 4; ++s) {
;       const int ro = ((2 * s + hh) ^ xr) * 16;
;       bf16x8 bfr[NTB];
; #pragma unroll
;       for (int tb = 0; tb < NTB; ++tb) bfr[tb] = *(const bf16x8*)(cur + bbase + tb * 32 * DROW + ro);
; #pragma unroll
;       for (int fb = 0; fb < NFB; ++fb) {
;         const bf16x8 afr = *(const bf16x8*)(cur + abase + fb * 32 * DROW + ro);
; #pragma unroll
;         for (int tb = 0; tb < NTB; ++tb) acc[tb * NFB + fb] = mfma(afr, bfr[tb], acc[tb * NFB + fb]);
;       }
;     }
;     asm volatile("s_waitcnt vmcnt(0) lgkmcnt(0)" ::: "memory");
;     __builtin_amdgcn_s_barrier();
;   }
; __global__ void __launch_bounds__(512) mega(Params p) {
;     ...
;           zero4(acc);
;           gemm_main<4, 1>((const u16*)(ws + OFF_WG) + ((size_t)n * 1024 + ft * 256) * 1024, 1024, (const u16*)(ws + OFF_H) + (size_t)tt * 128 * 1024, 1024, 16, acc, lds);
	v_add_u32_e32 v195, 0x18000, v186
	ds_read_b128 v[180:183], v195 offset:32768
	v_add_u32_e32 v194, 0x18000, v14
	ds_read_b128 v[238:241], v194
	ds_read_b128 v[242:245], v194 offset:4096
	ds_read_b128 v[246:249], v194 offset:8192
	ds_read_b128 v[250:253], v194 offset:12288
	v_add_u32_e32 v195, 0x18000, v189
	ds_read_b128 v[190:193], v195 offset:32768
	v_add_u32_e32 v194, 0x18000, v15
	s_waitcnt lgkmcnt(4)
	v_mfma_f32_32x32x16_bf16 v[112:127], v[238:241], v[180:183], v[112:127]
	ds_read_b128 v[238:241], v194
	s_add_u32 m0, s33, 0xc000
	v_lshl_add_u64 v[2:3], v[2:3], 0, s[84:85]
	global_load_lds_dwordx4 v[2:3], off
	s_waitcnt lgkmcnt(4)
	v_mfma_f32_32x32x16_bf16 v[96:111], v[242:245], v[180:183], v[96:111]
	ds_read_b128 v[242:245], v194 offset:4096
	s_add_u32 m0, s33, 0xe000
	v_lshl_add_u64 v[6:7], v[6:7], 0, s[84:85]
	global_load_lds_dwordx4 v[6:7], off
	s_waitcnt lgkmcnt(4)
	v_mfma_f32_32x32x16_bf16 v[80:95], v[246:249], v[180:183], v[80:95]
	ds_read_b128 v[246:249], v194 offset:8192
	s_waitcnt lgkmcnt(4)
	v_mfma_f32_32x32x16_bf16 v[64:79], v[250:253], v[180:183], v[64:79]
	ds_read_b128 v[250:253], v194 offset:12288
	s_add_u32 m0, s33, 0x10000
	v_lshl_add_u64 v[8:9], v[8:9], 0, s[84:85]
	global_load_lds_dwordx4 v[8:9], off
	v_add_u32_e32 v195, 0x18000, v233
	ds_read_b128 v[180:183], v195 offset:32768
	v_add_u32_e32 v194, 0x18000, v0
	s_waitcnt lgkmcnt(4)
	v_mfma_f32_32x32x16_bf16 v[112:127], v[238:241], v[190:193], v[112:127]
	ds_read_b128 v[238:241], v194
	s_waitcnt lgkmcnt(4)
	v_mfma_f32_32x32x16_bf16 v[96:111], v[242:245], v[190:193], v[96:111]
	ds_read_b128 v[242:245], v194 offset:4096
	s_add_u32 m0, s33, 0x12000
	v_lshl_add_u64 v[10:11], v[10:11], 0, s[84:85]
	global_load_lds_dwordx4 v[10:11], off
	s_waitcnt lgkmcnt(4)
	v_mfma_f32_32x32x16_bf16 v[80:95], v[246:249], v[190:193], v[80:95]
	ds_read_b128 v[246:249], v194 offset:8192
	s_waitcnt lgkmcnt(4)
	v_mfma_f32_32x32x16_bf16 v[64:79], v[250:253], v[190:193], v[64:79]
	ds_read_b128 v[250:253], v194 offset:12288
	s_add_u32 m0, s33, 0x14000
	v_lshl_add_u64 v[4:5], v[4:5], 0, s[84:85]
	global_load_lds_dwordx4 v[4:5], off
	v_add_u32_e32 v195, 0x18000, v234
	ds_read_b128 v[190:193], v195 offset:32768
	v_add_u32_e32 v194, 0x18000, v184
	s_waitcnt lgkmcnt(4)
	v_mfma_f32_32x32x16_bf16 v[112:127], v[238:241], v[180:183], v[112:127]
	ds_read_b128 v[238:241], v194
	s_waitcnt lgkmcnt(4)
	v_mfma_f32_32x32x16_bf16 v[96:111], v[242:245], v[180:183], v[96:111]
	ds_read_b128 v[242:245], v194 offset:4096
	s_add_u32 m0, s33, 0x16000
	v_lshl_add_u64 v[12:13], v[12:13], 0, s[84:85]
	global_load_lds_dwordx4 v[12:13], off
	s_waitcnt lgkmcnt(4)
	v_mfma_f32_32x32x16_bf16 v[80:95], v[246:249], v[180:183], v[80:95]
	ds_read_b128 v[246:249], v194 offset:8192
	s_waitcnt lgkmcnt(4)
	v_mfma_f32_32x32x16_bf16 v[64:79], v[250:253], v[180:183], v[64:79]
	ds_read_b128 v[250:253], v194 offset:12288
	s_waitcnt lgkmcnt(3)
	v_mfma_f32_32x32x16_bf16 v[112:127], v[238:241], v[190:193], v[112:127]
	s_waitcnt lgkmcnt(2)
	v_mfma_f32_32x32x16_bf16 v[96:111], v[242:245], v[190:193], v[96:111]
	s_waitcnt lgkmcnt(1)
	v_mfma_f32_32x32x16_bf16 v[80:95], v[246:249], v[190:193], v[80:95]
	s_waitcnt lgkmcnt(0)
	v_mfma_f32_32x32x16_bf16 v[64:79], v[250:253], v[190:193], v[64:79]
	s_waitcnt vmcnt(6)
	s_barrier
	ds_read_b128 v[180:183], v186 offset:32768
	ds_read_b128 v[238:241], v14
	ds_read_b128 v[242:245], v14 offset:4096
	ds_read_b128 v[246:249], v14 offset:8192
	ds_read_b128 v[250:253], v14 offset:12288
	ds_read_b128 v[190:193], v189 offset:32768
	s_waitcnt lgkmcnt(4)
	v_mfma_f32_32x32x16_bf16 v[112:127], v[238:241], v[180:183], v[112:127]
	ds_read_b128 v[238:241], v15
	s_lshl_b64 s[34:35], s[34:35], 11
	s_add_u32 s34, s38, s34
	s_addc_u32 s35, s39, s35
	v_ashrrev_i32_e32 v18, 3, v145
	v_lshrrev_b32_e32 v16, 4, v145
	v_xor_b32_e32 v16, v16, v145
	v_ashrrev_i32_e32 v19, 31, v18
	v_lshlrev_b64 v[18:19], 11, v[18:19]
	v_lshlrev_b32_e32 v16, 4, v16
	v_and_b32_e32 v16, 0x70, v16
	v_mov_b32_e32 v17, 0
	v_lshl_add_u64 v[2:3], s[34:35], 0, v[18:19]
	v_lshl_add_u64 v[4:5], s[64:65], 0, v[18:19]
	v_lshl_add_u64 v[2:3], v[2:3], 0, v[16:17]
	v_lshl_add_u64 v[4:5], v[4:5], 0, v[16:17]
	s_mov_b64 s[68:69], 0x20000
	v_lshl_add_u64 v[6:7], v[2:3], 0, s[68:69]
	v_lshl_add_u64 v[12:13], v[4:5], 0, s[68:69]
	v_lshl_add_u64 v[8:9], v[6:7], 0, s[68:69]
	v_lshl_add_u64 v[10:11], v[8:9], 0, s[68:69]
	s_add_u32 m0, s33, 0x18000
	s_nop 0
	global_load_lds_dwordx4 v[2:3], off
	s_waitcnt lgkmcnt(4)
	v_mfma_f32_32x32x16_bf16 v[96:111], v[242:245], v[180:183], v[96:111]
	ds_read_b128 v[242:245], v15 offset:4096
	s_add_u32 m0, s33, 0x1a000
	s_nop 0
	global_load_lds_dwordx4 v[6:7], off
	s_waitcnt lgkmcnt(4)
	v_mfma_f32_32x32x16_bf16 v[80:95], v[246:249], v[180:183], v[80:95]
	ds_read_b128 v[246:249], v15 offset:8192
	s_waitcnt lgkmcnt(4)
	v_mfma_f32_32x32x16_bf16 v[64:79], v[250:253], v[180:183], v[64:79]
	ds_read_b128 v[250:253], v15 offset:12288
	s_add_u32 m0, s33, 0x1c000
	s_nop 0
	global_load_lds_dwordx4 v[8:9], off
	ds_read_b128 v[180:183], v233 offset:32768
	s_waitcnt lgkmcnt(4)
	v_mfma_f32_32x32x16_bf16 v[112:127], v[238:241], v[190:193], v[112:127]
	ds_read_b128 v[238:241], v0
	s_waitcnt lgkmcnt(4)
	v_mfma_f32_32x32x16_bf16 v[96:111], v[242:245], v[190:193], v[96:111]
	ds_read_b128 v[242:245], v0 offset:4096
	s_add_u32 m0, s33, 0x1e000
	s_nop 0
	global_load_lds_dwordx4 v[10:11], off
	s_waitcnt lgkmcnt(4)
	v_mfma_f32_32x32x16_bf16 v[80:95], v[246:249], v[190:193], v[80:95]
	ds_read_b128 v[246:249], v0 offset:8192
	s_waitcnt lgkmcnt(4)
	v_mfma_f32_32x32x16_bf16 v[64:79], v[250:253], v[190:193], v[64:79]
	ds_read_b128 v[250:253], v0 offset:12288
	s_add_u32 m0, s33, 0x20000
	s_nop 0
	global_load_lds_dwordx4 v[4:5], off
	ds_read_b128 v[190:193], v234 offset:32768
	s_waitcnt lgkmcnt(4)
	v_mfma_f32_32x32x16_bf16 v[112:127], v[238:241], v[180:183], v[112:127]
	ds_read_b128 v[238:241], v184
	s_waitcnt lgkmcnt(4)
	v_mfma_f32_32x32x16_bf16 v[96:111], v[242:245], v[180:183], v[96:111]
	ds_read_b128 v[242:245], v184 offset:4096
	s_add_u32 m0, s33, 0x22000
	s_nop 0
	global_load_lds_dwordx4 v[12:13], off
	s_waitcnt lgkmcnt(4)
	v_mfma_f32_32x32x16_bf16 v[80:95], v[246:249], v[180:183], v[80:95]
	ds_read_b128 v[246:249], v184 offset:8192
	s_waitcnt lgkmcnt(4)
	v_mfma_f32_32x32x16_bf16 v[64:79], v[250:253], v[180:183], v[64:79]
	ds_read_b128 v[250:253], v184 offset:12288
	s_waitcnt lgkmcnt(3)
	v_mfma_f32_32x32x16_bf16 v[112:127], v[238:241], v[190:193], v[112:127]
	s_waitcnt lgkmcnt(2)
	v_mfma_f32_32x32x16_bf16 v[96:111], v[242:245], v[190:193], v[96:111]
	s_waitcnt lgkmcnt(1)
	v_mfma_f32_32x32x16_bf16 v[80:95], v[246:249], v[190:193], v[80:95]
	s_waitcnt lgkmcnt(0)
	v_mfma_f32_32x32x16_bf16 v[64:79], v[250:253], v[190:193], v[64:79]
	s_waitcnt vmcnt(6)
	s_barrier
; DI f32x16 mfma(bf16x8 a, bf16x8 b, f32x16 c) { return __builtin_amdgcn_mfma_f32_32x32x16_bf16(a, b, c, 0, 0, 0); }
;     ...
;   for (int kt = 0; kt < nk; ++kt) {
;     const char* cur = lds + (kt & 1) * DBUF;
;     if (kt + 1 < nk) DMA_ISSUE((kt + 1) & 1, kt + 1)
; #pragma unroll(NTB == 1 ? 2 : 4)
;     for (int s = 0; s < 4; ++s) {
;       const int ro = ((2 * s + hh) ^ xr) * 16;
;       bf16x8 bfr[NTB];
; #pragma unroll
;       for (int tb = 0; tb < NTB; ++tb) bfr[tb] = *(const bf16x8*)(cur + bbase + tb * 32 * DROW + ro);
; #pragma unroll
;       for (int fb = 0; fb < NFB; ++fb) {
;         const bf16x8 afr = *(const bf16x8*)(cur + abase + fb * 32 * DROW + ro);
; #pragma unroll
;         for (int tb = 0; tb < NTB; ++tb) acc[tb * NFB + fb] = mfma(afr, bfr[tb], acc[tb * NFB + fb]);
;       }
;     }
;     asm volatile("s_waitcnt vmcnt(0) lgkmcnt(0)" ::: "memory");
;     __builtin_amdgcn_s_barrier();
;   }
; __global__ void __launch_bounds__(512) mega(Params p) {
;     ...
;           zero4(acc);
;           gemm_main<4, 1>((const u16*)(ws + OFF_WG) + ((size_t)n * 1024 + ft * 256) * 1024, 1024, (const u16*)(ws + OFF_H) + (size_t)tt * 128 * 1024, 1024, 16, acc, lds);
	v_add_u32_e32 v195, 0xc000, v186
	ds_read_b128 v[180:183], v195 offset:32768
	v_add_u32_e32 v194, 0xc000, v14
	ds_read_b128 v[238:241], v194
	ds_read_b128 v[242:245], v194 offset:4096
	ds_read_b128 v[246:249], v194 offset:8192
	ds_read_b128 v[250:253], v194 offset:12288
	v_add_u32_e32 v195, 0xc000, v189
	ds_read_b128 v[190:193], v195 offset:32768
	v_add_u32_e32 v194, 0xc000, v15
	s_waitcnt lgkmcnt(4)
	v_mfma_f32_32x32x16_bf16 v[112:127], v[238:241], v[180:183], v[112:127]
	ds_read_b128 v[238:241], v194
	s_add_u32 m0, s33, 0x0
	v_lshl_add_u64 v[2:3], v[2:3], 0, s[84:85]
	global_load_lds_dwordx4 v[2:3], off
	s_waitcnt lgkmcnt(4)
	v_mfma_f32_32x32x16_bf16 v[96:111], v[242:245], v[180:183], v[96:111]
	ds_read_b128 v[242:245], v194 offset:4096
	s_add_u32 m0, s33, 0x2000
	v_lshl_add_u64 v[6:7], v[6:7], 0, s[84:85]
	global_load_lds_dwordx4 v[6:7], off
	s_waitcnt lgkmcnt(4)
	v_mfma_f32_32x32x16_bf16 v[80:95], v[246:249], v[180:183], v[80:95]
	ds_read_b128 v[246:249], v194 offset:8192
	s_waitcnt lgkmcnt(4)
	v_mfma_f32_32x32x16_bf16 v[64:79], v[250:253], v[180:183], v[64:79]
	ds_read_b128 v[250:253], v194 offset:12288
	s_add_u32 m0, s33, 0x4000
	v_lshl_add_u64 v[8:9], v[8:9], 0, s[84:85]
	global_load_lds_dwordx4 v[8:9], off
	v_add_u32_e32 v195, 0xc000, v233
	ds_read_b128 v[180:183], v195 offset:32768
	v_add_u32_e32 v194, 0xc000, v0
	s_waitcnt lgkmcnt(4)
	v_mfma_f32_32x32x16_bf16 v[112:127], v[238:241], v[190:193], v[112:127]
	ds_read_b128 v[238:241], v194
	s_waitcnt lgkmcnt(4)
	v_mfma_f32_32x32x16_bf16 v[96:111], v[242:245], v[190:193], v[96:111]
	ds_read_b128 v[242:245], v194 offset:4096
	s_add_u32 m0, s33, 0x6000
	v_lshl_add_u64 v[10:11], v[10:11], 0, s[84:85]
	global_load_lds_dwordx4 v[10:11], off
	s_waitcnt lgkmcnt(4)
	v_mfma_f32_32x32x16_bf16 v[80:95], v[246:249], v[190:193], v[80:95]
	ds_read_b128 v[246:249], v194 offset:8192
	s_waitcnt lgkmcnt(4)
	v_mfma_f32_32x32x16_bf16 v[64:79], v[250:253], v[190:193], v[64:79]
	ds_read_b128 v[250:253], v194 offset:12288
	s_add_u32 m0, s33, 0x8000
	v_lshl_add_u64 v[4:5], v[4:5], 0, s[84:85]
	global_load_lds_dwordx4 v[4:5], off
	v_add_u32_e32 v195, 0xc000, v234
	ds_read_b128 v[190:193], v195 offset:32768
	v_add_u32_e32 v194, 0xc000, v184
	s_waitcnt lgkmcnt(4)
	v_mfma_f32_32x32x16_bf16 v[112:127], v[238:241], v[180:183], v[112:127]
	ds_read_b128 v[238:241], v194
	s_waitcnt lgkmcnt(4)
	v_mfma_f32_32x32x16_bf16 v[96:111], v[242:245], v[180:183], v[96:111]
	ds_read_b128 v[242:245], v194 offset:4096
	s_add_u32 m0, s33, 0xa000
	v_lshl_add_u64 v[12:13], v[12:13], 0, s[84:85]
	global_load_lds_dwordx4 v[12:13], off
	s_waitcnt lgkmcnt(4)
	v_mfma_f32_32x32x16_bf16 v[80:95], v[246:249], v[180:183], v[80:95]
	ds_read_b128 v[246:249], v194 offset:8192
	s_waitcnt lgkmcnt(4)
	v_mfma_f32_32x32x16_bf16 v[64:79], v[250:253], v[180:183], v[64:79]
	ds_read_b128 v[250:253], v194 offset:12288
	s_waitcnt lgkmcnt(3)
	v_mfma_f32_32x32x16_bf16 v[112:127], v[238:241], v[190:193], v[112:127]
	s_waitcnt lgkmcnt(2)
	v_mfma_f32_32x32x16_bf16 v[96:111], v[242:245], v[190:193], v[96:111]
	s_waitcnt lgkmcnt(1)
	v_mfma_f32_32x32x16_bf16 v[80:95], v[246:249], v[190:193], v[80:95]
	s_waitcnt lgkmcnt(0)
	v_mfma_f32_32x32x16_bf16 v[64:79], v[250:253], v[190:193], v[64:79]
	s_waitcnt vmcnt(6)
	s_barrier
	v_add_u32_e32 v195, 0x18000, v186
	ds_read_b128 v[180:183], v195 offset:32768
	v_add_u32_e32 v194, 0x18000, v14
	ds_read_b128 v[238:241], v194
	ds_read_b128 v[242:245], v194 offset:4096
	ds_read_b128 v[246:249], v194 offset:8192
	ds_read_b128 v[250:253], v194 offset:12288
	v_add_u32_e32 v195, 0x18000, v189
	ds_read_b128 v[190:193], v195 offset:32768
	v_add_u32_e32 v194, 0x18000, v15
	s_waitcnt lgkmcnt(4)
	v_mfma_f32_32x32x16_bf16 v[128:143], v[238:241], v[180:183], 0
	ds_read_b128 v[238:241], v194
	s_add_u32 m0, s33, 0xc000
	v_lshl_add_u64 v[2:3], v[2:3], 0, s[84:85]
	global_load_lds_dwordx4 v[2:3], off
	s_waitcnt lgkmcnt(4)
	v_mfma_f32_32x32x16_bf16 v[48:63], v[242:245], v[180:183], 0
	ds_read_b128 v[242:245], v194 offset:4096
	s_add_u32 m0, s33, 0xe000
	v_lshl_add_u64 v[6:7], v[6:7], 0, s[84:85]
	global_load_lds_dwordx4 v[6:7], off
	s_waitcnt lgkmcnt(4)
	v_mfma_f32_32x32x16_bf16 v[32:47], v[246:249], v[180:183], 0
	ds_read_b128 v[246:249], v194 offset:8192
	s_waitcnt lgkmcnt(4)
	v_mfma_f32_32x32x16_bf16 v[16:31], v[250:253], v[180:183], 0
	ds_read_b128 v[250:253], v194 offset:12288
	s_add_u32 m0, s33, 0x10000
	v_lshl_add_u64 v[8:9], v[8:9], 0, s[84:85]
	global_load_lds_dwordx4 v[8:9], off
	v_add_u32_e32 v195, 0x18000, v233
	ds_read_b128 v[180:183], v195 offset:32768
	v_add_u32_e32 v194, 0x18000, v0
	s_waitcnt lgkmcnt(4)
	v_mfma_f32_32x32x16_bf16 v[128:143], v[238:241], v[190:193], v[128:143]
	ds_read_b128 v[238:241], v194
	s_waitcnt lgkmcnt(4)
	v_mfma_f32_32x32x16_bf16 v[48:63], v[242:245], v[190:193], v[48:63]
	ds_read_b128 v[242:245], v194 offset:4096
	s_add_u32 m0, s33, 0x12000
	v_lshl_add_u64 v[10:11], v[10:11], 0, s[84:85]
	global_load_lds_dwordx4 v[10:11], off
	s_waitcnt lgkmcnt(4)
	v_mfma_f32_32x32x16_bf16 v[32:47], v[246:249], v[190:193], v[32:47]
	ds_read_b128 v[246:249], v194 offset:8192
	s_waitcnt lgkmcnt(4)
	v_mfma_f32_32x32x16_bf16 v[16:31], v[250:253], v[190:193], v[16:31]
	ds_read_b128 v[250:253], v194 offset:12288
	s_add_u32 m0, s33, 0x14000
	v_lshl_add_u64 v[4:5], v[4:5], 0, s[84:85]
	global_load_lds_dwordx4 v[4:5], off
	v_add_u32_e32 v195, 0x18000, v234
	ds_read_b128 v[190:193], v195 offset:32768
	v_add_u32_e32 v194, 0x18000, v184
	s_waitcnt lgkmcnt(4)
	v_mfma_f32_32x32x16_bf16 v[128:143], v[238:241], v[180:183], v[128:143]
	ds_read_b128 v[238:241], v194
	s_waitcnt lgkmcnt(4)
	v_mfma_f32_32x32x16_bf16 v[48:63], v[242:245], v[180:183], v[48:63]
	ds_read_b128 v[242:245], v194 offset:4096
	s_add_u32 m0, s33, 0x16000
	v_lshl_add_u64 v[12:13], v[12:13], 0, s[84:85]
	global_load_lds_dwordx4 v[12:13], off
	s_waitcnt lgkmcnt(4)
	v_mfma_f32_32x32x16_bf16 v[32:47], v[246:249], v[180:183], v[32:47]
	ds_read_b128 v[246:249], v194 offset:8192
	s_waitcnt lgkmcnt(4)
	v_mfma_f32_32x32x16_bf16 v[16:31], v[250:253], v[180:183], v[16:31]
	ds_read_b128 v[250:253], v194 offset:12288
	s_waitcnt lgkmcnt(3)
	v_mfma_f32_32x32x16_bf16 v[128:143], v[238:241], v[190:193], v[128:143]
	s_waitcnt lgkmcnt(2)
	v_mfma_f32_32x32x16_bf16 v[48:63], v[242:245], v[190:193], v[48:63]
	s_waitcnt lgkmcnt(1)
	v_mfma_f32_32x32x16_bf16 v[32:47], v[246:249], v[190:193], v[32:47]
	s_waitcnt lgkmcnt(0)
	v_mfma_f32_32x32x16_bf16 v[16:31], v[250:253], v[190:193], v[16:31]
	s_waitcnt vmcnt(6)
	s_barrier
; DI f32x16 mfma(bf16x8 a, bf16x8 b, f32x16 c) { return __builtin_amdgcn_mfma_f32_32x32x16_bf16(a, b, c, 0, 0, 0); }
;     ...
;   for (int kt = 0; kt < nk; ++kt) {
;     const char* cur = lds + (kt & 1) * DBUF;
;     if (kt + 1 < nk) DMA_ISSUE((kt + 1) & 1, kt + 1)
; #pragma unroll(NTB == 1 ? 2 : 4)
;     for (int s = 0; s < 4; ++s) {
;       const int ro = ((2 * s + hh) ^ xr) * 16;
;       bf16x8 bfr[NTB];
; #pragma unroll
;       for (int tb = 0; tb < NTB; ++tb) bfr[tb] = *(const bf16x8*)(cur + bbase + tb * 32 * DROW + ro);
; #pragma unroll
;       for (int fb = 0; fb < NFB; ++fb) {
;         const bf16x8 afr = *(const bf16x8*)(cur + abase + fb * 32 * DROW + ro);
; #pragma unroll
;         for (int tb = 0; tb < NTB; ++tb) acc[tb * NFB + fb] = mfma(afr, bfr[tb], acc[tb * NFB + fb]);
;       }
;     }
;     asm volatile("s_waitcnt vmcnt(0) lgkmcnt(0)" ::: "memory");
;     __builtin_amdgcn_s_barrier();
;   }
	ds_read_b128 v[180:183], v186 offset:32768
	ds_read_b128 v[238:241], v14
	ds_read_b128 v[242:245], v14 offset:4096
	ds_read_b128 v[246:249], v14 offset:8192
	ds_read_b128 v[250:253], v14 offset:12288
	ds_read_b128 v[190:193], v189 offset:32768
	s_waitcnt lgkmcnt(4)
	v_mfma_f32_32x32x16_bf16 v[128:143], v[238:241], v[180:183], v[128:143]
	ds_read_b128 v[238:241], v15
	s_add_u32 m0, s33, 0x18000
	v_lshl_add_u64 v[2:3], v[2:3], 0, s[84:85]
	global_load_lds_dwordx4 v[2:3], off
	s_waitcnt lgkmcnt(4)
	v_mfma_f32_32x32x16_bf16 v[48:63], v[242:245], v[180:183], v[48:63]
	ds_read_b128 v[242:245], v15 offset:4096
	s_add_u32 m0, s33, 0x1a000
	v_lshl_add_u64 v[6:7], v[6:7], 0, s[84:85]
	global_load_lds_dwordx4 v[6:7], off
	s_waitcnt lgkmcnt(4)
	v_mfma_f32_32x32x16_bf16 v[32:47], v[246:249], v[180:183], v[32:47]
	ds_read_b128 v[246:249], v15 offset:8192
	s_waitcnt lgkmcnt(4)
	v_mfma_f32_32x32x16_bf16 v[16:31], v[250:253], v[180:183], v[16:31]
	ds_read_b128 v[250:253], v15 offset:12288
	s_add_u32 m0, s33, 0x1c000
	v_lshl_add_u64 v[8:9], v[8:9], 0, s[84:85]
	global_load_lds_dwordx4 v[8:9], off
	ds_read_b128 v[180:183], v233 offset:32768
	s_waitcnt lgkmcnt(4)
	v_mfma_f32_32x32x16_bf16 v[128:143], v[238:241], v[190:193], v[128:143]
	ds_read_b128 v[238:241], v0
	s_waitcnt lgkmcnt(4)
	v_mfma_f32_32x32x16_bf16 v[48:63], v[242:245], v[190:193], v[48:63]
	ds_read_b128 v[242:245], v0 offset:4096
	s_add_u32 m0, s33, 0x1e000
	v_lshl_add_u64 v[10:11], v[10:11], 0, s[84:85]
	global_load_lds_dwordx4 v[10:11], off
	s_waitcnt lgkmcnt(4)
	v_mfma_f32_32x32x16_bf16 v[32:47], v[246:249], v[190:193], v[32:47]
	ds_read_b128 v[246:249], v0 offset:8192
	s_waitcnt lgkmcnt(4)
	v_mfma_f32_32x32x16_bf16 v[16:31], v[250:253], v[190:193], v[16:31]
	ds_read_b128 v[250:253], v0 offset:12288
	s_add_u32 m0, s33, 0x20000
	v_lshl_add_u64 v[4:5], v[4:5], 0, s[84:85]
	global_load_lds_dwordx4 v[4:5], off
	ds_read_b128 v[190:193], v234 offset:32768
	s_waitcnt lgkmcnt(4)
	v_mfma_f32_32x32x16_bf16 v[128:143], v[238:241], v[180:183], v[128:143]
	ds_read_b128 v[238:241], v184
	s_waitcnt lgkmcnt(4)
	v_mfma_f32_32x32x16_bf16 v[48:63], v[242:245], v[180:183], v[48:63]
	ds_read_b128 v[242:245], v184 offset:4096
	s_add_u32 m0, s33, 0x22000
	v_lshl_add_u64 v[12:13], v[12:13], 0, s[84:85]
	global_load_lds_dwordx4 v[12:13], off
	s_waitcnt lgkmcnt(4)
	v_mfma_f32_32x32x16_bf16 v[32:47], v[246:249], v[180:183], v[32:47]
	ds_read_b128 v[246:249], v184 offset:8192
	s_waitcnt lgkmcnt(4)
	v_mfma_f32_32x32x16_bf16 v[16:31], v[250:253], v[180:183], v[16:31]
	ds_read_b128 v[250:253], v184 offset:12288
	s_waitcnt lgkmcnt(3)
	v_mfma_f32_32x32x16_bf16 v[128:143], v[238:241], v[190:193], v[128:143]
	s_waitcnt lgkmcnt(2)
	v_mfma_f32_32x32x16_bf16 v[48:63], v[242:245], v[190:193], v[48:63]
	s_waitcnt lgkmcnt(1)
	v_mfma_f32_32x32x16_bf16 v[32:47], v[246:249], v[190:193], v[32:47]
	s_waitcnt lgkmcnt(0)
	v_mfma_f32_32x32x16_bf16 v[16:31], v[250:253], v[190:193], v[16:31]
	s_waitcnt vmcnt(6)
	s_barrier
	v_add_u32_e32 v195, 0xc000, v186
	ds_read_b128 v[180:183], v195 offset:32768
	v_add_u32_e32 v194, 0xc000, v14
	ds_read_b128 v[238:241], v194
	ds_read_b128 v[242:245], v194 offset:4096
	ds_read_b128 v[246:249], v194 offset:8192
	ds_read_b128 v[250:253], v194 offset:12288
	v_add_u32_e32 v195, 0xc000, v189
	ds_read_b128 v[190:193], v195 offset:32768
	v_add_u32_e32 v194, 0xc000, v15
	s_waitcnt lgkmcnt(4)
	v_mfma_f32_32x32x16_bf16 v[128:143], v[238:241], v[180:183], v[128:143]
	ds_read_b128 v[238:241], v194
	s_add_u32 m0, s33, 0x0
	v_lshl_add_u64 v[2:3], v[2:3], 0, s[84:85]
	global_load_lds_dwordx4 v[2:3], off
	s_waitcnt lgkmcnt(4)
	v_mfma_f32_32x32x16_bf16 v[48:63], v[242:245], v[180:183], v[48:63]
	ds_read_b128 v[242:245], v194 offset:4096
	s_add_u32 m0, s33, 0x2000
	v_lshl_add_u64 v[6:7], v[6:7], 0, s[84:85]
	global_load_lds_dwordx4 v[6:7], off
	s_waitcnt lgkmcnt(4)
	v_mfma_f32_32x32x16_bf16 v[32:47], v[246:249], v[180:183], v[32:47]
	ds_read_b128 v[246:249], v194 offset:8192
	s_waitcnt lgkmcnt(4)
	v_mfma_f32_32x32x16_bf16 v[16:31], v[250:253], v[180:183], v[16:31]
	ds_read_b128 v[250:253], v194 offset:12288
	s_add_u32 m0, s33, 0x4000
	v_lshl_add_u64 v[8:9], v[8:9], 0, s[84:85]
	global_load_lds_dwordx4 v[8:9], off
	v_add_u32_e32 v195, 0xc000, v233
	ds_read_b128 v[180:183], v195 offset:32768
	v_add_u32_e32 v194, 0xc000, v0
	s_waitcnt lgkmcnt(4)
	v_mfma_f32_32x32x16_bf16 v[128:143], v[238:241], v[190:193], v[128:143]
	ds_read_b128 v[238:241], v194
	s_waitcnt lgkmcnt(4)
	v_mfma_f32_32x32x16_bf16 v[48:63], v[242:245], v[190:193], v[48:63]
	ds_read_b128 v[242:245], v194 offset:4096
	s_add_u32 m0, s33, 0x6000
	v_lshl_add_u64 v[10:11], v[10:11], 0, s[84:85]
	global_load_lds_dwordx4 v[10:11], off
	s_waitcnt lgkmcnt(4)
	v_mfma_f32_32x32x16_bf16 v[32:47], v[246:249], v[190:193], v[32:47]
	ds_read_b128 v[246:249], v194 offset:8192
	s_waitcnt lgkmcnt(4)
	v_mfma_f32_32x32x16_bf16 v[16:31], v[250:253], v[190:193], v[16:31]
	ds_read_b128 v[250:253], v194 offset:12288
	s_add_u32 m0, s33, 0x8000
	v_lshl_add_u64 v[4:5], v[4:5], 0, s[84:85]
	global_load_lds_dwordx4 v[4:5], off
	v_add_u32_e32 v195, 0xc000, v234
	ds_read_b128 v[190:193], v195 offset:32768
	v_add_u32_e32 v194, 0xc000, v184
	s_waitcnt lgkmcnt(4)
	v_mfma_f32_32x32x16_bf16 v[128:143], v[238:241], v[180:183], v[128:143]
	ds_read_b128 v[238:241], v194
	s_waitcnt lgkmcnt(4)
	v_mfma_f32_32x32x16_bf16 v[48:63], v[242:245], v[180:183], v[48:63]
	ds_read_b128 v[242:245], v194 offset:4096
	s_add_u32 m0, s33, 0xa000
	v_lshl_add_u64 v[12:13], v[12:13], 0, s[84:85]
	global_load_lds_dwordx4 v[12:13], off
	s_waitcnt lgkmcnt(4)
	v_mfma_f32_32x32x16_bf16 v[32:47], v[246:249], v[180:183], v[32:47]
	ds_read_b128 v[246:249], v194 offset:8192
	s_waitcnt lgkmcnt(4)
	v_mfma_f32_32x32x16_bf16 v[16:31], v[250:253], v[180:183], v[16:31]
	ds_read_b128 v[250:253], v194 offset:12288
	s_waitcnt lgkmcnt(3)
	v_mfma_f32_32x32x16_bf16 v[128:143], v[238:241], v[190:193], v[128:143]
	s_waitcnt lgkmcnt(2)
	v_mfma_f32_32x32x16_bf16 v[48:63], v[242:245], v[190:193], v[48:63]
	s_waitcnt lgkmcnt(1)
	v_mfma_f32_32x32x16_bf16 v[32:47], v[246:249], v[190:193], v[32:47]
	s_waitcnt lgkmcnt(0)
	v_mfma_f32_32x32x16_bf16 v[16:31], v[250:253], v[190:193], v[16:31]
	s_waitcnt vmcnt(6)
	s_barrier
; DI f32x16 mfma(bf16x8 a, bf16x8 b, f32x16 c) { return __builtin_amdgcn_mfma_f32_32x32x16_bf16(a, b, c, 0, 0, 0); }
;     ...
;   for (int kt = 0; kt < nk; ++kt) {
;     const char* cur = lds + (kt & 1) * DBUF;
;     if (kt + 1 < nk) DMA_ISSUE((kt + 1) & 1, kt + 1)
; #pragma unroll(NTB == 1 ? 2 : 4)
;     for (int s = 0; s < 4; ++s) {
;       const int ro = ((2 * s + hh) ^ xr) * 16;
;       bf16x8 bfr[NTB];
; #pragma unroll
;       for (int tb = 0; tb < NTB; ++tb) bfr[tb] = *(const bf16x8*)(cur + bbase + tb * 32 * DROW + ro);
; #pragma unroll
;       for (int fb = 0; fb < NFB; ++fb) {
;         const bf16x8 afr = *(const bf16x8*)(cur + abase + fb * 32 * DROW + ro);
; #pragma unroll
;         for (int tb = 0; tb < NTB; ++tb) acc[tb * NFB + fb] = mfma(afr, bfr[tb], acc[tb * NFB + fb]);
;       }
;     }
;     asm volatile("s_waitcnt vmcnt(0) lgkmcnt(0)" ::: "memory");
;     __builtin_amdgcn_s_barrier();
;   }
	v_add_u32_e32 v195, 0x18000, v186
	ds_read_b128 v[180:183], v195 offset:32768
	v_add_u32_e32 v194, 0x18000, v14
	ds_read_b128 v[238:241], v194
	ds_read_b128 v[242:245], v194 offset:4096
	ds_read_b128 v[246:249], v194 offset:8192
	ds_read_b128 v[250:253], v194 offset:12288
	v_add_u32_e32 v195, 0x18000, v189
	ds_read_b128 v[190:193], v195 offset:32768
	v_add_u32_e32 v194, 0x18000, v15
	s_waitcnt lgkmcnt(4)
	v_mfma_f32_32x32x16_bf16 v[128:143], v[238:241], v[180:183], v[128:143]
	ds_read_b128 v[238:241], v194
	s_add_u32 m0, s33, 0xc000
	v_lshl_add_u64 v[2:3], v[2:3], 0, s[84:85]
	global_load_lds_dwordx4 v[2:3], off
	s_waitcnt lgkmcnt(4)
	v_mfma_f32_32x32x16_bf16 v[48:63], v[242:245], v[180:183], v[48:63]
	ds_read_b128 v[242:245], v194 offset:4096
	s_add_u32 m0, s33, 0xe000
	v_lshl_add_u64 v[6:7], v[6:7], 0, s[84:85]
	global_load_lds_dwordx4 v[6:7], off
	s_waitcnt lgkmcnt(4)
	v_mfma_f32_32x32x16_bf16 v[32:47], v[246:249], v[180:183], v[32:47]
	ds_read_b128 v[246:249], v194 offset:8192
	s_waitcnt lgkmcnt(4)
	v_mfma_f32_32x32x16_bf16 v[16:31], v[250:253], v[180:183], v[16:31]
	ds_read_b128 v[250:253], v194 offset:12288
	s_add_u32 m0, s33, 0x10000
	v_lshl_add_u64 v[8:9], v[8:9], 0, s[84:85]
	global_load_lds_dwordx4 v[8:9], off
	v_add_u32_e32 v195, 0x18000, v233
	ds_read_b128 v[180:183], v195 offset:32768
	v_add_u32_e32 v194, 0x18000, v0
	s_waitcnt lgkmcnt(4)
	v_mfma_f32_32x32x16_bf16 v[128:143], v[238:241], v[190:193], v[128:143]
	ds_read_b128 v[238:241], v194
	s_waitcnt lgkmcnt(4)
	v_mfma_f32_32x32x16_bf16 v[48:63], v[242:245], v[190:193], v[48:63]
	ds_read_b128 v[242:245], v194 offset:4096
	s_add_u32 m0, s33, 0x12000
	v_lshl_add_u64 v[10:11], v[10:11], 0, s[84:85]
	global_load_lds_dwordx4 v[10:11], off
	s_waitcnt lgkmcnt(4)
	v_mfma_f32_32x32x16_bf16 v[32:47], v[246:249], v[190:193], v[32:47]
	ds_read_b128 v[246:249], v194 offset:8192
	s_waitcnt lgkmcnt(4)
	v_mfma_f32_32x32x16_bf16 v[16:31], v[250:253], v[190:193], v[16:31]
	ds_read_b128 v[250:253], v194 offset:12288
	s_add_u32 m0, s33, 0x14000
	v_lshl_add_u64 v[4:5], v[4:5], 0, s[84:85]
	global_load_lds_dwordx4 v[4:5], off
	v_add_u32_e32 v195, 0x18000, v234
	ds_read_b128 v[190:193], v195 offset:32768
	v_add_u32_e32 v194, 0x18000, v184
	s_waitcnt lgkmcnt(4)
	v_mfma_f32_32x32x16_bf16 v[128:143], v[238:241], v[180:183], v[128:143]
	ds_read_b128 v[238:241], v194
	s_waitcnt lgkmcnt(4)
	v_mfma_f32_32x32x16_bf16 v[48:63], v[242:245], v[180:183], v[48:63]
	ds_read_b128 v[242:245], v194 offset:4096
	s_add_u32 m0, s33, 0x16000
	v_lshl_add_u64 v[12:13], v[12:13], 0, s[84:85]
	global_load_lds_dwordx4 v[12:13], off
	s_waitcnt lgkmcnt(4)
	v_mfma_f32_32x32x16_bf16 v[32:47], v[246:249], v[180:183], v[32:47]
	ds_read_b128 v[246:249], v194 offset:8192
	s_waitcnt lgkmcnt(4)
	v_mfma_f32_32x32x16_bf16 v[16:31], v[250:253], v[180:183], v[16:31]
	ds_read_b128 v[250:253], v194 offset:12288
	s_waitcnt lgkmcnt(3)
	v_mfma_f32_32x32x16_bf16 v[128:143], v[238:241], v[190:193], v[128:143]
	s_waitcnt lgkmcnt(2)
	v_mfma_f32_32x32x16_bf16 v[48:63], v[242:245], v[190:193], v[48:63]
	s_waitcnt lgkmcnt(1)
	v_mfma_f32_32x32x16_bf16 v[32:47], v[246:249], v[190:193], v[32:47]
	s_waitcnt lgkmcnt(0)
	v_mfma_f32_32x32x16_bf16 v[16:31], v[250:253], v[190:193], v[16:31]
	s_waitcnt vmcnt(6)
	s_barrier
	ds_read_b128 v[180:183], v186 offset:32768
	ds_read_b128 v[238:241], v14
	ds_read_b128 v[242:245], v14 offset:4096
	ds_read_b128 v[246:249], v14 offset:8192
	ds_read_b128 v[250:253], v14 offset:12288
	ds_read_b128 v[190:193], v189 offset:32768
	s_waitcnt lgkmcnt(4)
	v_mfma_f32_32x32x16_bf16 v[128:143], v[238:241], v[180:183], v[128:143]
	ds_read_b128 v[238:241], v15
	s_add_u32 m0, s33, 0x18000
	v_lshl_add_u64 v[2:3], v[2:3], 0, s[84:85]
	global_load_lds_dwordx4 v[2:3], off
	s_waitcnt lgkmcnt(4)
	v_mfma_f32_32x32x16_bf16 v[48:63], v[242:245], v[180:183], v[48:63]
	ds_read_b128 v[242:245], v15 offset:4096
	s_add_u32 m0, s33, 0x1a000
	v_lshl_add_u64 v[6:7], v[6:7], 0, s[84:85]
	global_load_lds_dwordx4 v[6:7], off
	s_waitcnt lgkmcnt(4)
	v_mfma_f32_32x32x16_bf16 v[32:47], v[246:249], v[180:183], v[32:47]
	ds_read_b128 v[246:249], v15 offset:8192
	s_waitcnt lgkmcnt(4)
	v_mfma_f32_32x32x16_bf16 v[16:31], v[250:253], v[180:183], v[16:31]
	ds_read_b128 v[250:253], v15 offset:12288
	s_add_u32 m0, s33, 0x1c000
	v_lshl_add_u64 v[8:9], v[8:9], 0, s[84:85]
	global_load_lds_dwordx4 v[8:9], off
	ds_read_b128 v[180:183], v233 offset:32768
	s_waitcnt lgkmcnt(4)
	v_mfma_f32_32x32x16_bf16 v[128:143], v[238:241], v[190:193], v[128:143]
	ds_read_b128 v[238:241], v0
	s_waitcnt lgkmcnt(4)
	v_mfma_f32_32x32x16_bf16 v[48:63], v[242:245], v[190:193], v[48:63]
	ds_read_b128 v[242:245], v0 offset:4096
	s_add_u32 m0, s33, 0x1e000
	v_lshl_add_u64 v[10:11], v[10:11], 0, s[84:85]
	global_load_lds_dwordx4 v[10:11], off
	s_waitcnt lgkmcnt(4)
	v_mfma_f32_32x32x16_bf16 v[32:47], v[246:249], v[190:193], v[32:47]
	ds_read_b128 v[246:249], v0 offset:8192
	s_waitcnt lgkmcnt(4)
	v_mfma_f32_32x32x16_bf16 v[16:31], v[250:253], v[190:193], v[16:31]
	ds_read_b128 v[250:253], v0 offset:12288
	s_add_u32 m0, s33, 0x20000
	v_lshl_add_u64 v[4:5], v[4:5], 0, s[84:85]
	global_load_lds_dwordx4 v[4:5], off
	ds_read_b128 v[190:193], v234 offset:32768
	s_waitcnt lgkmcnt(4)
	v_mfma_f32_32x32x16_bf16 v[128:143], v[238:241], v[180:183], v[128:143]
	ds_read_b128 v[238:241], v184
	s_waitcnt lgkmcnt(4)
	v_mfma_f32_32x32x16_bf16 v[48:63], v[242:245], v[180:183], v[48:63]
	ds_read_b128 v[242:245], v184 offset:4096
	s_add_u32 m0, s33, 0x22000
	v_lshl_add_u64 v[12:13], v[12:13], 0, s[84:85]
	global_load_lds_dwordx4 v[12:13], off
	s_waitcnt lgkmcnt(4)
	v_mfma_f32_32x32x16_bf16 v[32:47], v[246:249], v[180:183], v[32:47]
	ds_read_b128 v[246:249], v184 offset:8192
	s_waitcnt lgkmcnt(4)
	v_mfma_f32_32x32x16_bf16 v[16:31], v[250:253], v[180:183], v[16:31]
	ds_read_b128 v[250:253], v184 offset:12288
	s_waitcnt lgkmcnt(3)
	v_mfma_f32_32x32x16_bf16 v[128:143], v[238:241], v[190:193], v[128:143]
	s_waitcnt lgkmcnt(2)
	v_mfma_f32_32x32x16_bf16 v[48:63], v[242:245], v[190:193], v[48:63]
	s_waitcnt lgkmcnt(1)
	v_mfma_f32_32x32x16_bf16 v[32:47], v[246:249], v[190:193], v[32:47]
	s_waitcnt lgkmcnt(0)
	v_mfma_f32_32x32x16_bf16 v[16:31], v[250:253], v[190:193], v[16:31]
	s_waitcnt vmcnt(6)
	s_barrier
; DI f32x16 mfma(bf16x8 a, bf16x8 b, f32x16 c) { return __builtin_amdgcn_mfma_f32_32x32x16_bf16(a, b, c, 0, 0, 0); }
;     ...
;   for (int kt = 0; kt < nk; ++kt) {
;     const char* cur = lds + (kt & 1) * DBUF;
;     if (kt + 1 < nk) DMA_ISSUE((kt + 1) & 1, kt + 1)
; #pragma unroll(NTB == 1 ? 2 : 4)
;     for (int s = 0; s < 4; ++s) {
;       const int ro = ((2 * s + hh) ^ xr) * 16;
;       bf16x8 bfr[NTB];
; #pragma unroll
;       for (int tb = 0; tb < NTB; ++tb) bfr[tb] = *(const bf16x8*)(cur + bbase + tb * 32 * DROW + ro);
; #pragma unroll
;       for (int fb = 0; fb < NFB; ++fb) {
;         const bf16x8 afr = *(const bf16x8*)(cur + abase + fb * 32 * DROW + ro);
; #pragma unroll
;         for (int tb = 0; tb < NTB; ++tb) acc[tb * NFB + fb] = mfma(afr, bfr[tb], acc[tb * NFB + fb]);
;       }
;     }
;     asm volatile("s_waitcnt vmcnt(0) lgkmcnt(0)" ::: "memory");
;     __builtin_amdgcn_s_barrier();
;   }
	v_add_u32_e32 v195, 0xc000, v186
	ds_read_b128 v[180:183], v195 offset:32768
	v_add_u32_e32 v194, 0xc000, v14
	ds_read_b128 v[238:241], v194
	ds_read_b128 v[242:245], v194 offset:4096
	ds_read_b128 v[246:249], v194 offset:8192
	ds_read_b128 v[250:253], v194 offset:12288
	v_add_u32_e32 v195, 0xc000, v189
	ds_read_b128 v[190:193], v195 offset:32768
	v_add_u32_e32 v194, 0xc000, v15
	s_waitcnt lgkmcnt(4)
	v_mfma_f32_32x32x16_bf16 v[128:143], v[238:241], v[180:183], v[128:143]
	ds_read_b128 v[238:241], v194
	s_add_u32 m0, s33, 0x0
	v_lshl_add_u64 v[2:3], v[2:3], 0, s[84:85]
	global_load_lds_dwordx4 v[2:3], off
	s_waitcnt lgkmcnt(4)
	v_mfma_f32_32x32x16_bf16 v[48:63], v[242:245], v[180:183], v[48:63]
	ds_read_b128 v[242:245], v194 offset:4096
	s_add_u32 m0, s33, 0x2000
	v_lshl_add_u64 v[6:7], v[6:7], 0, s[84:85]
	global_load_lds_dwordx4 v[6:7], off
	s_waitcnt lgkmcnt(4)
	v_mfma_f32_32x32x16_bf16 v[32:47], v[246:249], v[180:183], v[32:47]
	ds_read_b128 v[246:249], v194 offset:8192
	s_waitcnt lgkmcnt(4)
	v_mfma_f32_32x32x16_bf16 v[16:31], v[250:253], v[180:183], v[16:31]
	ds_read_b128 v[250:253], v194 offset:12288
	s_add_u32 m0, s33, 0x4000
	v_lshl_add_u64 v[8:9], v[8:9], 0, s[84:85]
	global_load_lds_dwordx4 v[8:9], off
	v_add_u32_e32 v195, 0xc000, v233
	ds_read_b128 v[180:183], v195 offset:32768
	v_add_u32_e32 v194, 0xc000, v0
	s_waitcnt lgkmcnt(4)
	v_mfma_f32_32x32x16_bf16 v[128:143], v[238:241], v[190:193], v[128:143]
	ds_read_b128 v[238:241], v194
	s_waitcnt lgkmcnt(4)
	v_mfma_f32_32x32x16_bf16 v[48:63], v[242:245], v[190:193], v[48:63]
	ds_read_b128 v[242:245], v194 offset:4096
	s_add_u32 m0, s33, 0x6000
	v_lshl_add_u64 v[10:11], v[10:11], 0, s[84:85]
	global_load_lds_dwordx4 v[10:11], off
	s_waitcnt lgkmcnt(4)
	v_mfma_f32_32x32x16_bf16 v[32:47], v[246:249], v[190:193], v[32:47]
	ds_read_b128 v[246:249], v194 offset:8192
	s_waitcnt lgkmcnt(4)
	v_mfma_f32_32x32x16_bf16 v[16:31], v[250:253], v[190:193], v[16:31]
	ds_read_b128 v[250:253], v194 offset:12288
	s_add_u32 m0, s33, 0x8000
	v_lshl_add_u64 v[4:5], v[4:5], 0, s[84:85]
	global_load_lds_dwordx4 v[4:5], off
	v_add_u32_e32 v195, 0xc000, v234
	ds_read_b128 v[190:193], v195 offset:32768
	v_add_u32_e32 v194, 0xc000, v184
	s_waitcnt lgkmcnt(4)
	v_mfma_f32_32x32x16_bf16 v[128:143], v[238:241], v[180:183], v[128:143]
	ds_read_b128 v[238:241], v194
	s_waitcnt lgkmcnt(4)
	v_mfma_f32_32x32x16_bf16 v[48:63], v[242:245], v[180:183], v[48:63]
	ds_read_b128 v[242:245], v194 offset:4096
	s_add_u32 m0, s33, 0xa000
	v_lshl_add_u64 v[12:13], v[12:13], 0, s[84:85]
	global_load_lds_dwordx4 v[12:13], off
	s_waitcnt lgkmcnt(4)
	v_mfma_f32_32x32x16_bf16 v[32:47], v[246:249], v[180:183], v[32:47]
	ds_read_b128 v[246:249], v194 offset:8192
	s_waitcnt lgkmcnt(4)
	v_mfma_f32_32x32x16_bf16 v[16:31], v[250:253], v[180:183], v[16:31]
	ds_read_b128 v[250:253], v194 offset:12288
	s_waitcnt lgkmcnt(3)
	v_mfma_f32_32x32x16_bf16 v[128:143], v[238:241], v[190:193], v[128:143]
	s_waitcnt lgkmcnt(2)
	v_mfma_f32_32x32x16_bf16 v[48:63], v[242:245], v[190:193], v[48:63]
	s_waitcnt lgkmcnt(1)
	v_mfma_f32_32x32x16_bf16 v[32:47], v[246:249], v[190:193], v[32:47]
	s_waitcnt lgkmcnt(0)
	v_mfma_f32_32x32x16_bf16 v[16:31], v[250:253], v[190:193], v[16:31]
	s_waitcnt vmcnt(6)
	s_barrier
	v_add_u32_e32 v195, 0x18000, v186
	ds_read_b128 v[180:183], v195 offset:32768
	v_add_u32_e32 v194, 0x18000, v14
	ds_read_b128 v[238:241], v194
	ds_read_b128 v[242:245], v194 offset:4096
	ds_read_b128 v[246:249], v194 offset:8192
	ds_read_b128 v[250:253], v194 offset:12288
	v_add_u32_e32 v195, 0x18000, v189
	ds_read_b128 v[190:193], v195 offset:32768
	v_add_u32_e32 v194, 0x18000, v15
	s_waitcnt lgkmcnt(4)
	v_mfma_f32_32x32x16_bf16 v[128:143], v[238:241], v[180:183], v[128:143]
	ds_read_b128 v[238:241], v194
	s_add_u32 m0, s33, 0xc000
	v_lshl_add_u64 v[2:3], v[2:3], 0, s[84:85]
	global_load_lds_dwordx4 v[2:3], off
	s_waitcnt lgkmcnt(4)
	v_mfma_f32_32x32x16_bf16 v[48:63], v[242:245], v[180:183], v[48:63]
	ds_read_b128 v[242:245], v194 offset:4096
	s_add_u32 m0, s33, 0xe000
	v_lshl_add_u64 v[6:7], v[6:7], 0, s[84:85]
	global_load_lds_dwordx4 v[6:7], off
	s_waitcnt lgkmcnt(4)
	v_mfma_f32_32x32x16_bf16 v[32:47], v[246:249], v[180:183], v[32:47]
	ds_read_b128 v[246:249], v194 offset:8192
	s_waitcnt lgkmcnt(4)
	v_mfma_f32_32x32x16_bf16 v[16:31], v[250:253], v[180:183], v[16:31]
	ds_read_b128 v[250:253], v194 offset:12288
	s_add_u32 m0, s33, 0x10000
	v_lshl_add_u64 v[8:9], v[8:9], 0, s[84:85]
	global_load_lds_dwordx4 v[8:9], off
	v_add_u32_e32 v195, 0x18000, v233
	ds_read_b128 v[180:183], v195 offset:32768
	v_add_u32_e32 v194, 0x18000, v0
	s_waitcnt lgkmcnt(4)
	v_mfma_f32_32x32x16_bf16 v[128:143], v[238:241], v[190:193], v[128:143]
	ds_read_b128 v[238:241], v194
	s_waitcnt lgkmcnt(4)
	v_mfma_f32_32x32x16_bf16 v[48:63], v[242:245], v[190:193], v[48:63]
	ds_read_b128 v[242:245], v194 offset:4096
	s_add_u32 m0, s33, 0x12000
	v_lshl_add_u64 v[10:11], v[10:11], 0, s[84:85]
	global_load_lds_dwordx4 v[10:11], off
	s_waitcnt lgkmcnt(4)
	v_mfma_f32_32x32x16_bf16 v[32:47], v[246:249], v[190:193], v[32:47]
	ds_read_b128 v[246:249], v194 offset:8192
	s_waitcnt lgkmcnt(4)
	v_mfma_f32_32x32x16_bf16 v[16:31], v[250:253], v[190:193], v[16:31]
	ds_read_b128 v[250:253], v194 offset:12288
	s_add_u32 m0, s33, 0x14000
	v_lshl_add_u64 v[4:5], v[4:5], 0, s[84:85]
	global_load_lds_dwordx4 v[4:5], off
	v_add_u32_e32 v195, 0x18000, v234
	ds_read_b128 v[190:193], v195 offset:32768
	v_add_u32_e32 v194, 0x18000, v184
	s_waitcnt lgkmcnt(4)
	v_mfma_f32_32x32x16_bf16 v[128:143], v[238:241], v[180:183], v[128:143]
	ds_read_b128 v[238:241], v194
	s_waitcnt lgkmcnt(4)
	v_mfma_f32_32x32x16_bf16 v[48:63], v[242:245], v[180:183], v[48:63]
	ds_read_b128 v[242:245], v194 offset:4096
	s_add_u32 m0, s33, 0x16000
	v_lshl_add_u64 v[12:13], v[12:13], 0, s[84:85]
	global_load_lds_dwordx4 v[12:13], off
	s_waitcnt lgkmcnt(4)
	v_mfma_f32_32x32x16_bf16 v[32:47], v[246:249], v[180:183], v[32:47]
	ds_read_b128 v[246:249], v194 offset:8192
	s_waitcnt lgkmcnt(4)
	v_mfma_f32_32x32x16_bf16 v[16:31], v[250:253], v[180:183], v[16:31]
	ds_read_b128 v[250:253], v194 offset:12288
	s_waitcnt lgkmcnt(3)
	v_mfma_f32_32x32x16_bf16 v[128:143], v[238:241], v[190:193], v[128:143]
	s_waitcnt lgkmcnt(2)
	v_mfma_f32_32x32x16_bf16 v[48:63], v[242:245], v[190:193], v[48:63]
	s_waitcnt lgkmcnt(1)
	v_mfma_f32_32x32x16_bf16 v[32:47], v[246:249], v[190:193], v[32:47]
	s_waitcnt lgkmcnt(0)
	v_mfma_f32_32x32x16_bf16 v[16:31], v[250:253], v[190:193], v[16:31]
	s_waitcnt vmcnt(6)
	s_barrier
; DI f32x16 mfma(bf16x8 a, bf16x8 b, f32x16 c) { return __builtin_amdgcn_mfma_f32_32x32x16_bf16(a, b, c, 0, 0, 0); }
;     ...
;   for (int kt = 0; kt < nk; ++kt) {
;     const char* cur = lds + (kt & 1) * DBUF;
;     if (kt + 1 < nk) DMA_ISSUE((kt + 1) & 1, kt + 1)
; #pragma unroll(NTB == 1 ? 2 : 4)
;     for (int s = 0; s < 4; ++s) {
;       const int ro = ((2 * s + hh) ^ xr) * 16;
;       bf16x8 bfr[NTB];
; #pragma unroll
;       for (int tb = 0; tb < NTB; ++tb) bfr[tb] = *(const bf16x8*)(cur + bbase + tb * 32 * DROW + ro);
; #pragma unroll
;       for (int fb = 0; fb < NFB; ++fb) {
;         const bf16x8 afr = *(const bf16x8*)(cur + abase + fb * 32 * DROW + ro);
; #pragma unroll
;         for (int tb = 0; tb < NTB; ++tb) acc[tb * NFB + fb] = mfma(afr, bfr[tb], acc[tb * NFB + fb]);
;       }
;     }
;     asm volatile("s_waitcnt vmcnt(0) lgkmcnt(0)" ::: "memory");
;     __builtin_amdgcn_s_barrier();
;   }
	ds_read_b128 v[180:183], v186 offset:32768
	ds_read_b128 v[238:241], v14
	ds_read_b128 v[242:245], v14 offset:4096
	ds_read_b128 v[246:249], v14 offset:8192
	ds_read_b128 v[250:253], v14 offset:12288
	ds_read_b128 v[190:193], v189 offset:32768
	s_waitcnt lgkmcnt(4)
	v_mfma_f32_32x32x16_bf16 v[128:143], v[238:241], v[180:183], v[128:143]
	ds_read_b128 v[238:241], v15
	s_add_u32 m0, s33, 0x18000
	v_lshl_add_u64 v[2:3], v[2:3], 0, s[84:85]
	global_load_lds_dwordx4 v[2:3], off
	s_waitcnt lgkmcnt(4)
	v_mfma_f32_32x32x16_bf16 v[48:63], v[242:245], v[180:183], v[48:63]
	ds_read_b128 v[242:245], v15 offset:4096
	s_add_u32 m0, s33, 0x1a000
	v_lshl_add_u64 v[6:7], v[6:7], 0, s[84:85]
	global_load_lds_dwordx4 v[6:7], off
	s_waitcnt lgkmcnt(4)
	v_mfma_f32_32x32x16_bf16 v[32:47], v[246:249], v[180:183], v[32:47]
	ds_read_b128 v[246:249], v15 offset:8192
	s_waitcnt lgkmcnt(4)
	v_mfma_f32_32x32x16_bf16 v[16:31], v[250:253], v[180:183], v[16:31]
	ds_read_b128 v[250:253], v15 offset:12288
	s_add_u32 m0, s33, 0x1c000
	v_lshl_add_u64 v[8:9], v[8:9], 0, s[84:85]
	global_load_lds_dwordx4 v[8:9], off
	ds_read_b128 v[180:183], v233 offset:32768
	s_waitcnt lgkmcnt(4)
	v_mfma_f32_32x32x16_bf16 v[128:143], v[238:241], v[190:193], v[128:143]
	ds_read_b128 v[238:241], v0
	s_waitcnt lgkmcnt(4)
	v_mfma_f32_32x32x16_bf16 v[48:63], v[242:245], v[190:193], v[48:63]
	ds_read_b128 v[242:245], v0 offset:4096
	s_add_u32 m0, s33, 0x1e000
	v_lshl_add_u64 v[10:11], v[10:11], 0, s[84:85]
	global_load_lds_dwordx4 v[10:11], off
	s_waitcnt lgkmcnt(4)
	v_mfma_f32_32x32x16_bf16 v[32:47], v[246:249], v[190:193], v[32:47]
	ds_read_b128 v[246:249], v0 offset:8192
	s_waitcnt lgkmcnt(4)
	v_mfma_f32_32x32x16_bf16 v[16:31], v[250:253], v[190:193], v[16:31]
	ds_read_b128 v[250:253], v0 offset:12288
	s_add_u32 m0, s33, 0x20000
	v_lshl_add_u64 v[4:5], v[4:5], 0, s[84:85]
	global_load_lds_dwordx4 v[4:5], off
	ds_read_b128 v[190:193], v234 offset:32768
	s_waitcnt lgkmcnt(4)
	v_mfma_f32_32x32x16_bf16 v[128:143], v[238:241], v[180:183], v[128:143]
	ds_read_b128 v[238:241], v184
	s_waitcnt lgkmcnt(4)
	v_mfma_f32_32x32x16_bf16 v[48:63], v[242:245], v[180:183], v[48:63]
	ds_read_b128 v[242:245], v184 offset:4096
	s_add_u32 m0, s33, 0x22000
	v_lshl_add_u64 v[12:13], v[12:13], 0, s[84:85]
	global_load_lds_dwordx4 v[12:13], off
	s_waitcnt lgkmcnt(4)
	v_mfma_f32_32x32x16_bf16 v[32:47], v[246:249], v[180:183], v[32:47]
	ds_read_b128 v[246:249], v184 offset:8192
	s_waitcnt lgkmcnt(4)
	v_mfma_f32_32x32x16_bf16 v[16:31], v[250:253], v[180:183], v[16:31]
	ds_read_b128 v[250:253], v184 offset:12288
	s_waitcnt lgkmcnt(3)
	v_mfma_f32_32x32x16_bf16 v[128:143], v[238:241], v[190:193], v[128:143]
	s_waitcnt lgkmcnt(2)
	v_mfma_f32_32x32x16_bf16 v[48:63], v[242:245], v[190:193], v[48:63]
	s_waitcnt lgkmcnt(1)
	v_mfma_f32_32x32x16_bf16 v[32:47], v[246:249], v[190:193], v[32:47]
	s_waitcnt lgkmcnt(0)
	v_mfma_f32_32x32x16_bf16 v[16:31], v[250:253], v[190:193], v[16:31]
	s_waitcnt vmcnt(6)
	s_barrier
	v_add_u32_e32 v195, 0xc000, v186
	ds_read_b128 v[180:183], v195 offset:32768
	v_add_u32_e32 v194, 0xc000, v14
	ds_read_b128 v[238:241], v194
	ds_read_b128 v[242:245], v194 offset:4096
	ds_read_b128 v[246:249], v194 offset:8192
	ds_read_b128 v[250:253], v194 offset:12288
	v_add_u32_e32 v195, 0xc000, v189
	ds_read_b128 v[190:193], v195 offset:32768
	v_add_u32_e32 v194, 0xc000, v15
	s_waitcnt lgkmcnt(4)
	v_mfma_f32_32x32x16_bf16 v[128:143], v[238:241], v[180:183], v[128:143]
	ds_read_b128 v[238:241], v194
	s_add_u32 m0, s33, 0x0
	v_lshl_add_u64 v[2:3], v[2:3], 0, s[84:85]
	global_load_lds_dwordx4 v[2:3], off
	s_waitcnt lgkmcnt(4)
	v_mfma_f32_32x32x16_bf16 v[48:63], v[242:245], v[180:183], v[48:63]
	ds_read_b128 v[242:245], v194 offset:4096
	s_add_u32 m0, s33, 0x2000
	v_lshl_add_u64 v[6:7], v[6:7], 0, s[84:85]
	global_load_lds_dwordx4 v[6:7], off
	s_waitcnt lgkmcnt(4)
	v_mfma_f32_32x32x16_bf16 v[32:47], v[246:249], v[180:183], v[32:47]
	ds_read_b128 v[246:249], v194 offset:8192
	s_waitcnt lgkmcnt(4)
	v_mfma_f32_32x32x16_bf16 v[16:31], v[250:253], v[180:183], v[16:31]
	ds_read_b128 v[250:253], v194 offset:12288
	s_add_u32 m0, s33, 0x4000
	v_lshl_add_u64 v[8:9], v[8:9], 0, s[84:85]
	global_load_lds_dwordx4 v[8:9], off
	v_add_u32_e32 v195, 0xc000, v233
	ds_read_b128 v[180:183], v195 offset:32768
	v_add_u32_e32 v194, 0xc000, v0
	s_waitcnt lgkmcnt(4)
	v_mfma_f32_32x32x16_bf16 v[128:143], v[238:241], v[190:193], v[128:143]
	ds_read_b128 v[238:241], v194
	s_waitcnt lgkmcnt(4)
	v_mfma_f32_32x32x16_bf16 v[48:63], v[242:245], v[190:193], v[48:63]
	ds_read_b128 v[242:245], v194 offset:4096
	s_add_u32 m0, s33, 0x6000
	v_lshl_add_u64 v[10:11], v[10:11], 0, s[84:85]
	global_load_lds_dwordx4 v[10:11], off
	s_waitcnt lgkmcnt(4)
	v_mfma_f32_32x32x16_bf16 v[32:47], v[246:249], v[190:193], v[32:47]
	ds_read_b128 v[246:249], v194 offset:8192
	s_waitcnt lgkmcnt(4)
	v_mfma_f32_32x32x16_bf16 v[16:31], v[250:253], v[190:193], v[16:31]
	ds_read_b128 v[250:253], v194 offset:12288
	s_add_u32 m0, s33, 0x8000
	v_lshl_add_u64 v[4:5], v[4:5], 0, s[84:85]
	global_load_lds_dwordx4 v[4:5], off
	v_add_u32_e32 v195, 0xc000, v234
	ds_read_b128 v[190:193], v195 offset:32768
	v_add_u32_e32 v194, 0xc000, v184
	s_waitcnt lgkmcnt(4)
	v_mfma_f32_32x32x16_bf16 v[128:143], v[238:241], v[180:183], v[128:143]
	ds_read_b128 v[238:241], v194
	s_waitcnt lgkmcnt(4)
	v_mfma_f32_32x32x16_bf16 v[48:63], v[242:245], v[180:183], v[48:63]
	ds_read_b128 v[242:245], v194 offset:4096
	s_add_u32 m0, s33, 0xa000
	v_lshl_add_u64 v[12:13], v[12:13], 0, s[84:85]
	global_load_lds_dwordx4 v[12:13], off
	s_waitcnt lgkmcnt(4)
	v_mfma_f32_32x32x16_bf16 v[32:47], v[246:249], v[180:183], v[32:47]
	ds_read_b128 v[246:249], v194 offset:8192
	s_waitcnt lgkmcnt(4)
	v_mfma_f32_32x32x16_bf16 v[16:31], v[250:253], v[180:183], v[16:31]
	ds_read_b128 v[250:253], v194 offset:12288
	s_waitcnt lgkmcnt(3)
	v_mfma_f32_32x32x16_bf16 v[128:143], v[238:241], v[190:193], v[128:143]
	s_waitcnt lgkmcnt(2)
	v_mfma_f32_32x32x16_bf16 v[48:63], v[242:245], v[190:193], v[48:63]
	s_waitcnt lgkmcnt(1)
	v_mfma_f32_32x32x16_bf16 v[32:47], v[246:249], v[190:193], v[32:47]
	s_waitcnt lgkmcnt(0)
	v_mfma_f32_32x32x16_bf16 v[16:31], v[250:253], v[190:193], v[16:31]
	s_waitcnt vmcnt(6)
	s_barrier
; DI f32x16 mfma(bf16x8 a, bf16x8 b, f32x16 c) { return __builtin_amdgcn_mfma_f32_32x32x16_bf16(a, b, c, 0, 0, 0); }
;     ...
;   for (int kt = 0; kt < nk; ++kt) {
;     const char* cur = lds + (kt & 1) * DBUF;
;     if (kt + 1 < nk) DMA_ISSUE((kt + 1) & 1, kt + 1)
; #pragma unroll(NTB == 1 ? 2 : 4)
;     for (int s = 0; s < 4; ++s) {
;       const int ro = ((2 * s + hh) ^ xr) * 16;
;       bf16x8 bfr[NTB];
; #pragma unroll
;       for (int tb = 0; tb < NTB; ++tb) bfr[tb] = *(const bf16x8*)(cur + bbase + tb * 32 * DROW + ro);
; #pragma unroll
;       for (int fb = 0; fb < NFB; ++fb) {
;         const bf16x8 afr = *(const bf16x8*)(cur + abase + fb * 32 * DROW + ro);
; #pragma unroll
;         for (int tb = 0; tb < NTB; ++tb) acc[tb * NFB + fb] = mfma(afr, bfr[tb], acc[tb * NFB + fb]);
;       }
;     }
;     asm volatile("s_waitcnt vmcnt(0) lgkmcnt(0)" ::: "memory");
;     __builtin_amdgcn_s_barrier();
;   }
	v_add_u32_e32 v195, 0x18000, v186
	ds_read_b128 v[180:183], v195 offset:32768
	v_add_u32_e32 v194, 0x18000, v14
	ds_read_b128 v[238:241], v194
	ds_read_b128 v[242:245], v194 offset:4096
	ds_read_b128 v[246:249], v194 offset:8192
	ds_read_b128 v[250:253], v194 offset:12288
	v_add_u32_e32 v195, 0x18000, v189
	ds_read_b128 v[190:193], v195 offset:32768
	v_add_u32_e32 v194, 0x18000, v15
	s_waitcnt lgkmcnt(4)
	v_mfma_f32_32x32x16_bf16 v[128:143], v[238:241], v[180:183], v[128:143]
	ds_read_b128 v[238:241], v194
	s_add_u32 m0, s33, 0xc000
	v_lshl_add_u64 v[2:3], v[2:3], 0, s[84:85]
	global_load_lds_dwordx4 v[2:3], off
	s_waitcnt lgkmcnt(4)
	v_mfma_f32_32x32x16_bf16 v[48:63], v[242:245], v[180:183], v[48:63]
	ds_read_b128 v[242:245], v194 offset:4096
	s_add_u32 m0, s33, 0xe000
	v_lshl_add_u64 v[6:7], v[6:7], 0, s[84:85]
	global_load_lds_dwordx4 v[6:7], off
	s_waitcnt lgkmcnt(4)
	v_mfma_f32_32x32x16_bf16 v[32:47], v[246:249], v[180:183], v[32:47]
	ds_read_b128 v[246:249], v194 offset:8192
	s_waitcnt lgkmcnt(4)
	v_mfma_f32_32x32x16_bf16 v[16:31], v[250:253], v[180:183], v[16:31]
	ds_read_b128 v[250:253], v194 offset:12288
	s_add_u32 m0, s33, 0x10000
	v_lshl_add_u64 v[8:9], v[8:9], 0, s[84:85]
	global_load_lds_dwordx4 v[8:9], off
	v_add_u32_e32 v195, 0x18000, v233
	ds_read_b128 v[180:183], v195 offset:32768
	v_add_u32_e32 v194, 0x18000, v0
	s_waitcnt lgkmcnt(4)
	v_mfma_f32_32x32x16_bf16 v[128:143], v[238:241], v[190:193], v[128:143]
	ds_read_b128 v[238:241], v194
	s_waitcnt lgkmcnt(4)
	v_mfma_f32_32x32x16_bf16 v[48:63], v[242:245], v[190:193], v[48:63]
	ds_read_b128 v[242:245], v194 offset:4096
	s_add_u32 m0, s33, 0x12000
	v_lshl_add_u64 v[10:11], v[10:11], 0, s[84:85]
	global_load_lds_dwordx4 v[10:11], off
	s_waitcnt lgkmcnt(4)
	v_mfma_f32_32x32x16_bf16 v[32:47], v[246:249], v[190:193], v[32:47]
	ds_read_b128 v[246:249], v194 offset:8192
	s_waitcnt lgkmcnt(4)
	v_mfma_f32_32x32x16_bf16 v[16:31], v[250:253], v[190:193], v[16:31]
	ds_read_b128 v[250:253], v194 offset:12288
	s_add_u32 m0, s33, 0x14000
	v_lshl_add_u64 v[4:5], v[4:5], 0, s[84:85]
	global_load_lds_dwordx4 v[4:5], off
	v_add_u32_e32 v195, 0x18000, v234
	ds_read_b128 v[190:193], v195 offset:32768
	v_add_u32_e32 v194, 0x18000, v184
	s_waitcnt lgkmcnt(4)
	v_mfma_f32_32x32x16_bf16 v[128:143], v[238:241], v[180:183], v[128:143]
	ds_read_b128 v[238:241], v194
	s_waitcnt lgkmcnt(4)
	v_mfma_f32_32x32x16_bf16 v[48:63], v[242:245], v[180:183], v[48:63]
	ds_read_b128 v[242:245], v194 offset:4096
	s_add_u32 m0, s33, 0x16000
	v_lshl_add_u64 v[12:13], v[12:13], 0, s[84:85]
	global_load_lds_dwordx4 v[12:13], off
	s_waitcnt lgkmcnt(4)
	v_mfma_f32_32x32x16_bf16 v[32:47], v[246:249], v[180:183], v[32:47]
	ds_read_b128 v[246:249], v194 offset:8192
	s_waitcnt lgkmcnt(4)
	v_mfma_f32_32x32x16_bf16 v[16:31], v[250:253], v[180:183], v[16:31]
	ds_read_b128 v[250:253], v194 offset:12288
	s_waitcnt lgkmcnt(3)
	v_mfma_f32_32x32x16_bf16 v[128:143], v[238:241], v[190:193], v[128:143]
	s_waitcnt lgkmcnt(2)
	v_mfma_f32_32x32x16_bf16 v[48:63], v[242:245], v[190:193], v[48:63]
	s_waitcnt lgkmcnt(1)
	v_mfma_f32_32x32x16_bf16 v[32:47], v[246:249], v[190:193], v[32:47]
	s_waitcnt lgkmcnt(0)
	v_mfma_f32_32x32x16_bf16 v[16:31], v[250:253], v[190:193], v[16:31]
	s_waitcnt vmcnt(6)
	s_barrier
	ds_read_b128 v[180:183], v186 offset:32768
	ds_read_b128 v[238:241], v14
	ds_read_b128 v[242:245], v14 offset:4096
	ds_read_b128 v[246:249], v14 offset:8192
	ds_read_b128 v[250:253], v14 offset:12288
	ds_read_b128 v[190:193], v189 offset:32768
	s_waitcnt lgkmcnt(4)
	v_mfma_f32_32x32x16_bf16 v[128:143], v[238:241], v[180:183], v[128:143]
	ds_read_b128 v[238:241], v15
	s_add_u32 m0, s33, 0x18000
	v_lshl_add_u64 v[2:3], v[2:3], 0, s[84:85]
	global_load_lds_dwordx4 v[2:3], off
	s_waitcnt lgkmcnt(4)
	v_mfma_f32_32x32x16_bf16 v[48:63], v[242:245], v[180:183], v[48:63]
	ds_read_b128 v[242:245], v15 offset:4096
	s_add_u32 m0, s33, 0x1a000
	v_lshl_add_u64 v[6:7], v[6:7], 0, s[84:85]
	global_load_lds_dwordx4 v[6:7], off
	s_waitcnt lgkmcnt(4)
	v_mfma_f32_32x32x16_bf16 v[32:47], v[246:249], v[180:183], v[32:47]
	ds_read_b128 v[246:249], v15 offset:8192
	s_waitcnt lgkmcnt(4)
	v_mfma_f32_32x32x16_bf16 v[16:31], v[250:253], v[180:183], v[16:31]
	ds_read_b128 v[250:253], v15 offset:12288
	s_add_u32 m0, s33, 0x1c000
	v_lshl_add_u64 v[8:9], v[8:9], 0, s[84:85]
	global_load_lds_dwordx4 v[8:9], off
	ds_read_b128 v[180:183], v233 offset:32768
	s_waitcnt lgkmcnt(4)
	v_mfma_f32_32x32x16_bf16 v[128:143], v[238:241], v[190:193], v[128:143]
	ds_read_b128 v[238:241], v0
	s_waitcnt lgkmcnt(4)
	v_mfma_f32_32x32x16_bf16 v[48:63], v[242:245], v[190:193], v[48:63]
	ds_read_b128 v[242:245], v0 offset:4096
	s_add_u32 m0, s33, 0x1e000
	v_lshl_add_u64 v[10:11], v[10:11], 0, s[84:85]
	global_load_lds_dwordx4 v[10:11], off
	s_waitcnt lgkmcnt(4)
	v_mfma_f32_32x32x16_bf16 v[32:47], v[246:249], v[190:193], v[32:47]
	ds_read_b128 v[246:249], v0 offset:8192
	s_waitcnt lgkmcnt(4)
	v_mfma_f32_32x32x16_bf16 v[16:31], v[250:253], v[190:193], v[16:31]
	ds_read_b128 v[250:253], v0 offset:12288
	s_add_u32 m0, s33, 0x20000
	v_lshl_add_u64 v[4:5], v[4:5], 0, s[84:85]
	global_load_lds_dwordx4 v[4:5], off
	ds_read_b128 v[190:193], v234 offset:32768
	s_waitcnt lgkmcnt(4)
	v_mfma_f32_32x32x16_bf16 v[128:143], v[238:241], v[180:183], v[128:143]
	ds_read_b128 v[238:241], v184
	s_waitcnt lgkmcnt(4)
	v_mfma_f32_32x32x16_bf16 v[48:63], v[242:245], v[180:183], v[48:63]
	ds_read_b128 v[242:245], v184 offset:4096
	s_add_u32 m0, s33, 0x22000
	v_lshl_add_u64 v[12:13], v[12:13], 0, s[84:85]
	global_load_lds_dwordx4 v[12:13], off
	s_waitcnt lgkmcnt(4)
	v_mfma_f32_32x32x16_bf16 v[32:47], v[246:249], v[180:183], v[32:47]
	ds_read_b128 v[246:249], v184 offset:8192
	s_waitcnt lgkmcnt(4)
	v_mfma_f32_32x32x16_bf16 v[16:31], v[250:253], v[180:183], v[16:31]
	ds_read_b128 v[250:253], v184 offset:12288
	s_waitcnt lgkmcnt(3)
	v_mfma_f32_32x32x16_bf16 v[128:143], v[238:241], v[190:193], v[128:143]
	s_waitcnt lgkmcnt(2)
	v_mfma_f32_32x32x16_bf16 v[48:63], v[242:245], v[190:193], v[48:63]
	s_waitcnt lgkmcnt(1)
	v_mfma_f32_32x32x16_bf16 v[32:47], v[246:249], v[190:193], v[32:47]
	s_waitcnt lgkmcnt(0)
	v_mfma_f32_32x32x16_bf16 v[16:31], v[250:253], v[190:193], v[16:31]
	s_waitcnt vmcnt(6)
	s_barrier
; DI f32x16 mfma(bf16x8 a, bf16x8 b, f32x16 c) { return __builtin_amdgcn_mfma_f32_32x32x16_bf16(a, b, c, 0, 0, 0); }
;     ...
;   for (int kt = 0; kt < nk; ++kt) {
;     const char* cur = lds + (kt & 1) * DBUF;
;     if (kt + 1 < nk) DMA_ISSUE((kt + 1) & 1, kt + 1)
; #pragma unroll(NTB == 1 ? 2 : 4)
;     for (int s = 0; s < 4; ++s) {
;       const int ro = ((2 * s + hh) ^ xr) * 16;
;       bf16x8 bfr[NTB];
; #pragma unroll
;       for (int tb = 0; tb < NTB; ++tb) bfr[tb] = *(const bf16x8*)(cur + bbase + tb * 32 * DROW + ro);
; #pragma unroll
;       for (int fb = 0; fb < NFB; ++fb) {
;         const bf16x8 afr = *(const bf16x8*)(cur + abase + fb * 32 * DROW + ro);
; #pragma unroll
;         for (int tb = 0; tb < NTB; ++tb) acc[tb * NFB + fb] = mfma(afr, bfr[tb], acc[tb * NFB + fb]);
;       }
;     }
;     asm volatile("s_waitcnt vmcnt(0) lgkmcnt(0)" ::: "memory");
;     __builtin_amdgcn_s_barrier();
;   }
	v_add_u32_e32 v195, 0xc000, v186
	ds_read_b128 v[180:183], v195 offset:32768
	v_add_u32_e32 v194, 0xc000, v14
	ds_read_b128 v[238:241], v194
	ds_read_b128 v[242:245], v194 offset:4096
	ds_read_b128 v[246:249], v194 offset:8192
	ds_read_b128 v[250:253], v194 offset:12288
	v_add_u32_e32 v195, 0xc000, v189
	ds_read_b128 v[190:193], v195 offset:32768
	v_add_u32_e32 v194, 0xc000, v15
	s_waitcnt lgkmcnt(4)
	v_mfma_f32_32x32x16_bf16 v[128:143], v[238:241], v[180:183], v[128:143]
	ds_read_b128 v[238:241], v194
	s_add_u32 m0, s33, 0x0
	v_lshl_add_u64 v[2:3], v[2:3], 0, s[84:85]
	global_load_lds_dwordx4 v[2:3], off
	s_waitcnt lgkmcnt(4)
	v_mfma_f32_32x32x16_bf16 v[48:63], v[242:245], v[180:183], v[48:63]
	ds_read_b128 v[242:245], v194 offset:4096
	s_add_u32 m0, s33, 0x2000
	v_lshl_add_u64 v[6:7], v[6:7], 0, s[84:85]
	global_load_lds_dwordx4 v[6:7], off
	s_waitcnt lgkmcnt(4)
	v_mfma_f32_32x32x16_bf16 v[32:47], v[246:249], v[180:183], v[32:47]
	ds_read_b128 v[246:249], v194 offset:8192
	s_waitcnt lgkmcnt(4)
	v_mfma_f32_32x32x16_bf16 v[16:31], v[250:253], v[180:183], v[16:31]
	ds_read_b128 v[250:253], v194 offset:12288
	s_add_u32 m0, s33, 0x4000
	v_lshl_add_u64 v[8:9], v[8:9], 0, s[84:85]
	global_load_lds_dwordx4 v[8:9], off
	v_add_u32_e32 v195, 0xc000, v233
	ds_read_b128 v[180:183], v195 offset:32768
	v_add_u32_e32 v194, 0xc000, v0
	s_waitcnt lgkmcnt(4)
	v_mfma_f32_32x32x16_bf16 v[128:143], v[238:241], v[190:193], v[128:143]
	ds_read_b128 v[238:241], v194
	s_waitcnt lgkmcnt(4)
	v_mfma_f32_32x32x16_bf16 v[48:63], v[242:245], v[190:193], v[48:63]
	ds_read_b128 v[242:245], v194 offset:4096
	s_add_u32 m0, s33, 0x6000
	v_lshl_add_u64 v[10:11], v[10:11], 0, s[84:85]
	global_load_lds_dwordx4 v[10:11], off
	s_waitcnt lgkmcnt(4)
	v_mfma_f32_32x32x16_bf16 v[32:47], v[246:249], v[190:193], v[32:47]
	ds_read_b128 v[246:249], v194 offset:8192
	s_waitcnt lgkmcnt(4)
	v_mfma_f32_32x32x16_bf16 v[16:31], v[250:253], v[190:193], v[16:31]
	ds_read_b128 v[250:253], v194 offset:12288
	s_add_u32 m0, s33, 0x8000
	v_lshl_add_u64 v[4:5], v[4:5], 0, s[84:85]
	global_load_lds_dwordx4 v[4:5], off
	v_add_u32_e32 v195, 0xc000, v234
	ds_read_b128 v[190:193], v195 offset:32768
	v_add_u32_e32 v194, 0xc000, v184
	s_waitcnt lgkmcnt(4)
	v_mfma_f32_32x32x16_bf16 v[128:143], v[238:241], v[180:183], v[128:143]
	ds_read_b128 v[238:241], v194
	s_waitcnt lgkmcnt(4)
	v_mfma_f32_32x32x16_bf16 v[48:63], v[242:245], v[180:183], v[48:63]
	ds_read_b128 v[242:245], v194 offset:4096
	s_add_u32 m0, s33, 0xa000
	v_lshl_add_u64 v[12:13], v[12:13], 0, s[84:85]
	global_load_lds_dwordx4 v[12:13], off
	s_waitcnt lgkmcnt(4)
	v_mfma_f32_32x32x16_bf16 v[32:47], v[246:249], v[180:183], v[32:47]
	ds_read_b128 v[246:249], v194 offset:8192
	s_waitcnt lgkmcnt(4)
	v_mfma_f32_32x32x16_bf16 v[16:31], v[250:253], v[180:183], v[16:31]
	ds_read_b128 v[250:253], v194 offset:12288
	s_waitcnt lgkmcnt(3)
	v_mfma_f32_32x32x16_bf16 v[128:143], v[238:241], v[190:193], v[128:143]
	s_waitcnt lgkmcnt(2)
	v_mfma_f32_32x32x16_bf16 v[48:63], v[242:245], v[190:193], v[48:63]
	s_waitcnt lgkmcnt(1)
	v_mfma_f32_32x32x16_bf16 v[32:47], v[246:249], v[190:193], v[32:47]
	s_waitcnt lgkmcnt(0)
	v_mfma_f32_32x32x16_bf16 v[16:31], v[250:253], v[190:193], v[16:31]
	s_waitcnt vmcnt(6)
	s_barrier
	v_add_u32_e32 v195, 0x18000, v186
	ds_read_b128 v[180:183], v195 offset:32768
	v_add_u32_e32 v194, 0x18000, v14
	ds_read_b128 v[238:241], v194
	ds_read_b128 v[242:245], v194 offset:4096
	ds_read_b128 v[246:249], v194 offset:8192
	ds_read_b128 v[250:253], v194 offset:12288
	v_add_u32_e32 v195, 0x18000, v189
	ds_read_b128 v[190:193], v195 offset:32768
	v_add_u32_e32 v194, 0x18000, v15
	s_waitcnt lgkmcnt(4)
	v_mfma_f32_32x32x16_bf16 v[128:143], v[238:241], v[180:183], v[128:143]
	ds_read_b128 v[238:241], v194
	s_add_u32 m0, s33, 0xc000
	v_lshl_add_u64 v[2:3], v[2:3], 0, s[84:85]
	global_load_lds_dwordx4 v[2:3], off
	s_waitcnt lgkmcnt(4)
	v_mfma_f32_32x32x16_bf16 v[48:63], v[242:245], v[180:183], v[48:63]
	ds_read_b128 v[242:245], v194 offset:4096
	s_add_u32 m0, s33, 0xe000
	v_lshl_add_u64 v[6:7], v[6:7], 0, s[84:85]
	global_load_lds_dwordx4 v[6:7], off
	s_waitcnt lgkmcnt(4)
	v_mfma_f32_32x32x16_bf16 v[32:47], v[246:249], v[180:183], v[32:47]
	ds_read_b128 v[246:249], v194 offset:8192
	s_waitcnt lgkmcnt(4)
	v_mfma_f32_32x32x16_bf16 v[16:31], v[250:253], v[180:183], v[16:31]
	ds_read_b128 v[250:253], v194 offset:12288
	s_add_u32 m0, s33, 0x10000
	v_lshl_add_u64 v[8:9], v[8:9], 0, s[84:85]
	global_load_lds_dwordx4 v[8:9], off
	v_add_u32_e32 v195, 0x18000, v233
	ds_read_b128 v[180:183], v195 offset:32768
	v_add_u32_e32 v194, 0x18000, v0
	s_waitcnt lgkmcnt(4)
	v_mfma_f32_32x32x16_bf16 v[128:143], v[238:241], v[190:193], v[128:143]
	ds_read_b128 v[238:241], v194
	s_waitcnt lgkmcnt(4)
	v_mfma_f32_32x32x16_bf16 v[48:63], v[242:245], v[190:193], v[48:63]
	ds_read_b128 v[242:245], v194 offset:4096
	s_add_u32 m0, s33, 0x12000
	v_lshl_add_u64 v[10:11], v[10:11], 0, s[84:85]
	global_load_lds_dwordx4 v[10:11], off
	s_waitcnt lgkmcnt(4)
	v_mfma_f32_32x32x16_bf16 v[32:47], v[246:249], v[190:193], v[32:47]
	ds_read_b128 v[246:249], v194 offset:8192
	s_waitcnt lgkmcnt(4)
	v_mfma_f32_32x32x16_bf16 v[16:31], v[250:253], v[190:193], v[16:31]
	ds_read_b128 v[250:253], v194 offset:12288
	s_add_u32 m0, s33, 0x14000
	v_lshl_add_u64 v[4:5], v[4:5], 0, s[84:85]
	global_load_lds_dwordx4 v[4:5], off
	v_add_u32_e32 v195, 0x18000, v234
	ds_read_b128 v[190:193], v195 offset:32768
	v_add_u32_e32 v194, 0x18000, v184
	s_waitcnt lgkmcnt(4)
	v_mfma_f32_32x32x16_bf16 v[128:143], v[238:241], v[180:183], v[128:143]
	ds_read_b128 v[238:241], v194
	s_waitcnt lgkmcnt(4)
	v_mfma_f32_32x32x16_bf16 v[48:63], v[242:245], v[180:183], v[48:63]
	ds_read_b128 v[242:245], v194 offset:4096
	s_add_u32 m0, s33, 0x16000
	v_lshl_add_u64 v[12:13], v[12:13], 0, s[84:85]
	global_load_lds_dwordx4 v[12:13], off
	s_waitcnt lgkmcnt(4)
	v_mfma_f32_32x32x16_bf16 v[32:47], v[246:249], v[180:183], v[32:47]
	ds_read_b128 v[246:249], v194 offset:8192
	s_waitcnt lgkmcnt(4)
	v_mfma_f32_32x32x16_bf16 v[16:31], v[250:253], v[180:183], v[16:31]
	ds_read_b128 v[250:253], v194 offset:12288
	s_waitcnt lgkmcnt(3)
	v_mfma_f32_32x32x16_bf16 v[128:143], v[238:241], v[190:193], v[128:143]
	s_waitcnt lgkmcnt(2)
	v_mfma_f32_32x32x16_bf16 v[48:63], v[242:245], v[190:193], v[48:63]
	s_waitcnt lgkmcnt(1)
	v_mfma_f32_32x32x16_bf16 v[32:47], v[246:249], v[190:193], v[32:47]
	s_waitcnt lgkmcnt(0)
	v_mfma_f32_32x32x16_bf16 v[16:31], v[250:253], v[190:193], v[16:31]
	s_waitcnt vmcnt(6)
	s_barrier
; DI f32x16 mfma(bf16x8 a, bf16x8 b, f32x16 c) { return __builtin_amdgcn_mfma_f32_32x32x16_bf16(a, b, c, 0, 0, 0); }
;     ...
;   __syncthreads();
;   DMA_ISSUE(0, 0)
;   asm volatile("s_waitcnt vmcnt(0)" ::: "memory");
;   __builtin_amdgcn_s_barrier();
;   for (int kt = 0; kt < nk; ++kt) {
;     const char* cur = lds + (kt & 1) * DBUF;
;     if (kt + 1 < nk) DMA_ISSUE((kt + 1) & 1, kt + 1)
; #pragma unroll(NTB == 1 ? 2 : 4)
;     for (int s = 0; s < 4; ++s) {
;       const int ro = ((2 * s + hh) ^ xr) * 16;
;       bf16x8 bfr[NTB];
; #pragma unroll
;       for (int tb = 0; tb < NTB; ++tb) bfr[tb] = *(const bf16x8*)(cur + bbase + tb * 32 * DROW + ro);
; #pragma unroll
;       for (int fb = 0; fb < NFB; ++fb) {
;         const bf16x8 afr = *(const bf16x8*)(cur + abase + fb * 32 * DROW + ro);
; #pragma unroll
;         for (int tb = 0; tb < NTB; ++tb) acc[tb * NFB + fb] = mfma(afr, bfr[tb], acc[tb * NFB + fb]);
;       }
;     }
;     asm volatile("s_waitcnt vmcnt(0) lgkmcnt(0)" ::: "memory");
;     __builtin_amdgcn_s_barrier();
;   }
	ds_read_b128 v[180:183], v186 offset:32768
	ds_read_b128 v[238:241], v14
	ds_read_b128 v[242:245], v14 offset:4096
	ds_read_b128 v[246:249], v14 offset:8192
	ds_read_b128 v[250:253], v14 offset:12288
	ds_read_b128 v[190:193], v189 offset:32768
	s_waitcnt lgkmcnt(4)
	v_mfma_f32_32x32x16_bf16 v[128:143], v[238:241], v[180:183], v[128:143]
	ds_read_b128 v[238:241], v15
	s_add_u32 m0, s33, 0x18000
	v_lshl_add_u64 v[2:3], v[2:3], 0, s[84:85]
	global_load_lds_dwordx4 v[2:3], off
	s_waitcnt lgkmcnt(4)
	v_mfma_f32_32x32x16_bf16 v[48:63], v[242:245], v[180:183], v[48:63]
	ds_read_b128 v[242:245], v15 offset:4096
	s_add_u32 m0, s33, 0x1a000
	v_lshl_add_u64 v[6:7], v[6:7], 0, s[84:85]
	global_load_lds_dwordx4 v[6:7], off
	s_waitcnt lgkmcnt(4)
	v_mfma_f32_32x32x16_bf16 v[32:47], v[246:249], v[180:183], v[32:47]
	ds_read_b128 v[246:249], v15 offset:8192
	s_waitcnt lgkmcnt(4)
	v_mfma_f32_32x32x16_bf16 v[16:31], v[250:253], v[180:183], v[16:31]
	ds_read_b128 v[250:253], v15 offset:12288
	s_add_u32 m0, s33, 0x1c000
	v_lshl_add_u64 v[8:9], v[8:9], 0, s[84:85]
	global_load_lds_dwordx4 v[8:9], off
	ds_read_b128 v[180:183], v233 offset:32768
	s_waitcnt lgkmcnt(4)
	v_mfma_f32_32x32x16_bf16 v[128:143], v[238:241], v[190:193], v[128:143]
	ds_read_b128 v[238:241], v0
	s_waitcnt lgkmcnt(4)
	v_mfma_f32_32x32x16_bf16 v[48:63], v[242:245], v[190:193], v[48:63]
	ds_read_b128 v[242:245], v0 offset:4096
	s_add_u32 m0, s33, 0x1e000
	v_lshl_add_u64 v[10:11], v[10:11], 0, s[84:85]
	global_load_lds_dwordx4 v[10:11], off
	s_waitcnt lgkmcnt(4)
	v_mfma_f32_32x32x16_bf16 v[32:47], v[246:249], v[190:193], v[32:47]
	ds_read_b128 v[246:249], v0 offset:8192
	s_waitcnt lgkmcnt(4)
	v_mfma_f32_32x32x16_bf16 v[16:31], v[250:253], v[190:193], v[16:31]
	ds_read_b128 v[250:253], v0 offset:12288
	s_add_u32 m0, s33, 0x20000
	v_lshl_add_u64 v[4:5], v[4:5], 0, s[84:85]
	global_load_lds_dwordx4 v[4:5], off
	ds_read_b128 v[190:193], v234 offset:32768
	s_waitcnt lgkmcnt(4)
	v_mfma_f32_32x32x16_bf16 v[128:143], v[238:241], v[180:183], v[128:143]
	ds_read_b128 v[238:241], v184
	s_waitcnt lgkmcnt(4)
	v_mfma_f32_32x32x16_bf16 v[48:63], v[242:245], v[180:183], v[48:63]
	ds_read_b128 v[242:245], v184 offset:4096
	s_add_u32 m0, s33, 0x22000
	v_lshl_add_u64 v[12:13], v[12:13], 0, s[84:85]
	global_load_lds_dwordx4 v[12:13], off
	s_waitcnt lgkmcnt(4)
	v_mfma_f32_32x32x16_bf16 v[32:47], v[246:249], v[180:183], v[32:47]
	ds_read_b128 v[246:249], v184 offset:8192
	s_waitcnt lgkmcnt(4)
	v_mfma_f32_32x32x16_bf16 v[16:31], v[250:253], v[180:183], v[16:31]
	ds_read_b128 v[250:253], v184 offset:12288
	s_waitcnt lgkmcnt(3)
	v_mfma_f32_32x32x16_bf16 v[128:143], v[238:241], v[190:193], v[128:143]
	s_waitcnt lgkmcnt(2)
	v_mfma_f32_32x32x16_bf16 v[48:63], v[242:245], v[190:193], v[48:63]
	s_waitcnt lgkmcnt(1)
	v_mfma_f32_32x32x16_bf16 v[32:47], v[246:249], v[190:193], v[32:47]
	s_waitcnt lgkmcnt(0)
	v_mfma_f32_32x32x16_bf16 v[16:31], v[250:253], v[190:193], v[16:31]
	s_waitcnt vmcnt(6)
	s_barrier
	v_add_u32_e32 v195, 0xc000, v186
	ds_read_b128 v[180:183], v195 offset:32768
	v_add_u32_e32 v194, 0xc000, v14
	ds_read_b128 v[238:241], v194
	ds_read_b128 v[242:245], v194 offset:4096
	ds_read_b128 v[246:249], v194 offset:8192
	ds_read_b128 v[250:253], v194 offset:12288
	v_add_u32_e32 v195, 0xc000, v189
	ds_read_b128 v[190:193], v195 offset:32768
	v_add_u32_e32 v194, 0xc000, v15
	s_waitcnt lgkmcnt(4)
	v_mfma_f32_32x32x16_bf16 v[128:143], v[238:241], v[180:183], v[128:143]
	ds_read_b128 v[238:241], v194
	s_waitcnt lgkmcnt(4)
	v_mfma_f32_32x32x16_bf16 v[48:63], v[242:245], v[180:183], v[48:63]
	ds_read_b128 v[242:245], v194 offset:4096
	s_waitcnt lgkmcnt(4)
	v_mfma_f32_32x32x16_bf16 v[32:47], v[246:249], v[180:183], v[32:47]
	ds_read_b128 v[246:249], v194 offset:8192
	s_waitcnt lgkmcnt(4)
	v_mfma_f32_32x32x16_bf16 v[16:31], v[250:253], v[180:183], v[16:31]
	ds_read_b128 v[250:253], v194 offset:12288
	v_add_u32_e32 v195, 0xc000, v233
	ds_read_b128 v[180:183], v195 offset:32768
	v_add_u32_e32 v194, 0xc000, v0
	s_waitcnt lgkmcnt(4)
	v_mfma_f32_32x32x16_bf16 v[128:143], v[238:241], v[190:193], v[128:143]
	ds_read_b128 v[238:241], v194
	s_waitcnt lgkmcnt(4)
	v_mfma_f32_32x32x16_bf16 v[48:63], v[242:245], v[190:193], v[48:63]
	ds_read_b128 v[242:245], v194 offset:4096
	s_waitcnt lgkmcnt(4)
	v_mfma_f32_32x32x16_bf16 v[32:47], v[246:249], v[190:193], v[32:47]
	ds_read_b128 v[246:249], v194 offset:8192
	s_waitcnt lgkmcnt(4)
	v_mfma_f32_32x32x16_bf16 v[16:31], v[250:253], v[190:193], v[16:31]
	ds_read_b128 v[250:253], v194 offset:12288
	v_add_u32_e32 v195, 0xc000, v234
	ds_read_b128 v[190:193], v195 offset:32768
	v_add_u32_e32 v194, 0xc000, v184
	s_waitcnt lgkmcnt(4)
	v_mfma_f32_32x32x16_bf16 v[128:143], v[238:241], v[180:183], v[128:143]
	ds_read_b128 v[238:241], v194
	s_waitcnt lgkmcnt(4)
	v_mfma_f32_32x32x16_bf16 v[48:63], v[242:245], v[180:183], v[48:63]
	ds_read_b128 v[242:245], v194 offset:4096
	s_waitcnt lgkmcnt(4)
	v_mfma_f32_32x32x16_bf16 v[32:47], v[246:249], v[180:183], v[32:47]
	ds_read_b128 v[246:249], v194 offset:8192
	s_waitcnt lgkmcnt(4)
	v_mfma_f32_32x32x16_bf16 v[16:31], v[250:253], v[180:183], v[16:31]
	ds_read_b128 v[250:253], v194 offset:12288
	s_waitcnt lgkmcnt(3)
	v_mfma_f32_32x32x16_bf16 v[128:143], v[238:241], v[190:193], v[128:143]
	s_waitcnt lgkmcnt(2)
	v_mfma_f32_32x32x16_bf16 v[48:63], v[242:245], v[190:193], v[48:63]
	s_waitcnt lgkmcnt(1)
	v_mfma_f32_32x32x16_bf16 v[32:47], v[246:249], v[190:193], v[32:47]
	s_waitcnt lgkmcnt(0)
	v_mfma_f32_32x32x16_bf16 v[16:31], v[250:253], v[190:193], v[16:31]
	s_waitcnt vmcnt(0)
	s_barrier
; DI unsigned pack2(float a, float b) { f2_t v = {a, b}; bf2_t r = __builtin_convertvector(v, bf2_t); return __builtin_bit_cast(unsigned, r); }
; DI f32x16 mfma(bf16x8 a, bf16x8 b, f32x16 c) { return __builtin_amdgcn_mfma_f32_32x32x16_bf16(a, b, c, 0, 0, 0); }
;     ...
;     for (int s = 0; s < 4; ++s) {
;       const int ro = ((2 * s + hh) ^ xr) * 16;
;       bf16x8 bfr[NTB];
; #pragma unroll
;       for (int tb = 0; tb < NTB; ++tb) bfr[tb] = *(const bf16x8*)(cur + bbase + tb * 32 * DROW + ro);
; #pragma unroll
;       for (int fb = 0; fb < NFB; ++fb) {
;         const bf16x8 afr = *(const bf16x8*)(cur + abase + fb * 32 * DROW + ro);
; #pragma unroll
;         for (int tb = 0; tb < NTB; ++tb) acc[tb * NFB + fb] = mfma(afr, bfr[tb], acc[tb * NFB + fb]);
;       }
;     }
;     asm volatile("s_waitcnt vmcnt(0) lgkmcnt(0)" ::: "memory");
;     __builtin_amdgcn_s_barrier();
; __global__ void __launch_bounds__(512) mega(Params p) {
;     ...
; #pragma unroll
;           for (int fb = 0; fb < 4; ++fb)
; #pragma unroll
;             for (int i = 0; i < 8; ++i) {
;               const float b0 = __uint_as_float(bp[fb][i] << 16), b1 = __uint_as_float(bp[fb][i] & 0xffff0000u);
;               const float g0 = 1.f / (1.f + __builtin_amdgcn_exp2f(nr1 * acc[fb][2 * i]));
;               const float g1 = 1.f / (1.f + __builtin_amdgcn_exp2f(nr1 * acc[fb][2 * i + 1]));
;               float y0 = g0 * b0, y1 = g1 * b1;
;               if (n > 0) { y0 += __uint_as_float(yp[fb][i] << 16); y1 += __uint_as_float(yp[fb][i] & 0xffff0000u); }
;               yp[fb][i] = pack2(y0, y1);
;             }
	v_add_u32_e32 v195, 0x18000, v186
	ds_read_b128 v[180:183], v195 offset:32768
	v_add_u32_e32 v194, 0x18000, v14
	ds_read_b128 v[238:241], v194
	ds_read_b128 v[242:245], v194 offset:4096
	ds_read_b128 v[246:249], v194 offset:8192
	ds_read_b128 v[250:253], v194 offset:12288
	v_add_u32_e32 v195, 0x18000, v189
	ds_read_b128 v[190:193], v195 offset:32768
	v_add_u32_e32 v194, 0x18000, v15
	s_waitcnt lgkmcnt(4)
	v_mfma_f32_32x32x16_bf16 v[128:143], v[238:241], v[180:183], v[128:143]
	ds_read_b128 v[238:241], v194
	s_waitcnt lgkmcnt(4)
	v_mfma_f32_32x32x16_bf16 v[48:63], v[242:245], v[180:183], v[48:63]
	ds_read_b128 v[242:245], v194 offset:4096
	s_waitcnt lgkmcnt(4)
	v_mfma_f32_32x32x16_bf16 v[32:47], v[246:249], v[180:183], v[32:47]
	ds_read_b128 v[246:249], v194 offset:8192
	s_waitcnt lgkmcnt(4)
	v_mfma_f32_32x32x16_bf16 v[16:31], v[250:253], v[180:183], v[16:31]
	ds_read_b128 v[250:253], v194 offset:12288
	v_add_u32_e32 v195, 0x18000, v233
	ds_read_b128 v[180:183], v195 offset:32768
	v_add_u32_e32 v194, 0x18000, v0
	s_waitcnt lgkmcnt(4)
	v_mfma_f32_32x32x16_bf16 v[128:143], v[238:241], v[190:193], v[128:143]
	ds_read_b128 v[238:241], v194
	s_waitcnt lgkmcnt(4)
	v_mfma_f32_32x32x16_bf16 v[48:63], v[242:245], v[190:193], v[48:63]
	ds_read_b128 v[242:245], v194 offset:4096
	s_waitcnt lgkmcnt(4)
	v_mfma_f32_32x32x16_bf16 v[32:47], v[246:249], v[190:193], v[32:47]
	ds_read_b128 v[246:249], v194 offset:8192
	s_waitcnt lgkmcnt(4)
	v_mfma_f32_32x32x16_bf16 v[16:31], v[250:253], v[190:193], v[16:31]
	ds_read_b128 v[250:253], v194 offset:12288
	v_add_u32_e32 v195, 0x18000, v234
	ds_read_b128 v[190:193], v195 offset:32768
	v_add_u32_e32 v194, 0x18000, v184
	s_waitcnt lgkmcnt(4)
	v_mfma_f32_32x32x16_bf16 v[128:143], v[238:241], v[180:183], v[128:143]
	ds_read_b128 v[238:241], v194
	s_waitcnt lgkmcnt(4)
	v_mfma_f32_32x32x16_bf16 v[48:63], v[242:245], v[180:183], v[48:63]
	ds_read_b128 v[242:245], v194 offset:4096
	s_waitcnt lgkmcnt(4)
	v_mfma_f32_32x32x16_bf16 v[32:47], v[246:249], v[180:183], v[32:47]
	ds_read_b128 v[246:249], v194 offset:8192
	s_waitcnt lgkmcnt(4)
	v_mfma_f32_32x32x16_bf16 v[16:31], v[250:253], v[180:183], v[16:31]
	ds_read_b128 v[250:253], v194 offset:12288
	s_waitcnt lgkmcnt(3)
	v_mfma_f32_32x32x16_bf16 v[128:143], v[238:241], v[190:193], v[128:143]
	s_waitcnt lgkmcnt(2)
	v_mfma_f32_32x32x16_bf16 v[48:63], v[242:245], v[190:193], v[48:63]
	s_waitcnt lgkmcnt(1)
	v_mfma_f32_32x32x16_bf16 v[32:47], v[246:249], v[190:193], v[32:47]
	s_waitcnt lgkmcnt(0)
	v_mfma_f32_32x32x16_bf16 v[16:31], v[250:253], v[190:193], v[16:31]
	s_nop 7
	s_nop 7
	s_waitcnt vmcnt(0) lgkmcnt(0)
	s_barrier
	v_cvt_pk_bf16_f32 v7, v66, v67
	v_mul_f32_e32 v66, v236, v128
	v_mul_f32_e32 v67, v236, v129
	v_exp_f32_e32 v66, v66
	v_exp_f32_e32 v67, v67
	v_cvt_pk_bf16_f32 v6, v68, v69
	v_cvt_pk_bf16_f32 v5, v70, v71
	v_cvt_pk_bf16_f32 v4, v72, v73
	v_pk_add_f32 v[66:67], v[66:67], 1.0 op_sel_hi:[1,0]
	v_cvt_pk_bf16_f32 v180, v112, v113
	v_cvt_pk_bf16_f32 v8, v64, v65
	v_lshlrev_b32_e32 v64, 16, v180
	v_and_b32_e32 v65, 0xffff0000, v180
	v_rcp_f32_e32 v67, v67
	v_cvt_pk_bf16_f32 v181, v114, v115
	v_cvt_pk_bf16_f32 v182, v116, v117
	v_cvt_pk_bf16_f32 v118, v118, v119
	v_rcp_f32_e32 v66, v66
	v_lshlrev_b32_e32 v70, 16, v166
	v_and_b32_e32 v71, 0xffff0000, v166
	v_pk_mul_f32 v[68:69], v[66:67], v[64:65]
	v_pk_fma_f32 v[64:65], v[66:67], v[64:65], v[70:71]
	v_mul_f32_e32 v66, v236, v130
	v_mul_f32_e32 v67, v236, v131
	v_exp_f32_e32 v66, v66
	v_exp_f32_e32 v67, v67
	v_cndmask_b32_e64 v64, v64, v68, s[0:1]
	v_cndmask_b32_e64 v65, v65, v69, s[0:1]
	v_cvt_pk_bf16_f32 v166, v64, v65
	v_pk_add_f32 v[66:67], v[66:67], 1.0 op_sel_hi:[1,0]
	v_lshlrev_b32_e32 v64, 16, v181
	v_and_b32_e32 v65, 0xffff0000, v181
	v_cvt_pk_bf16_f32 v117, v120, v121
	v_cvt_pk_bf16_f32 v116, v122, v123
	v_rcp_f32_e32 v67, v67
	v_cvt_pk_bf16_f32 v115, v124, v125
	v_mul_f32_e32 v48, v236, v48
	v_mul_f32_e32 v49, v236, v49
	v_rcp_f32_e32 v66, v66
	v_lshlrev_b32_e32 v70, 16, v167
	v_and_b32_e32 v71, 0xffff0000, v167
	v_pk_mul_f32 v[68:69], v[66:67], v[64:65]
	v_pk_fma_f32 v[64:65], v[66:67], v[64:65], v[70:71]
	v_mul_f32_e32 v66, v236, v132
	v_mul_f32_e32 v67, v236, v133
	v_exp_f32_e32 v66, v66
	v_exp_f32_e32 v67, v67
	v_cndmask_b32_e64 v64, v64, v68, s[0:1]
	v_cndmask_b32_e64 v65, v65, v69, s[0:1]
	v_cvt_pk_bf16_f32 v167, v64, v65
	v_pk_add_f32 v[66:67], v[66:67], 1.0 op_sel_hi:[1,0]
	v_lshlrev_b32_e32 v64, 16, v182
	v_and_b32_e32 v65, 0xffff0000, v182
	v_exp_f32_e32 v48, v48
	v_exp_f32_e32 v49, v49
	v_rcp_f32_e32 v67, v67
	v_cvt_pk_bf16_f32 v114, v126, v127
	v_pk_add_f32 v[48:49], v[48:49], 1.0 op_sel_hi:[1,0]
	v_mul_f32_e32 v50, v236, v50
	v_rcp_f32_e32 v66, v66
	v_lshlrev_b32_e32 v70, 16, v168
	v_and_b32_e32 v71, 0xffff0000, v168
	v_pk_mul_f32 v[68:69], v[66:67], v[64:65]
	v_pk_fma_f32 v[64:65], v[66:67], v[64:65], v[70:71]
	v_mul_f32_e32 v66, v236, v134
	v_mul_f32_e32 v67, v236, v135
	v_exp_f32_e32 v66, v66
	v_exp_f32_e32 v67, v67
	v_cndmask_b32_e64 v64, v64, v68, s[0:1]
	v_cndmask_b32_e64 v65, v65, v69, s[0:1]
	v_cvt_pk_bf16_f32 v168, v64, v65
	v_pk_add_f32 v[66:67], v[66:67], 1.0 op_sel_hi:[1,0]
	v_lshlrev_b32_e32 v64, 16, v118
	v_and_b32_e32 v65, 0xffff0000, v118
	v_mul_f32_e32 v51, v236, v51
	v_exp_f32_e32 v50, v50
	v_rcp_f32_e32 v67, v67
	v_exp_f32_e32 v51, v51
	v_cvt_pk_bf16_f32 v113, v96, v97
	v_cvt_pk_bf16_f32 v112, v98, v99
	v_rcp_f32_e32 v66, v66
	v_lshlrev_b32_e32 v70, 16, v169
	v_and_b32_e32 v71, 0xffff0000, v169
	v_pk_mul_f32 v[68:69], v[66:67], v[64:65]
	v_pk_fma_f32 v[64:65], v[66:67], v[64:65], v[70:71]
	v_mul_f32_e32 v66, v236, v136
	v_mul_f32_e32 v67, v236, v137
	v_exp_f32_e32 v66, v66
; DI unsigned pack2(float a, float b) { f2_t v = {a, b}; bf2_t r = __builtin_convertvector(v, bf2_t); return __builtin_bit_cast(unsigned, r); }
; __global__ void __launch_bounds__(512) mega(Params p) {
;     ...
; #pragma unroll
;           for (int fb = 0; fb < 4; ++fb)
; #pragma unroll
;             for (int i = 0; i < 8; ++i) {
;               const float b0 = __uint_as_float(bp[fb][i] << 16), b1 = __uint_as_float(bp[fb][i] & 0xffff0000u);
;               const float g0 = 1.f / (1.f + __builtin_amdgcn_exp2f(nr1 * acc[fb][2 * i]));
;               const float g1 = 1.f / (1.f + __builtin_amdgcn_exp2f(nr1 * acc[fb][2 * i + 1]));
;               float y0 = g0 * b0, y1 = g1 * b1;
;               if (n > 0) { y0 += __uint_as_float(yp[fb][i] << 16); y1 += __uint_as_float(yp[fb][i] & 0xffff0000u); }
;               yp[fb][i] = pack2(y0, y1);
;             }
	v_exp_f32_e32 v67, v67
	v_cndmask_b32_e64 v64, v64, v68, s[0:1]
	v_cndmask_b32_e64 v65, v65, v69, s[0:1]
	v_cvt_pk_bf16_f32 v169, v64, v65
	v_pk_add_f32 v[66:67], v[66:67], 1.0 op_sel_hi:[1,0]
	v_lshlrev_b32_e32 v64, 16, v117
	v_and_b32_e32 v65, 0xffff0000, v117
	v_pk_add_f32 v[50:51], v[50:51], 1.0 op_sel_hi:[1,0]
	v_cvt_pk_bf16_f32 v101, v100, v101
	v_rcp_f32_e32 v67, v67
	v_cvt_pk_bf16_f32 v100, v102, v103
	v_cvt_pk_bf16_f32 v99, v104, v105
	v_cvt_pk_bf16_f32 v98, v106, v107
	v_rcp_f32_e32 v66, v66
	v_lshlrev_b32_e32 v70, 16, v170
	v_and_b32_e32 v71, 0xffff0000, v170
	v_pk_mul_f32 v[68:69], v[66:67], v[64:65]
	v_pk_fma_f32 v[64:65], v[66:67], v[64:65], v[70:71]
	v_mul_f32_e32 v66, v236, v138
	v_mul_f32_e32 v67, v236, v139
	v_exp_f32_e32 v66, v66
	v_exp_f32_e32 v67, v67
	v_cndmask_b32_e64 v64, v64, v68, s[0:1]
	v_cndmask_b32_e64 v65, v65, v69, s[0:1]
	v_cvt_pk_bf16_f32 v170, v64, v65
	v_pk_add_f32 v[66:67], v[66:67], 1.0 op_sel_hi:[1,0]
	v_lshlrev_b32_e32 v64, 16, v116
	v_and_b32_e32 v65, 0xffff0000, v116
	v_cvt_pk_bf16_f32 v97, v108, v109
	v_mul_f32_e32 v32, v236, v32
	v_rcp_f32_e32 v67, v67
	v_mul_f32_e32 v33, v236, v33
	v_exp_f32_e32 v32, v32
	v_exp_f32_e32 v33, v33
	v_rcp_f32_e32 v66, v66
	v_lshlrev_b32_e32 v70, 16, v171
	v_and_b32_e32 v71, 0xffff0000, v171
	v_pk_mul_f32 v[68:69], v[66:67], v[64:65]
	v_pk_fma_f32 v[64:65], v[66:67], v[64:65], v[70:71]
	v_mul_f32_e32 v66, v236, v140
	v_mul_f32_e32 v67, v236, v141
	v_exp_f32_e32 v66, v66
	v_exp_f32_e32 v67, v67
	v_cndmask_b32_e64 v64, v64, v68, s[0:1]
	v_cndmask_b32_e64 v65, v65, v69, s[0:1]
	v_cvt_pk_bf16_f32 v171, v64, v65
	v_pk_add_f32 v[66:67], v[66:67], 1.0 op_sel_hi:[1,0]
	v_lshlrev_b32_e32 v64, 16, v115
	v_and_b32_e32 v65, 0xffff0000, v115
	v_cvt_pk_bf16_f32 v96, v110, v111
	v_pk_add_f32 v[32:33], v[32:33], 1.0 op_sel_hi:[1,0]
	v_rcp_f32_e32 v67, v67
	v_cvt_pk_bf16_f32 v80, v80, v81
	v_cvt_pk_bf16_f32 v15, v82, v83
	v_cvt_pk_bf16_f32 v14, v84, v85
	v_rcp_f32_e32 v66, v66
	v_lshlrev_b32_e32 v70, 16, v172
	v_and_b32_e32 v71, 0xffff0000, v172
	v_pk_mul_f32 v[68:69], v[66:67], v[64:65]
	v_pk_fma_f32 v[64:65], v[66:67], v[64:65], v[70:71]
	v_mul_f32_e32 v66, v236, v142
	v_mul_f32_e32 v67, v236, v143
	v_exp_f32_e32 v66, v66
	v_exp_f32_e32 v67, v67
	v_cndmask_b32_e64 v64, v64, v68, s[0:1]
	v_cndmask_b32_e64 v65, v65, v69, s[0:1]
	v_cvt_pk_bf16_f32 v172, v64, v65
	v_pk_add_f32 v[66:67], v[66:67], 1.0 op_sel_hi:[1,0]
	v_lshlrev_b32_e32 v64, 16, v114
	v_and_b32_e32 v65, 0xffff0000, v114
	v_cvt_pk_bf16_f32 v13, v86, v87
	v_cvt_pk_bf16_f32 v12, v88, v89
	v_rcp_f32_e32 v67, v67
	v_cvt_pk_bf16_f32 v11, v90, v91
	v_cvt_pk_bf16_f32 v10, v92, v93
	v_cvt_pk_bf16_f32 v9, v94, v95
	v_rcp_f32_e32 v66, v66
	v_lshlrev_b32_e32 v70, 16, v173
	v_and_b32_e32 v71, 0xffff0000, v173
	v_pk_mul_f32 v[68:69], v[66:67], v[64:65]
	v_pk_fma_f32 v[64:65], v[66:67], v[64:65], v[70:71]
	v_cndmask_b32_e64 v64, v64, v68, s[0:1]
	v_cndmask_b32_e64 v65, v65, v69, s[0:1]
	v_cvt_pk_bf16_f32 v173, v64, v65
	v_rcp_f32_e32 v49, v49
	v_lshlrev_b32_e32 v64, 16, v113
	v_and_b32_e32 v65, 0xffff0000, v113
	v_cvt_pk_bf16_f32 v3, v74, v75
	v_rcp_f32_e32 v48, v48
	v_lshlrev_b32_e32 v68, 16, v174
	v_and_b32_e32 v69, 0xffff0000, v174
	v_pk_mul_f32 v[66:67], v[48:49], v[64:65]
	v_pk_fma_f32 v[48:49], v[48:49], v[64:65], v[68:69]
	v_cndmask_b32_e64 v48, v48, v66, s[0:1]
	v_cndmask_b32_e64 v49, v49, v67, s[0:1]
	v_cvt_pk_bf16_f32 v174, v48, v49
	v_rcp_f32_e32 v51, v51
	v_lshlrev_b32_e32 v48, 16, v112
	v_and_b32_e32 v49, 0xffff0000, v112
	v_cvt_pk_bf16_f32 v2, v76, v77
	v_rcp_f32_e32 v50, v50
	v_lshlrev_b32_e32 v66, 16, v175
	v_and_b32_e32 v67, 0xffff0000, v175
	v_pk_mul_f32 v[64:65], v[50:51], v[48:49]
	v_pk_fma_f32 v[48:49], v[50:51], v[48:49], v[66:67]
	v_mul_f32_e32 v50, v236, v52
	v_mul_f32_e32 v51, v236, v53
	v_exp_f32_e32 v50, v50
	v_exp_f32_e32 v51, v51
	v_cndmask_b32_e64 v48, v48, v64, s[0:1]
	v_cndmask_b32_e64 v49, v49, v65, s[0:1]
	v_cvt_pk_bf16_f32 v175, v48, v49
	v_pk_add_f32 v[50:51], v[50:51], 1.0 op_sel_hi:[1,0]
	v_lshlrev_b32_e32 v48, 16, v101
	v_and_b32_e32 v49, 0xffff0000, v101
	v_cvt_pk_bf16_f32 v0, v78, v79
	s_add_i32 s8, s8, 1
	v_rcp_f32_e32 v51, v51
	s_cmp_eq_u32 s8, 3
	v_rcp_f32_e32 v50, v50
	v_lshlrev_b32_e32 v64, 16, v176
	v_and_b32_e32 v65, 0xffff0000, v176
	v_pk_mul_f32 v[52:53], v[50:51], v[48:49]
	v_pk_fma_f32 v[48:49], v[50:51], v[48:49], v[64:65]
	v_mul_f32_e32 v50, v236, v54
	v_mul_f32_e32 v51, v236, v55
	v_exp_f32_e32 v50, v50
	v_exp_f32_e32 v51, v51
	v_cndmask_b32_e64 v48, v48, v52, s[0:1]
	v_cndmask_b32_e64 v49, v49, v53, s[0:1]
	v_cvt_pk_bf16_f32 v176, v48, v49
	v_pk_add_f32 v[50:51], v[50:51], 1.0 op_sel_hi:[1,0]
	v_lshlrev_b32_e32 v48, 16, v100
	v_and_b32_e32 v49, 0xffff0000, v100
	v_rcp_f32_e32 v51, v51
	s_nop 0
	v_rcp_f32_e32 v50, v50
	v_lshlrev_b32_e32 v54, 16, v177
	v_and_b32_e32 v55, 0xffff0000, v177
	v_pk_mul_f32 v[52:53], v[50:51], v[48:49]
	v_pk_fma_f32 v[48:49], v[50:51], v[48:49], v[54:55]
	v_mul_f32_e32 v50, v236, v56
	v_mul_f32_e32 v51, v236, v57
	v_exp_f32_e32 v50, v50
	v_exp_f32_e32 v51, v51
	v_cndmask_b32_e64 v48, v48, v52, s[0:1]
	v_cndmask_b32_e64 v49, v49, v53, s[0:1]
	v_cvt_pk_bf16_f32 v177, v48, v49
	v_pk_add_f32 v[50:51], v[50:51], 1.0 op_sel_hi:[1,0]
	v_lshlrev_b32_e32 v48, 16, v99
	v_and_b32_e32 v49, 0xffff0000, v99
	v_rcp_f32_e32 v51, v51
	s_nop 0
	v_rcp_f32_e32 v50, v50
	v_lshlrev_b32_e32 v54, 16, v178
	v_and_b32_e32 v55, 0xffff0000, v178
	v_pk_mul_f32 v[52:53], v[50:51], v[48:49]
	v_pk_fma_f32 v[48:49], v[50:51], v[48:49], v[54:55]
	v_mul_f32_e32 v50, v236, v58
	v_mul_f32_e32 v51, v236, v59
	v_exp_f32_e32 v50, v50
	v_exp_f32_e32 v51, v51
	v_cndmask_b32_e64 v48, v48, v52, s[0:1]
; DI unsigned pack2(float a, float b) { f2_t v = {a, b}; bf2_t r = __builtin_convertvector(v, bf2_t); return __builtin_bit_cast(unsigned, r); }
; __global__ void __launch_bounds__(512) mega(Params p) {
;     ...
; #pragma unroll
;           for (int fb = 0; fb < 4; ++fb)
; #pragma unroll
;             for (int i = 0; i < 8; ++i) {
;               const float b0 = __uint_as_float(bp[fb][i] << 16), b1 = __uint_as_float(bp[fb][i] & 0xffff0000u);
;               const float g0 = 1.f / (1.f + __builtin_amdgcn_exp2f(nr1 * acc[fb][2 * i]));
;               const float g1 = 1.f / (1.f + __builtin_amdgcn_exp2f(nr1 * acc[fb][2 * i + 1]));
;               float y0 = g0 * b0, y1 = g1 * b1;
;               if (n > 0) { y0 += __uint_as_float(yp[fb][i] << 16); y1 += __uint_as_float(yp[fb][i] & 0xffff0000u); }
;               yp[fb][i] = pack2(y0, y1);
;             }
	v_cndmask_b32_e64 v49, v49, v53, s[0:1]
	v_cvt_pk_bf16_f32 v178, v48, v49
	v_pk_add_f32 v[50:51], v[50:51], 1.0 op_sel_hi:[1,0]
	v_lshlrev_b32_e32 v48, 16, v98
	v_and_b32_e32 v49, 0xffff0000, v98
	v_rcp_f32_e32 v51, v51
	s_nop 0
	v_rcp_f32_e32 v50, v50
	v_lshlrev_b32_e32 v54, 16, v179
	v_and_b32_e32 v55, 0xffff0000, v179
	v_pk_mul_f32 v[52:53], v[50:51], v[48:49]
	v_pk_fma_f32 v[48:49], v[50:51], v[48:49], v[54:55]
	v_mul_f32_e32 v50, v236, v60
	v_mul_f32_e32 v51, v236, v61
	v_exp_f32_e32 v50, v50
	v_exp_f32_e32 v51, v51
	v_cndmask_b32_e64 v48, v48, v52, s[0:1]
	v_cndmask_b32_e64 v49, v49, v53, s[0:1]
	v_cvt_pk_bf16_f32 v179, v48, v49
	v_pk_add_f32 v[50:51], v[50:51], 1.0 op_sel_hi:[1,0]
	v_lshlrev_b32_e32 v48, 16, v97
	v_and_b32_e32 v49, 0xffff0000, v97
	v_rcp_f32_e32 v51, v51
	s_nop 0
	v_rcp_f32_e32 v50, v50
	v_lshlrev_b32_e32 v54, 16, v164
	v_and_b32_e32 v55, 0xffff0000, v164
	v_pk_mul_f32 v[52:53], v[50:51], v[48:49]
	v_pk_fma_f32 v[48:49], v[50:51], v[48:49], v[54:55]
	v_mul_f32_e32 v50, v236, v62
	v_mul_f32_e32 v51, v236, v63
	v_exp_f32_e32 v50, v50
	v_exp_f32_e32 v51, v51
	v_cndmask_b32_e64 v48, v48, v52, s[0:1]
	v_cndmask_b32_e64 v49, v49, v53, s[0:1]
	v_cvt_pk_bf16_f32 v164, v48, v49
	v_pk_add_f32 v[50:51], v[50:51], 1.0 op_sel_hi:[1,0]
	v_lshlrev_b32_e32 v48, 16, v96
	v_and_b32_e32 v49, 0xffff0000, v96
	v_rcp_f32_e32 v51, v51
	s_nop 0
	v_rcp_f32_e32 v50, v50
	v_lshlrev_b32_e32 v54, 16, v165
	v_and_b32_e32 v55, 0xffff0000, v165
	v_pk_mul_f32 v[52:53], v[50:51], v[48:49]
	v_pk_fma_f32 v[48:49], v[50:51], v[48:49], v[54:55]
	v_cndmask_b32_e64 v48, v48, v52, s[0:1]
	v_cndmask_b32_e64 v49, v49, v53, s[0:1]
	v_cvt_pk_bf16_f32 v165, v48, v49
	v_rcp_f32_e32 v33, v33
	v_lshlrev_b32_e32 v48, 16, v80
	v_and_b32_e32 v49, 0xffff0000, v80
	v_rcp_f32_e32 v32, v32
	v_lshlrev_b32_e32 v52, 16, v162
	v_and_b32_e32 v53, 0xffff0000, v162
	v_pk_mul_f32 v[50:51], v[32:33], v[48:49]
	v_pk_fma_f32 v[32:33], v[32:33], v[48:49], v[52:53]
	s_nop 0
	v_cndmask_b32_e64 v33, v33, v51, s[0:1]
	v_cndmask_b32_e64 v32, v32, v50, s[0:1]
	v_cvt_pk_bf16_f32 v162, v32, v33
	v_lshlrev_b32_e32 v32, 16, v15
	v_and_b32_e32 v33, 0xffff0000, v15
	v_mul_f32_e32 v15, v236, v34
	v_exp_f32_e32 v34, v15
	v_mul_f32_e32 v15, v236, v35
	v_exp_f32_e32 v35, v15
	s_nop 0
	v_pk_add_f32 v[34:35], v[34:35], 1.0 op_sel_hi:[1,0]
	s_nop 0
	s_nop 0
	v_rcp_f32_e32 v35, v35
	s_nop 0
	v_rcp_f32_e32 v34, v34
	v_lshlrev_b32_e32 v50, 16, v163
	v_and_b32_e32 v51, 0xffff0000, v163
	v_pk_mul_f32 v[48:49], v[34:35], v[32:33]
	v_pk_fma_f32 v[32:33], v[34:35], v[32:33], v[50:51]
	s_nop 0
	v_cndmask_b32_e64 v15, v33, v49, s[0:1]
	v_cndmask_b32_e64 v32, v32, v48, s[0:1]
	v_cvt_pk_bf16_f32 v163, v32, v15
	v_lshlrev_b32_e32 v32, 16, v14
	v_and_b32_e32 v33, 0xffff0000, v14
	v_mul_f32_e32 v14, v236, v36
	v_mul_f32_e32 v15, v236, v37
	v_exp_f32_e32 v14, v14
	v_exp_f32_e32 v15, v15
	s_nop 0
	v_pk_add_f32 v[14:15], v[14:15], 1.0 op_sel_hi:[1,0]
	s_nop 0
	s_nop 0
	v_rcp_f32_e32 v15, v15
	s_nop 0
	v_rcp_f32_e32 v14, v14
	v_lshlrev_b32_e32 v36, 16, v160
	v_and_b32_e32 v37, 0xffff0000, v160
	v_pk_mul_f32 v[34:35], v[14:15], v[32:33]
	v_pk_fma_f32 v[14:15], v[14:15], v[32:33], v[36:37]
	s_nop 0
	v_cndmask_b32_e64 v15, v15, v35, s[0:1]
	v_cndmask_b32_e64 v14, v14, v34, s[0:1]
	v_cvt_pk_bf16_f32 v160, v14, v15
	v_lshlrev_b32_e32 v14, 16, v13
	v_and_b32_e32 v15, 0xffff0000, v13
	v_mul_f32_e32 v13, v236, v38
	v_exp_f32_e32 v32, v13
	v_mul_f32_e32 v13, v236, v39
	v_exp_f32_e32 v33, v13
	s_nop 0
	v_pk_add_f32 v[32:33], v[32:33], 1.0 op_sel_hi:[1,0]
	s_nop 0
	s_nop 0
	v_rcp_f32_e32 v33, v33
	s_nop 0
	v_rcp_f32_e32 v32, v32
	v_lshlrev_b32_e32 v36, 16, v161
	v_and_b32_e32 v37, 0xffff0000, v161
	v_pk_mul_f32 v[34:35], v[32:33], v[14:15]
	v_pk_fma_f32 v[14:15], v[32:33], v[14:15], v[36:37]
	s_nop 0
	v_cndmask_b32_e64 v13, v15, v35, s[0:1]
	v_cndmask_b32_e64 v14, v14, v34, s[0:1]
	v_cvt_pk_bf16_f32 v161, v14, v13
	v_lshlrev_b32_e32 v14, 16, v12
	v_and_b32_e32 v15, 0xffff0000, v12
	v_mul_f32_e32 v12, v236, v40
	v_mul_f32_e32 v13, v236, v41
	v_exp_f32_e32 v12, v12
	v_exp_f32_e32 v13, v13
	s_nop 0
	v_pk_add_f32 v[12:13], v[12:13], 1.0 op_sel_hi:[1,0]
	s_nop 0
	s_nop 0
	v_rcp_f32_e32 v13, v13
	s_nop 0
	v_rcp_f32_e32 v12, v12
	v_lshlrev_b32_e32 v34, 16, v158
	v_and_b32_e32 v35, 0xffff0000, v158
	v_pk_mul_f32 v[32:33], v[12:13], v[14:15]
	v_pk_fma_f32 v[12:13], v[12:13], v[14:15], v[34:35]
	s_nop 0
	v_cndmask_b32_e64 v13, v13, v33, s[0:1]
	v_cndmask_b32_e64 v12, v12, v32, s[0:1]
	v_cvt_pk_bf16_f32 v158, v12, v13
	v_lshlrev_b32_e32 v12, 16, v11
	v_and_b32_e32 v13, 0xffff0000, v11
	v_mul_f32_e32 v11, v236, v42
	v_exp_f32_e32 v14, v11
	v_mul_f32_e32 v11, v236, v43
	v_exp_f32_e32 v15, v11
	s_nop 0
	v_pk_add_f32 v[14:15], v[14:15], 1.0 op_sel_hi:[1,0]
	s_nop 0
	s_nop 0
	v_rcp_f32_e32 v15, v15
	s_nop 0
	v_rcp_f32_e32 v14, v14
	v_lshlrev_b32_e32 v34, 16, v159
	v_and_b32_e32 v35, 0xffff0000, v159
	v_pk_mul_f32 v[32:33], v[14:15], v[12:13]
	v_pk_fma_f32 v[12:13], v[14:15], v[12:13], v[34:35]
	s_nop 0
	v_cndmask_b32_e64 v11, v13, v33, s[0:1]
	v_cndmask_b32_e64 v12, v12, v32, s[0:1]
	v_cvt_pk_bf16_f32 v159, v12, v11
	v_lshlrev_b32_e32 v12, 16, v10
	v_and_b32_e32 v13, 0xffff0000, v10
	v_mul_f32_e32 v10, v236, v44
	v_mul_f32_e32 v11, v236, v45
	v_exp_f32_e32 v10, v10
	v_exp_f32_e32 v11, v11
	s_nop 0
	v_pk_add_f32 v[10:11], v[10:11], 1.0 op_sel_hi:[1,0]
	s_nop 0
	s_nop 0
	v_rcp_f32_e32 v11, v11
	s_nop 0
	v_rcp_f32_e32 v10, v10
	v_lshlrev_b32_e32 v32, 16, v156
	v_and_b32_e32 v33, 0xffff0000, v156
	v_pk_mul_f32 v[14:15], v[10:11], v[12:13]
	v_pk_fma_f32 v[10:11], v[10:11], v[12:13], v[32:33]
	s_nop 0
	v_cndmask_b32_e64 v11, v11, v15, s[0:1]
; DI int get_tid() { int t = threadIdx.x; asm volatile("" : "+v"(t)); return t; }
; DI unsigned pack2(float a, float b) { f2_t v = {a, b}; bf2_t r = __builtin_convertvector(v, bf2_t); return __builtin_bit_cast(unsigned, r); }
; template <int ROWS>
; DI void epi_flush(char* lds, u16* __restrict__ dst, size_t ld) {
;   const int tid = get_tid();
;   const int r0 = tid >> 5, ch = tid & 31;
;   __syncthreads();
; #pragma unroll 4
;   for (int r = r0; r < ROWS; r += 16) {
;     const u32x4 v = *(const u32x4*)(lds + r * EROW + ch * 16);
;     *(u32x4*)(dst + (size_t)r * ld + ch * 8) = v;
; __global__ void __launch_bounds__(512) mega(Params p) {
;     ...
;           for (int fb = 0; fb < 4; ++fb)
; #pragma unroll
;             for (int i = 0; i < 8; ++i) {
;               const float b0 = __uint_as_float(bp[fb][i] << 16), b1 = __uint_as_float(bp[fb][i] & 0xffff0000u);
;               const float g0 = 1.f / (1.f + __builtin_amdgcn_exp2f(nr1 * acc[fb][2 * i]));
;               const float g1 = 1.f / (1.f + __builtin_amdgcn_exp2f(nr1 * acc[fb][2 * i + 1]));
;               float y0 = g0 * b0, y1 = g1 * b1;
;               if (n > 0) { y0 += __uint_as_float(yp[fb][i] << 16); y1 += __uint_as_float(yp[fb][i] & 0xffff0000u); }
;               yp[fb][i] = pack2(y0, y1);
;             }
;         }
;         __syncthreads();
; #pragma unroll
;         for (int fb = 0; fb < 4; ++fb)
; #pragma unroll
;           for (int jq = 0; jq < 4; ++jq)
;             *(uint2*)(lds + (wt * 32 + l32) * EROW + (wf * 128 + fb * 32 + 8 * jq + 4 * hh) * 2) = make_uint2(yp[fb][2 * jq], yp[fb][2 * jq + 1]);
;         epi_flush<128>(lds, (u16*)(ws + R_Y) + (size_t)tt * 128 * 1024 + ft * 256, 1024);
	v_cndmask_b32_e64 v10, v10, v14, s[0:1]
	v_cvt_pk_bf16_f32 v156, v10, v11
	v_lshlrev_b32_e32 v10, 16, v9
	v_and_b32_e32 v11, 0xffff0000, v9
	v_mul_f32_e32 v9, v236, v46
	v_exp_f32_e32 v12, v9
	v_mul_f32_e32 v9, v236, v47
	v_exp_f32_e32 v13, v9
	s_nop 0
	v_pk_add_f32 v[12:13], v[12:13], 1.0 op_sel_hi:[1,0]
	s_nop 0
	s_nop 0
	v_rcp_f32_e32 v13, v13
	s_nop 0
	v_rcp_f32_e32 v12, v12
	v_lshlrev_b32_e32 v32, 16, v157
	v_and_b32_e32 v33, 0xffff0000, v157
	v_pk_mul_f32 v[14:15], v[12:13], v[10:11]
	v_pk_fma_f32 v[10:11], v[12:13], v[10:11], v[32:33]
	s_nop 0
	v_cndmask_b32_e64 v9, v11, v15, s[0:1]
	v_cndmask_b32_e64 v10, v10, v14, s[0:1]
	v_cvt_pk_bf16_f32 v157, v10, v9
	v_lshlrev_b32_e32 v10, 16, v8
	v_and_b32_e32 v11, 0xffff0000, v8
	v_mul_f32_e32 v8, v236, v16
	v_mul_f32_e32 v9, v236, v17
	v_exp_f32_e32 v8, v8
	v_exp_f32_e32 v9, v9
	s_nop 0
	v_pk_add_f32 v[8:9], v[8:9], 1.0 op_sel_hi:[1,0]
	s_nop 0
	s_nop 0
	v_rcp_f32_e32 v9, v9
	s_nop 0
	v_rcp_f32_e32 v8, v8
	v_lshlrev_b32_e32 v14, 16, v154
	v_and_b32_e32 v15, 0xffff0000, v154
	v_pk_mul_f32 v[12:13], v[8:9], v[10:11]
	v_pk_fma_f32 v[8:9], v[8:9], v[10:11], v[14:15]
	s_nop 0
	v_cndmask_b32_e64 v9, v9, v13, s[0:1]
	v_cndmask_b32_e64 v8, v8, v12, s[0:1]
	v_cvt_pk_bf16_f32 v154, v8, v9
	v_lshlrev_b32_e32 v8, 16, v7
	v_and_b32_e32 v9, 0xffff0000, v7
	v_mul_f32_e32 v7, v236, v18
	v_exp_f32_e32 v10, v7
	v_mul_f32_e32 v7, v236, v19
	v_exp_f32_e32 v11, v7
	s_nop 0
	v_pk_add_f32 v[10:11], v[10:11], 1.0 op_sel_hi:[1,0]
	s_nop 0
	s_nop 0
	v_rcp_f32_e32 v11, v11
	s_nop 0
	v_rcp_f32_e32 v10, v10
	v_lshlrev_b32_e32 v14, 16, v155
	v_and_b32_e32 v15, 0xffff0000, v155
	v_pk_mul_f32 v[12:13], v[10:11], v[8:9]
	v_pk_fma_f32 v[8:9], v[10:11], v[8:9], v[14:15]
	s_nop 0
	v_cndmask_b32_e64 v7, v9, v13, s[0:1]
	v_cndmask_b32_e64 v8, v8, v12, s[0:1]
	v_cvt_pk_bf16_f32 v155, v8, v7
	v_lshlrev_b32_e32 v8, 16, v6
	v_and_b32_e32 v9, 0xffff0000, v6
	v_mul_f32_e32 v6, v236, v20
	v_mul_f32_e32 v7, v236, v21
	v_exp_f32_e32 v6, v6
	v_exp_f32_e32 v7, v7
	s_nop 0
	v_pk_add_f32 v[6:7], v[6:7], 1.0 op_sel_hi:[1,0]
	s_nop 0
	s_nop 0
	v_rcp_f32_e32 v7, v7
	s_nop 0
	v_rcp_f32_e32 v6, v6
	v_lshlrev_b32_e32 v12, 16, v152
	v_and_b32_e32 v13, 0xffff0000, v152
	v_pk_mul_f32 v[10:11], v[6:7], v[8:9]
	v_pk_fma_f32 v[6:7], v[6:7], v[8:9], v[12:13]
	s_nop 0
	v_cndmask_b32_e64 v7, v7, v11, s[0:1]
	v_cndmask_b32_e64 v6, v6, v10, s[0:1]
	v_cvt_pk_bf16_f32 v152, v6, v7
	v_lshlrev_b32_e32 v6, 16, v5
	v_and_b32_e32 v7, 0xffff0000, v5
	v_mul_f32_e32 v5, v236, v22
	v_exp_f32_e32 v8, v5
	v_mul_f32_e32 v5, v236, v23
	v_exp_f32_e32 v9, v5
	s_nop 0
	v_pk_add_f32 v[8:9], v[8:9], 1.0 op_sel_hi:[1,0]
	s_nop 0
	s_nop 0
	v_rcp_f32_e32 v9, v9
	s_nop 0
	v_rcp_f32_e32 v8, v8
	v_lshlrev_b32_e32 v12, 16, v153
	v_and_b32_e32 v13, 0xffff0000, v153
	v_pk_mul_f32 v[10:11], v[8:9], v[6:7]
	v_pk_fma_f32 v[6:7], v[8:9], v[6:7], v[12:13]
	s_nop 0
	v_cndmask_b32_e64 v5, v7, v11, s[0:1]
	v_cndmask_b32_e64 v6, v6, v10, s[0:1]
	v_cvt_pk_bf16_f32 v153, v6, v5
	v_lshlrev_b32_e32 v6, 16, v4
	v_and_b32_e32 v7, 0xffff0000, v4
	v_mul_f32_e32 v4, v236, v24
	v_mul_f32_e32 v5, v236, v25
	v_exp_f32_e32 v4, v4
	v_exp_f32_e32 v5, v5
	s_nop 0
	v_pk_add_f32 v[4:5], v[4:5], 1.0 op_sel_hi:[1,0]
	s_nop 0
	s_nop 0
	v_rcp_f32_e32 v5, v5
	s_nop 0
	v_rcp_f32_e32 v4, v4
	v_lshlrev_b32_e32 v10, 16, v150
	v_and_b32_e32 v11, 0xffff0000, v150
	v_pk_mul_f32 v[8:9], v[4:5], v[6:7]
	v_pk_fma_f32 v[4:5], v[4:5], v[6:7], v[10:11]
	s_nop 0
	v_cndmask_b32_e64 v5, v5, v9, s[0:1]
	v_cndmask_b32_e64 v4, v4, v8, s[0:1]
	v_cvt_pk_bf16_f32 v150, v4, v5
	v_lshlrev_b32_e32 v4, 16, v3
	v_and_b32_e32 v5, 0xffff0000, v3
	v_mul_f32_e32 v3, v236, v26
	v_exp_f32_e32 v6, v3
	v_mul_f32_e32 v3, v236, v27
	v_exp_f32_e32 v7, v3
	s_nop 0
	v_pk_add_f32 v[6:7], v[6:7], 1.0 op_sel_hi:[1,0]
	s_nop 0
	s_nop 0
	v_rcp_f32_e32 v7, v7
	s_nop 0
	v_rcp_f32_e32 v6, v6
	v_lshlrev_b32_e32 v10, 16, v151
	v_and_b32_e32 v11, 0xffff0000, v151
	v_pk_mul_f32 v[8:9], v[6:7], v[4:5]
	v_pk_fma_f32 v[4:5], v[6:7], v[4:5], v[10:11]
	s_nop 0
	v_cndmask_b32_e64 v3, v5, v9, s[0:1]
	v_cndmask_b32_e64 v4, v4, v8, s[0:1]
	v_cvt_pk_bf16_f32 v151, v4, v3
	v_lshlrev_b32_e32 v4, 16, v2
	v_and_b32_e32 v5, 0xffff0000, v2
	v_mul_f32_e32 v2, v236, v28
	v_mul_f32_e32 v3, v236, v29
	v_exp_f32_e32 v2, v2
	v_exp_f32_e32 v3, v3
	s_nop 0
	v_pk_add_f32 v[2:3], v[2:3], 1.0 op_sel_hi:[1,0]
	s_nop 0
	s_nop 0
	v_rcp_f32_e32 v3, v3
	s_nop 0
	v_rcp_f32_e32 v2, v2
	v_lshlrev_b32_e32 v8, 16, v148
	v_and_b32_e32 v9, 0xffff0000, v148
	v_pk_mul_f32 v[6:7], v[2:3], v[4:5]
	v_pk_fma_f32 v[2:3], v[2:3], v[4:5], v[8:9]
	s_nop 0
	v_cndmask_b32_e64 v3, v3, v7, s[0:1]
	v_cndmask_b32_e64 v2, v2, v6, s[0:1]
	v_cvt_pk_bf16_f32 v148, v2, v3
	v_lshlrev_b32_e32 v2, 16, v0
	v_and_b32_e32 v3, 0xffff0000, v0
	v_mul_f32_e32 v0, v236, v30
	v_exp_f32_e32 v4, v0
	v_mul_f32_e32 v0, v236, v31
	v_exp_f32_e32 v5, v0
	s_nop 0
	v_pk_add_f32 v[4:5], v[4:5], 1.0 op_sel_hi:[1,0]
	s_nop 0
	s_nop 0
	v_rcp_f32_e32 v5, v5
	s_nop 0
	v_rcp_f32_e32 v4, v4
	v_lshlrev_b32_e32 v8, 16, v149
	v_and_b32_e32 v9, 0xffff0000, v149
	v_pk_mul_f32 v[6:7], v[4:5], v[2:3]
	v_pk_fma_f32 v[2:3], v[4:5], v[2:3], v[8:9]
	s_nop 0
	v_cndmask_b32_e64 v0, v3, v7, s[0:1]
	v_cndmask_b32_e64 v2, v2, v6, s[0:1]
	v_cvt_pk_bf16_f32 v149, v2, v0
	s_cbranch_scc0 .LBB0_25
	v_mov_b32_e32 v6, v145
	s_waitcnt vmcnt(0)
	s_barrier
	ds_write2_b64 v235, v[166:167], v[168:169] offset1:2
	ds_write2_b64 v235, v[170:171], v[172:173] offset0:4 offset1:6
	ds_write2_b64 v235, v[174:175], v[176:177] offset0:8 offset1:10
	ds_write2_b64 v235, v[178:179], v[164:165] offset0:12 offset1:14
	ds_write2_b64 v235, v[162:163], v[160:161] offset0:16 offset1:18
	ds_write2_b64 v235, v[158:159], v[156:157] offset0:20 offset1:22
	ds_write2_b64 v235, v[154:155], v[152:153] offset0:24 offset1:26
	ds_write2_b64 v235, v[150:151], v[148:149] offset0:28 offset1:30
	s_waitcnt lgkmcnt(0)
	v_ashrrev_i32_e32 v2, 5, v6
	v_cmp_gt_i32_e32 vcc, s70, v2
	s_barrier
	s_and_saveexec_b64 s[0:1], vcc
	s_cbranch_execz .LBB0_23
	v_max_i32_e32 v0, 0x70, v2
	v_sub_u32_e32 v0, v0, v2
	v_add_u32_e32 v0, 15, v0
	v_and_b32_e32 v4, 31, v6
	v_and_b32_e32 v3, 48, v0
	s_and_b32 s33, s52, 0xe0
	v_lshlrev_b32_e32 v12, 4, v4
	v_cmp_ne_u32_e32 vcc, 48, v3
	s_and_saveexec_b64 s[8:9], vcc
	s_cbranch_execz .LBB0_55
	v_lshrrev_b32_e32 v3, 4, v0
	s_add_i32 s34, s33, s57
	v_add_u32_e32 v3, 1, v3
	s_add_i32 s34, s34, s58
	v_and_b32_e32 v7, 3, v3
	s_ashr_i32 s35, s34, 31
	v_ashrrev_i32_e32 v3, 31, v2
	s_lshl_b64 s[34:35], s[34:35], 18
	v_lshlrev_b64 v[8:9], 11, v[2:3]
	v_lshl_add_u64 v[8:9], s[34:35], 0, v[8:9]
	s_lshl_b64 s[34:35], s[54:55], 1
	s_add_u32 s34, s10, s34
	v_lshl_or_b32 v8, v4, 4, v8
	s_addc_u32 s35, s11, s35
	v_lshl_add_u64 v[4:5], s[34:35], 0, v[8:9]
	s_movk_i32 s34, 0x210
	v_mul_lo_u32 v3, v2, s34
	v_add3_u32 v3, v3, v12, 0
	v_sub_u32_e32 v7, 0, v7
	s_mov_b64 s[34:35], 0
	s_mov_b64 s[64:65], 0x8000

; DI unsigned pack2(float a, float b) { f2_t v = {a, b}; bf2_t r = __builtin_convertvector(v, bf2_t); return __builtin_bit_cast(unsigned, r); }
; __global__ void __launch_bounds__(512) mega(Params p) {
;     ...
;           const int r0 = tid >> 5, ch = tid & 31;
; #pragma unroll 4
;           for (int it = 0; it < 16; ++it) {
;             const int row = r0 + 16 * it;
;             const int t = tt * 256 + row;
;             const size_t off = (size_t)t * 1024 + ft * 256 + ch * 8;
;             const u32x4 d = *(const u32x4*)(lds + row * EROW + ch * 16);
;             float4 v0 = *(const float4*)(xin + off), v1 = *(const float4*)(xin + off + 4);
;             v0.x += __uint_as_float(d.x << 16); v0.y += __uint_as_float(d.x & 0xffff0000u);
;             v0.z += __uint_as_float(d.y << 16); v0.w += __uint_as_float(d.y & 0xffff0000u);
;             v1.x += __uint_as_float(d.z << 16); v1.y += __uint_as_float(d.z & 0xffff0000u);
;             v1.z += __uint_as_float(d.w << 16); v1.w += __uint_as_float(d.w & 0xffff0000u);
;             __builtin_nontemporal_store(__builtin_bit_cast(u32x4, v0), (u32x4*)(p.out + off));
;             __builtin_nontemporal_store(__builtin_bit_cast(u32x4, v1), (u32x4*)(p.out + off + 4));
;             u32x4 xb4;
;             xb4.x = pack2(v0.x, v0.y); xb4.y = pack2(v0.z, v0.w); xb4.z = pack2(v1.x, v1.y); xb4.w = pack2(v1.z, v1.w);
;             *(u32x4*)((u16*)(ws + OFF_H) + off) = xb4;
.LBB0_178:
	ds_read_b128 v[156:159], v22
	global_load_dwordx4 v[152:155], v[10:11], off
	global_load_dwordx4 v[148:151], v[10:11], off offset:-16
	v_add_u32_e32 v134, -32, v4
	v_ashrrev_i32_e32 v135, 31, v134
	v_lshlrev_b64 v[134:135], 10, v[134:135]
	v_lshl_add_u64 v[134:135], v[134:135], 0, v[2:3]
	v_lshlrev_b64 v[136:137], 2, v[134:135]
	v_lshl_add_u64 v[140:141], s[64:65], 0, v[136:137]
	ds_read_b128 v[168:171], v22 offset:8448
	global_load_dwordx4 v[164:167], v[140:141], off offset:16
	global_load_dwordx4 v[160:163], v[140:141], off
	v_lshl_add_u64 v[248:249], v[134:135], 1, s[52:53]
	v_lshl_add_u64 v[246:247], s[28:29], 0, v[136:137]
	v_add_u32_e32 v134, -16, v4
	v_ashrrev_i32_e32 v135, 31, v134
	v_lshlrev_b64 v[134:135], 10, v[134:135]
	v_lshl_add_u64 v[134:135], v[134:135], 0, v[2:3]
	v_lshlrev_b64 v[136:137], 2, v[134:135]
	v_lshl_add_u64 v[140:141], s[64:65], 0, v[136:137]
	ds_read_b128 v[180:183], v22 offset:16896
	global_load_dwordx4 v[176:179], v[140:141], off offset:16
	global_load_dwordx4 v[172:175], v[140:141], off
	v_lshl_add_u64 v[252:253], v[134:135], 1, s[52:53]
	v_lshl_add_u64 v[250:251], s[28:29], 0, v[136:137]
	v_mov_b32_e32 v134, v4
	v_ashrrev_i32_e32 v135, 31, v134
	v_lshlrev_b64 v[134:135], 10, v[134:135]
	v_lshl_add_u64 v[134:135], v[134:135], 0, v[2:3]
	v_lshlrev_b64 v[136:137], 2, v[134:135]
	v_lshl_add_u64 v[140:141], s[64:65], 0, v[136:137]
	ds_read_b128 v[242:245], v22 offset:25344
	global_load_dwordx4 v[238:241], v[140:141], off offset:16
	global_load_dwordx4 v[234:237], v[140:141], off
	v_lshl_add_u64 v[192:193], v[134:135], 1, s[52:53]
	v_lshl_add_u64 v[190:191], s[28:29], 0, v[136:137]
	s_waitcnt vmcnt(0) lgkmcnt(0)
; DI unsigned pack2(float a, float b) { f2_t v = {a, b}; bf2_t r = __builtin_convertvector(v, bf2_t); return __builtin_bit_cast(unsigned, r); }
; __global__ void __launch_bounds__(512) mega(Params p) {
;     ...
;             float4 v0 = *(const float4*)(xin + off), v1 = *(const float4*)(xin + off + 4);
;             v0.x += __uint_as_float(d.x << 16); v0.y += __uint_as_float(d.x & 0xffff0000u);
;             v0.z += __uint_as_float(d.y << 16); v0.w += __uint_as_float(d.y & 0xffff0000u);
;             v1.x += __uint_as_float(d.z << 16); v1.y += __uint_as_float(d.z & 0xffff0000u);
;             v1.z += __uint_as_float(d.w << 16); v1.w += __uint_as_float(d.w & 0xffff0000u);
;             __builtin_nontemporal_store(__builtin_bit_cast(u32x4, v0), (u32x4*)(p.out + off));
;             __builtin_nontemporal_store(__builtin_bit_cast(u32x4, v1), (u32x4*)(p.out + off + 4));
;             u32x4 xb4;
;             xb4.x = pack2(v0.x, v0.y); xb4.y = pack2(v0.z, v0.w); xb4.z = pack2(v1.x, v1.y); xb4.w = pack2(v1.z, v1.w);
;             *(u32x4*)((u16*)(ws + OFF_H) + off) = xb4;
;             float ss = v0.x * v0.x + v0.y * v0.y + v0.z * v0.z + v0.w * v0.w + v1.x * v1.x + v1.y * v1.y + v1.z * v1.z + v1.w * v1.w;
; #pragma unroll
;             for (int o = 16; o >= 1; o >>= 1) ss += __shfl_xor(ss, o);
;             if (ch == 0) ssacc[(size_t)ft * T_TOK + t] = ss;
	v_lshlrev_b32_e32 v142, 16, v156
	v_and_b32_e32 v143, 0xffff0000, v156
	v_pk_add_f32 v[148:149], v[148:149], v[142:143]
	v_lshlrev_b32_e32 v142, 16, v157
	v_and_b32_e32 v143, 0xffff0000, v157
	v_pk_add_f32 v[150:151], v[150:151], v[142:143]
	v_lshlrev_b32_e32 v142, 16, v158
	v_and_b32_e32 v143, 0xffff0000, v158
	v_pk_add_f32 v[152:153], v[152:153], v[142:143]
	v_lshlrev_b32_e32 v142, 16, v159
	v_and_b32_e32 v143, 0xffff0000, v159
	v_pk_add_f32 v[154:155], v[154:155], v[142:143]
	global_store_dwordx4 v[14:15], v[148:151], off offset:-16 nt
	global_store_dwordx4 v[14:15], v[152:155], off nt
	v_cvt_pk_bf16_f32 v156, v148, v149
	v_cvt_pk_bf16_f32 v157, v150, v151
	v_cvt_pk_bf16_f32 v158, v152, v153
	v_cvt_pk_bf16_f32 v159, v154, v155
	global_store_dwordx4 v[12:13], v[156:159], off
	v_pk_mul_f32 v[134:135], v[148:149], v[148:149]
	v_pk_mul_f32 v[136:137], v[150:151], v[150:151]
	v_pk_mul_f32 v[140:141], v[152:153], v[152:153]
	v_pk_mul_f32 v[142:143], v[154:155], v[154:155]
	v_add_f32_e32 v194, v134, v135
	v_add_f32_e32 v194, v136, v194
	v_add_f32_e32 v194, v137, v194
	v_add_f32_e32 v194, v140, v194
	v_add_f32_e32 v194, v141, v194
	v_add_f32_e32 v194, v142, v194
	v_add_f32_e32 v194, v143, v194
	v_lshlrev_b32_e32 v142, 16, v168
	v_and_b32_e32 v143, 0xffff0000, v168
	v_pk_add_f32 v[160:161], v[160:161], v[142:143]
	v_lshlrev_b32_e32 v142, 16, v169
	v_and_b32_e32 v143, 0xffff0000, v169
	v_pk_add_f32 v[162:163], v[162:163], v[142:143]
	v_lshlrev_b32_e32 v142, 16, v170
	v_and_b32_e32 v143, 0xffff0000, v170
	v_pk_add_f32 v[164:165], v[164:165], v[142:143]
	v_lshlrev_b32_e32 v142, 16, v171
	v_and_b32_e32 v143, 0xffff0000, v171
	v_pk_add_f32 v[166:167], v[166:167], v[142:143]
	global_store_dwordx4 v[246:247], v[160:163], off nt
	global_store_dwordx4 v[246:247], v[164:167], off offset:16 nt
	v_cvt_pk_bf16_f32 v168, v160, v161
	v_cvt_pk_bf16_f32 v169, v162, v163
	v_cvt_pk_bf16_f32 v170, v164, v165
	v_cvt_pk_bf16_f32 v171, v166, v167
	global_store_dwordx4 v[248:249], v[168:171], off
	v_pk_mul_f32 v[134:135], v[160:161], v[160:161]
	v_pk_mul_f32 v[136:137], v[162:163], v[162:163]
	v_pk_mul_f32 v[140:141], v[164:165], v[164:165]
	v_pk_mul_f32 v[142:143], v[166:167], v[166:167]
	v_add_f32_e32 v195, v134, v135
	v_add_f32_e32 v195, v136, v195
	v_add_f32_e32 v195, v137, v195
	v_add_f32_e32 v195, v140, v195
	v_add_f32_e32 v195, v141, v195
	v_add_f32_e32 v195, v142, v195
	v_add_f32_e32 v195, v143, v195
	v_lshlrev_b32_e32 v142, 16, v180
	v_and_b32_e32 v143, 0xffff0000, v180
	v_pk_add_f32 v[172:173], v[172:173], v[142:143]
	v_lshlrev_b32_e32 v142, 16, v181
	v_and_b32_e32 v143, 0xffff0000, v181
	v_pk_add_f32 v[174:175], v[174:175], v[142:143]
	v_lshlrev_b32_e32 v142, 16, v182
	v_and_b32_e32 v143, 0xffff0000, v182
	v_pk_add_f32 v[176:177], v[176:177], v[142:143]
	v_lshlrev_b32_e32 v142, 16, v183
	v_and_b32_e32 v143, 0xffff0000, v183
	v_pk_add_f32 v[178:179], v[178:179], v[142:143]
	global_store_dwordx4 v[250:251], v[172:175], off nt
	global_store_dwordx4 v[250:251], v[176:179], off offset:16 nt
	v_cvt_pk_bf16_f32 v180, v172, v173
	v_cvt_pk_bf16_f32 v181, v174, v175
	v_cvt_pk_bf16_f32 v182, v176, v177
	v_cvt_pk_bf16_f32 v183, v178, v179
	global_store_dwordx4 v[252:253], v[180:183], off
	v_pk_mul_f32 v[134:135], v[172:173], v[172:173]
	v_pk_mul_f32 v[136:137], v[174:175], v[174:175]
	v_pk_mul_f32 v[140:141], v[176:177], v[176:177]
	v_pk_mul_f32 v[142:143], v[178:179], v[178:179]
	v_add_f32_e32 v231, v134, v135
	v_add_f32_e32 v231, v136, v231
	v_add_f32_e32 v231, v137, v231
	v_add_f32_e32 v231, v140, v231
	v_add_f32_e32 v231, v141, v231
	v_add_f32_e32 v231, v142, v231
	v_add_f32_e32 v231, v143, v231
	v_lshlrev_b32_e32 v142, 16, v242
	v_and_b32_e32 v143, 0xffff0000, v242
	v_pk_add_f32 v[234:235], v[234:235], v[142:143]
	v_lshlrev_b32_e32 v142, 16, v243
	v_and_b32_e32 v143, 0xffff0000, v243
	v_pk_add_f32 v[236:237], v[236:237], v[142:143]
	v_lshlrev_b32_e32 v142, 16, v244
	v_and_b32_e32 v143, 0xffff0000, v244
	v_pk_add_f32 v[238:239], v[238:239], v[142:143]
	v_lshlrev_b32_e32 v142, 16, v245
	v_and_b32_e32 v143, 0xffff0000, v245
	v_pk_add_f32 v[240:241], v[240:241], v[142:143]
	global_store_dwordx4 v[190:191], v[234:237], off nt
	global_store_dwordx4 v[190:191], v[238:241], off offset:16 nt
	v_cvt_pk_bf16_f32 v242, v234, v235
	v_cvt_pk_bf16_f32 v243, v236, v237
	v_cvt_pk_bf16_f32 v244, v238, v239
	v_cvt_pk_bf16_f32 v245, v240, v241
	global_store_dwordx4 v[192:193], v[242:245], off
	v_pk_mul_f32 v[134:135], v[234:235], v[234:235]
	v_pk_mul_f32 v[136:137], v[236:237], v[236:237]
	v_pk_mul_f32 v[140:141], v[238:239], v[238:239]
	v_pk_mul_f32 v[142:143], v[240:241], v[240:241]
	v_add_f32_e32 v232, v134, v135
	v_add_f32_e32 v232, v136, v232
	v_add_f32_e32 v232, v137, v232
	v_add_f32_e32 v232, v140, v232
	v_add_f32_e32 v232, v141, v232
	v_add_f32_e32 v232, v142, v232
	v_add_f32_e32 v232, v143, v232
	ds_bpermute_b32 v233, v0, v194
	ds_bpermute_b32 v184, v0, v195
	ds_bpermute_b32 v186, v0, v231
	ds_bpermute_b32 v189, v0, v232
	s_waitcnt lgkmcnt(0)
	v_add_f32_e32 v194, v194, v233
	v_add_f32_e32 v195, v195, v184
	v_add_f32_e32 v231, v231, v186
	v_add_f32_e32 v232, v232, v189
	ds_bpermute_b32 v233, v18, v194
	ds_bpermute_b32 v184, v18, v195
	ds_bpermute_b32 v186, v18, v231
	ds_bpermute_b32 v189, v18, v232
	s_waitcnt lgkmcnt(0)
	v_add_f32_e32 v194, v194, v233
	v_add_f32_e32 v195, v195, v184
	v_add_f32_e32 v231, v231, v186
	v_add_f32_e32 v232, v232, v189
	ds_bpermute_b32 v233, v19, v194
	ds_bpermute_b32 v184, v19, v195
	ds_bpermute_b32 v186, v19, v231
	ds_bpermute_b32 v189, v19, v232
	s_waitcnt lgkmcnt(0)
	v_add_f32_e32 v194, v194, v233
	v_add_f32_e32 v195, v195, v184
	v_add_f32_e32 v231, v231, v186
	v_add_f32_e32 v232, v232, v189
	ds_bpermute_b32 v233, v20, v194
	ds_bpermute_b32 v184, v20, v195
	ds_bpermute_b32 v186, v20, v231
	ds_bpermute_b32 v189, v20, v232
	s_waitcnt lgkmcnt(0)
	v_add_f32_e32 v194, v194, v233
	v_add_f32_e32 v195, v195, v184
	v_add_f32_e32 v231, v231, v186
	v_add_f32_e32 v232, v232, v189
	ds_bpermute_b32 v233, v21, v194
	ds_bpermute_b32 v184, v21, v195
	ds_bpermute_b32 v186, v21, v231
	ds_bpermute_b32 v189, v21, v232
	s_waitcnt lgkmcnt(0)
	v_add_f32_e32 v194, v194, v233
	v_add_f32_e32 v195, v195, v184
	v_add_f32_e32 v231, v231, v186
	v_add_f32_e32 v232, v232, v189
	s_and_saveexec_b64 s[8:9], s[0:1]
	v_lshl_add_u64 v[134:135], v[8:9], 0, s[4:5]
	v_lshl_add_u64 v[136:137], v[6:7], 0, s[4:5]
	global_store_dword v[134:135], v194, off
	global_store_dword v[136:137], v195, off offset:64
	global_store_dword v[136:137], v231, off offset:128
	global_store_dword v[136:137], v232, off offset:192
	s_branch .LBB0_177
